# L-slot wave raised to priority 2 while it issues LDS-DMA and ds_reads
# baseline (speedup 1.0000x reference)
; #define PG8_STAGE(bufoff, gbase, voff) do { _Pragma("unroll") for (int _i = 0; _i < 2; ++_i) \
;         __builtin_amdgcn_global_load_lds((const unsigned*)((const char*)(gbase) + (voff)[_i]), (PG8_LAS unsigned*)(lds + (bufoff) + ldsw + _i * 8192), 16, 0, 0); } while (0)
; #define PG8_LDA(dst, b, h) do { _Pragma("unroll") for (int m = 0; m < 4; ++m) _Pragma("unroll") for (int k = 0; k < 2; ++k) dst[m][k] = *(const PG8_LAS bf16x8*)(lds + PG8_SA(b, h) + aoff + m * 2048 + k * 1024); } while (0)
; #define PG8_LDB(dst, b, h) do { _Pragma("unroll") for (int n = 0; n < 2; ++n) _Pragma("unroll") for (int k = 0; k < 2; ++k) dst[n][k] = *(const PG8_LAS bf16x8*)(lds + PG8_SB(b, h) + boff + n * 2048 + k * 1024); } while (0)
; #define PG8_MMA(ai, bj, At, Bt) do { __builtin_amdgcn_s_setprio(1); _Pragma("unroll") for (int m = 0; m < 4; ++m) _Pragma("unroll") for (int n = 0; n < 2; ++n) _Pragma("unroll") for (int k = 0; k < 2; ++k) \
;         acc[ai][bj][m][n] = __builtin_amdgcn_mfma_f32_16x16x32_bf16(Bt[n][k], At[m][k], acc[ai][bj][m][n], 0, 0, 0); __builtin_amdgcn_s_setprio(0); } while (0)
; #define PG8_WAIT_V(n) asm volatile("s_waitcnt vmcnt(" #n ")" ::: "memory")
; template <class Epi, class Sched, bool ALIGN_EPI>
; __device__ __forceinline__ void gemm_phase(PG8_LAS unsigned char* lds, const Gemm g, const Sched& S, const Epi& E) {
;     ...
;             PG8_LDB(B0, 0, 0); PG8_LDB(B1, 0, 1); PG8_SCHED; PG8_LDA(At, 0, 0); PG8_STAGE(PG8_SA(1, 1), a1 + hstepA, voffA);
;             PG8_WAIT_V(8); PG8_WAIT_L(0); PG8_BAR; PG8_MMA(0, 0, At, B0); PG8_MMA(0, 1, At, B1); PG8_BAR; PG8_SCHED;
;             PG8_LDA(At, 0, 1); PG8_STAGE(PG8_SB(0, 0), b2, voffB); PG8_STAGE(PG8_SB(0, 1), b2 + hstepB, voffB); PG8_STAGE(PG8_SA(0, 0), a2, voffA);
;             PG8_WAIT_V(8); PG8_WAIT_L(0); PG8_BAR; PG8_MMA(1, 0, At, B0); PG8_MMA(1, 1, At, B1); PG8_BAR; PG8_SCHED;
;             PG8_LDB(B0, 1, 0); PG8_LDB(B1, 1, 1); PG8_SCHED; PG8_LDA(At, 1, 0); PG8_STAGE(PG8_SA(0, 1), a2 + hstepA, voffA);
;             PG8_WAIT_V(8); PG8_WAIT_L(0); PG8_BAR; PG8_MMA(0, 0, At, B0); PG8_MMA(0, 1, At, B1); PG8_BAR; PG8_SCHED;
;             PG8_LDA(At, 1, 1); PG8_STAGE(PG8_SB(1, 0), b3, voffB); PG8_STAGE(PG8_SB(1, 1), b3 + hstepB, voffB); PG8_STAGE(PG8_SA(1, 0), a3, voffA);
;             PG8_WAIT_V(8); PG8_WAIT_L(0); PG8_BAR; PG8_MMA(1, 0, At, B0); PG8_MMA(1, 1, At, B1); PG8_BAR; PG8_SCHED;
.Lp8k_A_first:
	s_add_u32 s28, s30, 0x80
	s_addc_u32 s29, s31, 0
	s_setprio 2
	ds_read_b128 v[190:193], v155 offset:0
	ds_read_b128 v[194:197], v155 offset:1024
	ds_read_b128 v[198:201], v155 offset:2048
	s_add_i32 m0, s2, 0x18000
	s_nop 0
	global_load_lds_dwordx4 v134, s[28:29]
	ds_read_b128 v[202:205], v155 offset:3072
	ds_read_b128 v[206:209], v155 offset:4096
	ds_read_b128 v[210:213], v155 offset:5120
	s_add_i32 m0, s2, 0x1a000
	s_nop 0
	global_load_lds_dwordx4 v130, s[28:29]
	ds_read_b128 v[214:217], v155 offset:6144
	ds_read_b128 v[218:221], v155 offset:7168
	ds_read_b128 v[156:159], v153 offset:0
	s_add_u32 s30, s28, 0x20000
	s_addc_u32 s31, s29, 0
	s_add_i32 m0, s2, 0x19000
	s_nop 0
	global_load_lds_dwordx4 v134, s[30:31]
	ds_read_b128 v[160:163], v153 offset:1024
	ds_read_b128 v[164:167], v153 offset:2048
	ds_read_b128 v[168:171], v153 offset:3072
	s_add_i32 m0, s2, 0x1b000
	s_nop 0
	global_load_lds_dwordx4 v130, s[30:31]
	ds_read_b128 v[174:177], v153 offset:16384
	ds_read_b128 v[178:181], v153 offset:17408
	ds_read_b128 v[182:185], v153 offset:18432
	s_add_u32 s30, s28, 0x80000
	s_addc_u32 s31, s29, 0
	s_add_i32 m0, s2, 0x1c000
	s_nop 0
	global_load_lds_dwordx4 v134, s[30:31]
	ds_read_b128 v[186:189], v153 offset:19456
	ds_read_b128 v[222:225], v155 offset:16384
	ds_read_b128 v[226:229], v155 offset:17408
	s_add_i32 m0, s2, 0x1e000
	s_nop 0
	global_load_lds_dwordx4 v130, s[30:31]
	ds_read_b128 v[230:233], v155 offset:18432
	ds_read_b128 v[234:237], v155 offset:19456
	ds_read_b128 v[238:241], v155 offset:20480
	s_add_u32 s30, s28, 0xa0000
	s_addc_u32 s31, s29, 0
	s_add_i32 m0, s2, 0x1d000
	s_nop 0
	global_load_lds_dwordx4 v134, s[30:31]
	ds_read_b128 v[242:245], v155 offset:21504
	ds_read_b128 v[246:249], v155 offset:22528
	ds_read_b128 v[250:253], v155 offset:23552
	s_add_i32 m0, s2, 0x1f000
	s_nop 0
	global_load_lds_dwordx4 v130, s[30:31]
	s_add_u32 s28, s28, 0x80
	s_addc_u32 s29, s29, 0
.Lp8k_A_entry:
	s_waitcnt vmcnt(8) lgkmcnt(0)
	s_barrier
	s_setprio 1
	v_mfma_f32_16x16x32_bf16 v[126:129], v[156:159], v[190:193], 0
	v_mfma_f32_16x16x32_bf16 v[126:129], v[160:163], v[194:197], v[126:129]
	v_mfma_f32_16x16x32_bf16 v[122:125], v[168:171], v[194:197], 0
	v_mfma_f32_16x16x32_bf16 v[122:125], v[164:167], v[190:193], v[122:125]
	v_mfma_f32_16x16x32_bf16 v[118:121], v[174:177], v[190:193], 0
	v_mfma_f32_16x16x32_bf16 v[118:121], v[178:181], v[194:197], v[118:121]
	v_mfma_f32_16x16x32_bf16 v[114:117], v[186:189], v[194:197], 0
	v_mfma_f32_16x16x32_bf16 v[114:117], v[182:185], v[190:193], v[114:117]
	v_mfma_f32_16x16x32_bf16 v[98:101], v[182:185], v[198:201], 0
	v_mfma_f32_16x16x32_bf16 v[98:101], v[186:189], v[202:205], v[98:101]
	v_mfma_f32_16x16x32_bf16 v[102:105], v[178:181], v[202:205], 0
	v_mfma_f32_16x16x32_bf16 v[102:105], v[174:177], v[198:201], v[102:105]
	v_mfma_f32_16x16x32_bf16 v[106:109], v[164:167], v[198:201], 0
	v_mfma_f32_16x16x32_bf16 v[106:109], v[168:171], v[202:205], v[106:109]
	v_mfma_f32_16x16x32_bf16 v[110:113], v[160:163], v[202:205], 0
	v_mfma_f32_16x16x32_bf16 v[110:113], v[156:159], v[198:201], v[110:113]
	v_mfma_f32_16x16x32_bf16 v[94:97], v[156:159], v[206:209], 0
	v_mfma_f32_16x16x32_bf16 v[94:97], v[160:163], v[210:213], v[94:97]
	v_mfma_f32_16x16x32_bf16 v[90:93], v[168:171], v[210:213], 0
	v_mfma_f32_16x16x32_bf16 v[90:93], v[164:167], v[206:209], v[90:93]
	v_mfma_f32_16x16x32_bf16 v[86:89], v[174:177], v[206:209], 0
	v_mfma_f32_16x16x32_bf16 v[86:89], v[178:181], v[210:213], v[86:89]
	v_mfma_f32_16x16x32_bf16 v[82:85], v[186:189], v[210:213], 0
	v_mfma_f32_16x16x32_bf16 v[82:85], v[182:185], v[206:209], v[82:85]
	v_mfma_f32_16x16x32_bf16 v[66:69], v[182:185], v[214:217], 0
	v_mfma_f32_16x16x32_bf16 v[66:69], v[186:189], v[218:221], v[66:69]
	v_mfma_f32_16x16x32_bf16 v[70:73], v[178:181], v[218:221], 0
	v_mfma_f32_16x16x32_bf16 v[70:73], v[174:177], v[214:217], v[70:73]
	v_mfma_f32_16x16x32_bf16 v[74:77], v[164:167], v[214:217], 0
	v_mfma_f32_16x16x32_bf16 v[74:77], v[168:171], v[218:221], v[74:77]
	v_mfma_f32_16x16x32_bf16 v[78:81], v[160:163], v[218:221], 0
	v_mfma_f32_16x16x32_bf16 v[78:81], v[156:159], v[214:217], v[78:81]
	v_mfma_f32_16x16x32_bf16 v[62:65], v[156:159], v[222:225], 0
	v_mfma_f32_16x16x32_bf16 v[62:65], v[160:163], v[226:229], v[62:65]
	v_mfma_f32_16x16x32_bf16 v[58:61], v[168:171], v[226:229], 0
	v_mfma_f32_16x16x32_bf16 v[58:61], v[164:167], v[222:225], v[58:61]
	v_mfma_f32_16x16x32_bf16 v[54:57], v[174:177], v[222:225], 0
	v_mfma_f32_16x16x32_bf16 v[54:57], v[178:181], v[226:229], v[54:57]
	v_mfma_f32_16x16x32_bf16 v[50:53], v[186:189], v[226:229], 0
	v_mfma_f32_16x16x32_bf16 v[50:53], v[182:185], v[222:225], v[50:53]
	v_mfma_f32_16x16x32_bf16 v[34:37], v[182:185], v[230:233], 0
	v_mfma_f32_16x16x32_bf16 v[34:37], v[186:189], v[234:237], v[34:37]
	v_mfma_f32_16x16x32_bf16 v[38:41], v[178:181], v[234:237], 0
	v_mfma_f32_16x16x32_bf16 v[38:41], v[174:177], v[230:233], v[38:41]
	v_mfma_f32_16x16x32_bf16 v[42:45], v[164:167], v[230:233], 0
	v_mfma_f32_16x16x32_bf16 v[42:45], v[168:171], v[234:237], v[42:45]
	v_mfma_f32_16x16x32_bf16 v[46:49], v[160:163], v[234:237], 0
	v_mfma_f32_16x16x32_bf16 v[46:49], v[156:159], v[230:233], v[46:49]
	v_mfma_f32_16x16x32_bf16 v[30:33], v[156:159], v[238:241], 0
	v_mfma_f32_16x16x32_bf16 v[30:33], v[160:163], v[242:245], v[30:33]
	v_mfma_f32_16x16x32_bf16 v[26:29], v[168:171], v[242:245], 0
	v_mfma_f32_16x16x32_bf16 v[26:29], v[164:167], v[238:241], v[26:29]
	v_mfma_f32_16x16x32_bf16 v[22:25], v[174:177], v[238:241], 0
	v_mfma_f32_16x16x32_bf16 v[22:25], v[178:181], v[242:245], v[22:25]
	v_mfma_f32_16x16x32_bf16 v[18:21], v[186:189], v[242:245], 0
	v_mfma_f32_16x16x32_bf16 v[18:21], v[182:185], v[238:241], v[18:21]
	v_mfma_f32_16x16x32_bf16 v[2:5], v[182:185], v[246:249], 0
	v_mfma_f32_16x16x32_bf16 v[2:5], v[186:189], v[250:253], v[2:5]
	v_mfma_f32_16x16x32_bf16 v[6:9], v[178:181], v[250:253], 0
	v_mfma_f32_16x16x32_bf16 v[6:9], v[174:177], v[246:249], v[6:9]
	v_mfma_f32_16x16x32_bf16 v[10:13], v[164:167], v[246:249], 0
	v_mfma_f32_16x16x32_bf16 v[10:13], v[168:171], v[250:253], v[10:13]
	v_mfma_f32_16x16x32_bf16 v[14:17], v[160:163], v[250:253], 0
	v_mfma_f32_16x16x32_bf16 v[14:17], v[156:159], v[246:249], v[14:17]
	s_setprio 0
	s_waitcnt vmcnt(0)
	s_barrier
; #define PG8_STAGE(bufoff, gbase, voff) do { _Pragma("unroll") for (int _i = 0; _i < 2; ++_i) \
;         __builtin_amdgcn_global_load_lds((const unsigned*)((const char*)(gbase) + (voff)[_i]), (PG8_LAS unsigned*)(lds + (bufoff) + ldsw + _i * 8192), 16, 0, 0); } while (0)
; #define PG8_LDA(dst, b, h) do { _Pragma("unroll") for (int m = 0; m < 4; ++m) _Pragma("unroll") for (int k = 0; k < 2; ++k) dst[m][k] = *(const PG8_LAS bf16x8*)(lds + PG8_SA(b, h) + aoff + m * 2048 + k * 1024); } while (0)
; #define PG8_LDB(dst, b, h) do { _Pragma("unroll") for (int n = 0; n < 2; ++n) _Pragma("unroll") for (int k = 0; k < 2; ++k) dst[n][k] = *(const PG8_LAS bf16x8*)(lds + PG8_SB(b, h) + boff + n * 2048 + k * 1024); } while (0)
; #define PG8_MMA(ai, bj, At, Bt) do { __builtin_amdgcn_s_setprio(1); _Pragma("unroll") for (int m = 0; m < 4; ++m) _Pragma("unroll") for (int n = 0; n < 2; ++n) _Pragma("unroll") for (int k = 0; k < 2; ++k) \
;         acc[ai][bj][m][n] = __builtin_amdgcn_mfma_f32_16x16x32_bf16(Bt[n][k], At[m][k], acc[ai][bj][m][n], 0, 0, 0); __builtin_amdgcn_s_setprio(0); } while (0)
; #define PG8_WAIT_V(n) asm volatile("s_waitcnt vmcnt(" #n ")" ::: "memory")
; template <class Epi, class Sched, bool ALIGN_EPI>
; __device__ __forceinline__ void gemm_phase(PG8_LAS unsigned char* lds, const Gemm g, const Sched& S, const Epi& E) {
;     ...
;             PG8_LDB(B0, 0, 0); PG8_LDB(B1, 0, 1); PG8_SCHED; PG8_LDA(At, 0, 0); PG8_STAGE(PG8_SA(1, 1), a1 + hstepA, voffA);
;             PG8_WAIT_V(8); PG8_WAIT_L(0); PG8_BAR; PG8_MMA(0, 0, At, B0); PG8_MMA(0, 1, At, B1); PG8_BAR; PG8_SCHED;
;             PG8_LDA(At, 0, 1); PG8_STAGE(PG8_SB(0, 0), b2, voffB); PG8_STAGE(PG8_SB(0, 1), b2 + hstepB, voffB); PG8_STAGE(PG8_SA(0, 0), a2, voffA);
;             PG8_WAIT_V(8); PG8_WAIT_L(0); PG8_BAR; PG8_MMA(1, 0, At, B0); PG8_MMA(1, 1, At, B1); PG8_BAR; PG8_SCHED;
;             PG8_LDB(B0, 1, 0); PG8_LDB(B1, 1, 1); PG8_SCHED; PG8_LDA(At, 1, 0); PG8_STAGE(PG8_SA(0, 1), a2 + hstepA, voffA);
;             PG8_WAIT_V(8); PG8_WAIT_L(0); PG8_BAR; PG8_MMA(0, 0, At, B0); PG8_MMA(0, 1, At, B1); PG8_BAR; PG8_SCHED;
;             PG8_LDA(At, 1, 1); PG8_STAGE(PG8_SB(1, 0), b3, voffB); PG8_STAGE(PG8_SB(1, 1), b3 + hstepB, voffB); PG8_STAGE(PG8_SA(1, 0), a3, voffA);
;             PG8_WAIT_V(8); PG8_WAIT_L(0); PG8_BAR; PG8_MMA(1, 0, At, B0); PG8_MMA(1, 1, At, B1); PG8_BAR; PG8_SCHED;
	s_setprio 2
	ds_read_b128 v[190:193], v155 offset:32768
	ds_read_b128 v[194:197], v155 offset:33792
	ds_read_b128 v[198:201], v155 offset:34816
	s_cmp_eq_u32 s49, 15
	s_cselect_b32 s28, s50, s28
	s_cselect_b32 s29, s51, s29
	s_add_i32 m0, s2, 0x10000
	s_nop 0
	global_load_lds_dwordx4 v134, s[28:29]
	ds_read_b128 v[202:205], v155 offset:35840
	ds_read_b128 v[206:209], v155 offset:36864
	ds_read_b128 v[210:213], v155 offset:37888
	s_add_i32 m0, s2, 0x12000
	s_nop 0
	global_load_lds_dwordx4 v130, s[28:29]
	ds_read_b128 v[214:217], v155 offset:38912
	ds_read_b128 v[218:221], v155 offset:39936
	ds_read_b128 v[156:159], v153 offset:32768
	s_add_u32 s30, s28, 0x20000
	s_addc_u32 s31, s29, 0
	s_add_i32 m0, s2, 0x11000
	s_nop 0
	global_load_lds_dwordx4 v134, s[30:31]
	ds_read_b128 v[160:163], v153 offset:33792
	ds_read_b128 v[164:167], v153 offset:34816
	ds_read_b128 v[168:171], v153 offset:35840
	s_add_i32 m0, s2, 0x13000
	s_nop 0
	global_load_lds_dwordx4 v130, s[30:31]
	ds_read_b128 v[174:177], v153 offset:49152
	ds_read_b128 v[178:181], v153 offset:50176
	ds_read_b128 v[182:185], v153 offset:51200
	s_add_u32 s30, s28, 0x80000
	s_addc_u32 s31, s29, 0
	s_add_i32 m0, s2, 0x14000
	s_nop 0
	global_load_lds_dwordx4 v134, s[30:31]
	ds_read_b128 v[186:189], v153 offset:52224
	ds_read_b128 v[222:225], v155 offset:49152
	ds_read_b128 v[226:229], v155 offset:50176
	s_add_i32 m0, s2, 0x16000
	s_nop 0
	global_load_lds_dwordx4 v130, s[30:31]
	ds_read_b128 v[230:233], v155 offset:51200
	ds_read_b128 v[234:237], v155 offset:52224
	ds_read_b128 v[238:241], v155 offset:53248
	s_add_u32 s30, s28, 0xa0000
	s_addc_u32 s31, s29, 0
	s_add_i32 m0, s2, 0x15000
	s_nop 0
	global_load_lds_dwordx4 v134, s[30:31]
	ds_read_b128 v[242:245], v155 offset:54272
	ds_read_b128 v[246:249], v155 offset:55296
	ds_read_b128 v[250:253], v155 offset:56320
	s_add_i32 m0, s2, 0x17000
	s_nop 0
	global_load_lds_dwordx4 v130, s[30:31]
	s_add_u32 s28, s28, 0x80
	s_addc_u32 s29, s29, 0
	s_waitcnt vmcnt(8) lgkmcnt(0)
	s_barrier
	s_setprio 1
	v_mfma_f32_16x16x32_bf16 v[126:129], v[156:159], v[190:193], v[126:129]
	v_mfma_f32_16x16x32_bf16 v[126:129], v[160:163], v[194:197], v[126:129]
	v_mfma_f32_16x16x32_bf16 v[122:125], v[168:171], v[194:197], v[122:125]
	v_mfma_f32_16x16x32_bf16 v[122:125], v[164:167], v[190:193], v[122:125]
	v_mfma_f32_16x16x32_bf16 v[118:121], v[174:177], v[190:193], v[118:121]
	v_mfma_f32_16x16x32_bf16 v[118:121], v[178:181], v[194:197], v[118:121]
	v_mfma_f32_16x16x32_bf16 v[114:117], v[186:189], v[194:197], v[114:117]
	v_mfma_f32_16x16x32_bf16 v[114:117], v[182:185], v[190:193], v[114:117]
	v_mfma_f32_16x16x32_bf16 v[98:101], v[182:185], v[198:201], v[98:101]
	v_mfma_f32_16x16x32_bf16 v[98:101], v[186:189], v[202:205], v[98:101]
	v_mfma_f32_16x16x32_bf16 v[102:105], v[178:181], v[202:205], v[102:105]
	v_mfma_f32_16x16x32_bf16 v[102:105], v[174:177], v[198:201], v[102:105]
	v_mfma_f32_16x16x32_bf16 v[106:109], v[164:167], v[198:201], v[106:109]
	v_mfma_f32_16x16x32_bf16 v[106:109], v[168:171], v[202:205], v[106:109]
	v_mfma_f32_16x16x32_bf16 v[110:113], v[160:163], v[202:205], v[110:113]
	v_mfma_f32_16x16x32_bf16 v[110:113], v[156:159], v[198:201], v[110:113]
	v_mfma_f32_16x16x32_bf16 v[94:97], v[156:159], v[206:209], v[94:97]
	v_mfma_f32_16x16x32_bf16 v[94:97], v[160:163], v[210:213], v[94:97]
	v_mfma_f32_16x16x32_bf16 v[90:93], v[168:171], v[210:213], v[90:93]
	v_mfma_f32_16x16x32_bf16 v[90:93], v[164:167], v[206:209], v[90:93]
	v_mfma_f32_16x16x32_bf16 v[86:89], v[174:177], v[206:209], v[86:89]
	v_mfma_f32_16x16x32_bf16 v[86:89], v[178:181], v[210:213], v[86:89]
	v_mfma_f32_16x16x32_bf16 v[82:85], v[186:189], v[210:213], v[82:85]
	v_mfma_f32_16x16x32_bf16 v[82:85], v[182:185], v[206:209], v[82:85]
	v_mfma_f32_16x16x32_bf16 v[66:69], v[182:185], v[214:217], v[66:69]
	v_mfma_f32_16x16x32_bf16 v[66:69], v[186:189], v[218:221], v[66:69]
	v_mfma_f32_16x16x32_bf16 v[70:73], v[178:181], v[218:221], v[70:73]
	v_mfma_f32_16x16x32_bf16 v[70:73], v[174:177], v[214:217], v[70:73]
	v_mfma_f32_16x16x32_bf16 v[74:77], v[164:167], v[214:217], v[74:77]
	v_mfma_f32_16x16x32_bf16 v[74:77], v[168:171], v[218:221], v[74:77]
	v_mfma_f32_16x16x32_bf16 v[78:81], v[160:163], v[218:221], v[78:81]
	v_mfma_f32_16x16x32_bf16 v[78:81], v[156:159], v[214:217], v[78:81]
	v_mfma_f32_16x16x32_bf16 v[62:65], v[156:159], v[222:225], v[62:65]
	v_mfma_f32_16x16x32_bf16 v[62:65], v[160:163], v[226:229], v[62:65]
	v_mfma_f32_16x16x32_bf16 v[58:61], v[168:171], v[226:229], v[58:61]
	v_mfma_f32_16x16x32_bf16 v[58:61], v[164:167], v[222:225], v[58:61]
	v_mfma_f32_16x16x32_bf16 v[54:57], v[174:177], v[222:225], v[54:57]
	v_mfma_f32_16x16x32_bf16 v[54:57], v[178:181], v[226:229], v[54:57]
	v_mfma_f32_16x16x32_bf16 v[50:53], v[186:189], v[226:229], v[50:53]
	v_mfma_f32_16x16x32_bf16 v[50:53], v[182:185], v[222:225], v[50:53]
	v_mfma_f32_16x16x32_bf16 v[34:37], v[182:185], v[230:233], v[34:37]
	v_mfma_f32_16x16x32_bf16 v[34:37], v[186:189], v[234:237], v[34:37]
	v_mfma_f32_16x16x32_bf16 v[38:41], v[178:181], v[234:237], v[38:41]
	v_mfma_f32_16x16x32_bf16 v[38:41], v[174:177], v[230:233], v[38:41]
	v_mfma_f32_16x16x32_bf16 v[42:45], v[164:167], v[230:233], v[42:45]
	v_mfma_f32_16x16x32_bf16 v[42:45], v[168:171], v[234:237], v[42:45]
	v_mfma_f32_16x16x32_bf16 v[46:49], v[160:163], v[234:237], v[46:49]
	v_mfma_f32_16x16x32_bf16 v[46:49], v[156:159], v[230:233], v[46:49]
	v_mfma_f32_16x16x32_bf16 v[30:33], v[156:159], v[238:241], v[30:33]
	v_mfma_f32_16x16x32_bf16 v[30:33], v[160:163], v[242:245], v[30:33]
	v_mfma_f32_16x16x32_bf16 v[26:29], v[168:171], v[242:245], v[26:29]
	v_mfma_f32_16x16x32_bf16 v[26:29], v[164:167], v[238:241], v[26:29]
	v_mfma_f32_16x16x32_bf16 v[22:25], v[174:177], v[238:241], v[22:25]
	v_mfma_f32_16x16x32_bf16 v[22:25], v[178:181], v[242:245], v[22:25]
	v_mfma_f32_16x16x32_bf16 v[18:21], v[186:189], v[242:245], v[18:21]
	v_mfma_f32_16x16x32_bf16 v[18:21], v[182:185], v[238:241], v[18:21]
	v_mfma_f32_16x16x32_bf16 v[2:5], v[182:185], v[246:249], v[2:5]
	v_mfma_f32_16x16x32_bf16 v[2:5], v[186:189], v[250:253], v[2:5]
	v_mfma_f32_16x16x32_bf16 v[6:9], v[178:181], v[250:253], v[6:9]
	v_mfma_f32_16x16x32_bf16 v[6:9], v[174:177], v[246:249], v[6:9]
	v_mfma_f32_16x16x32_bf16 v[10:13], v[164:167], v[246:249], v[10:13]
	v_mfma_f32_16x16x32_bf16 v[10:13], v[168:171], v[250:253], v[10:13]
	v_mfma_f32_16x16x32_bf16 v[14:17], v[160:163], v[250:253], v[14:17]
	v_mfma_f32_16x16x32_bf16 v[14:17], v[156:159], v[246:249], v[14:17]
	s_setprio 0
	s_waitcnt vmcnt(0)
	s_barrier
	s_add_i32 s49, s49, 1
; #define PG8_STAGE(bufoff, gbase, voff) do { _Pragma("unroll") for (int _i = 0; _i < 2; ++_i) \
;         __builtin_amdgcn_global_load_lds((const unsigned*)((const char*)(gbase) + (voff)[_i]), (PG8_LAS unsigned*)(lds + (bufoff) + ldsw + _i * 8192), 16, 0, 0); } while (0)
; #define PG8_LDA(dst, b, h) do { _Pragma("unroll") for (int m = 0; m < 4; ++m) _Pragma("unroll") for (int k = 0; k < 2; ++k) dst[m][k] = *(const PG8_LAS bf16x8*)(lds + PG8_SA(b, h) + aoff + m * 2048 + k * 1024); } while (0)
; #define PG8_LDB(dst, b, h) do { _Pragma("unroll") for (int n = 0; n < 2; ++n) _Pragma("unroll") for (int k = 0; k < 2; ++k) dst[n][k] = *(const PG8_LAS bf16x8*)(lds + PG8_SB(b, h) + boff + n * 2048 + k * 1024); } while (0)
; #define PG8_MMA(ai, bj, At, Bt) do { __builtin_amdgcn_s_setprio(1); _Pragma("unroll") for (int m = 0; m < 4; ++m) _Pragma("unroll") for (int n = 0; n < 2; ++n) _Pragma("unroll") for (int k = 0; k < 2; ++k) \
;         acc[ai][bj][m][n] = __builtin_amdgcn_mfma_f32_16x16x32_bf16(Bt[n][k], At[m][k], acc[ai][bj][m][n], 0, 0, 0); __builtin_amdgcn_s_setprio(0); } while (0)
; #define PG8_WAIT_V(n) asm volatile("s_waitcnt vmcnt(" #n ")" ::: "memory")
; template <class Epi, class Sched, bool ALIGN_EPI>
; __device__ __forceinline__ void gemm_phase(PG8_LAS unsigned char* lds, const Gemm g, const Sched& S, const Epi& E) {
;     ...
;             PG8_LDB(B0, 0, 0); PG8_LDB(B1, 0, 1); PG8_SCHED; PG8_LDA(At, 0, 0); PG8_STAGE(PG8_SA(1, 1), a1 + hstepA, voffA);
;             PG8_WAIT_V(8); PG8_WAIT_L(0); PG8_BAR; PG8_MMA(0, 0, At, B0); PG8_MMA(0, 1, At, B1); PG8_BAR; PG8_SCHED;
;             PG8_LDA(At, 0, 1); PG8_STAGE(PG8_SB(0, 0), b2, voffB); PG8_STAGE(PG8_SB(0, 1), b2 + hstepB, voffB); PG8_STAGE(PG8_SA(0, 0), a2, voffA);
;             PG8_WAIT_V(8); PG8_WAIT_L(0); PG8_BAR; PG8_MMA(1, 0, At, B0); PG8_MMA(1, 1, At, B1); PG8_BAR; PG8_SCHED;
;             PG8_LDB(B0, 1, 0); PG8_LDB(B1, 1, 1); PG8_SCHED; PG8_LDA(At, 1, 0); PG8_STAGE(PG8_SA(0, 1), a2 + hstepA, voffA);
;             PG8_WAIT_V(8); PG8_WAIT_L(0); PG8_BAR; PG8_MMA(0, 0, At, B0); PG8_MMA(0, 1, At, B1); PG8_BAR; PG8_SCHED;
;             PG8_LDA(At, 1, 1); PG8_STAGE(PG8_SB(1, 0), b3, voffB); PG8_STAGE(PG8_SB(1, 1), b3 + hstepB, voffB); PG8_STAGE(PG8_SA(1, 0), a3, voffA);
;             PG8_WAIT_V(8); PG8_WAIT_L(0); PG8_BAR; PG8_MMA(1, 0, At, B0); PG8_MMA(1, 1, At, B1); PG8_BAR; PG8_SCHED;
.Lp8k_A_loop:
	s_setprio 2
	ds_read_b128 v[190:193], v155 offset:0
	ds_read_b128 v[194:197], v155 offset:1024
	ds_read_b128 v[198:201], v155 offset:2048
	s_add_i32 m0, s2, 0x18000
	s_nop 0
	global_load_lds_dwordx4 v134, s[28:29]
	ds_read_b128 v[202:205], v155 offset:3072
	ds_read_b128 v[206:209], v155 offset:4096
	ds_read_b128 v[210:213], v155 offset:5120
	s_add_i32 m0, s2, 0x1a000
	s_nop 0
	global_load_lds_dwordx4 v130, s[28:29]
	ds_read_b128 v[214:217], v155 offset:6144
	ds_read_b128 v[218:221], v155 offset:7168
	ds_read_b128 v[156:159], v153 offset:0
	s_add_u32 s30, s28, 0x20000
	s_addc_u32 s31, s29, 0
	s_add_i32 m0, s2, 0x19000
	s_nop 0
	global_load_lds_dwordx4 v134, s[30:31]
	ds_read_b128 v[160:163], v153 offset:1024
	ds_read_b128 v[164:167], v153 offset:2048
	ds_read_b128 v[168:171], v153 offset:3072
	s_add_i32 m0, s2, 0x1b000
	s_nop 0
	global_load_lds_dwordx4 v130, s[30:31]
	ds_read_b128 v[174:177], v153 offset:16384
	ds_read_b128 v[178:181], v153 offset:17408
	ds_read_b128 v[182:185], v153 offset:18432
	s_add_u32 s30, s28, 0x80000
	s_addc_u32 s31, s29, 0
	s_add_i32 m0, s2, 0x1c000
	s_nop 0
	global_load_lds_dwordx4 v134, s[30:31]
	ds_read_b128 v[186:189], v153 offset:19456
	ds_read_b128 v[222:225], v155 offset:16384
	ds_read_b128 v[226:229], v155 offset:17408
	s_add_i32 m0, s2, 0x1e000
	s_nop 0
	global_load_lds_dwordx4 v130, s[30:31]
	ds_read_b128 v[230:233], v155 offset:18432
	ds_read_b128 v[234:237], v155 offset:19456
	ds_read_b128 v[238:241], v155 offset:20480
	s_add_u32 s30, s28, 0xa0000
	s_addc_u32 s31, s29, 0
	s_add_i32 m0, s2, 0x1d000
	s_nop 0
	global_load_lds_dwordx4 v134, s[30:31]
	ds_read_b128 v[242:245], v155 offset:21504
	ds_read_b128 v[246:249], v155 offset:22528
	ds_read_b128 v[250:253], v155 offset:23552
	s_add_i32 m0, s2, 0x1f000
	s_nop 0
	global_load_lds_dwordx4 v130, s[30:31]
	s_add_u32 s28, s28, 0x80
	s_addc_u32 s29, s29, 0
	s_waitcnt vmcnt(8) lgkmcnt(0)
	s_barrier
	s_setprio 1
	v_mfma_f32_16x16x32_bf16 v[126:129], v[156:159], v[190:193], v[126:129]
	v_mfma_f32_16x16x32_bf16 v[126:129], v[160:163], v[194:197], v[126:129]
	v_mfma_f32_16x16x32_bf16 v[122:125], v[168:171], v[194:197], v[122:125]
	v_mfma_f32_16x16x32_bf16 v[122:125], v[164:167], v[190:193], v[122:125]
	v_mfma_f32_16x16x32_bf16 v[118:121], v[174:177], v[190:193], v[118:121]
	v_mfma_f32_16x16x32_bf16 v[118:121], v[178:181], v[194:197], v[118:121]
	v_mfma_f32_16x16x32_bf16 v[114:117], v[186:189], v[194:197], v[114:117]
	v_mfma_f32_16x16x32_bf16 v[114:117], v[182:185], v[190:193], v[114:117]
	v_mfma_f32_16x16x32_bf16 v[98:101], v[182:185], v[198:201], v[98:101]
	v_mfma_f32_16x16x32_bf16 v[98:101], v[186:189], v[202:205], v[98:101]
	v_mfma_f32_16x16x32_bf16 v[102:105], v[178:181], v[202:205], v[102:105]
	v_mfma_f32_16x16x32_bf16 v[102:105], v[174:177], v[198:201], v[102:105]
	v_mfma_f32_16x16x32_bf16 v[106:109], v[164:167], v[198:201], v[106:109]
	v_mfma_f32_16x16x32_bf16 v[106:109], v[168:171], v[202:205], v[106:109]
	v_mfma_f32_16x16x32_bf16 v[110:113], v[160:163], v[202:205], v[110:113]
	v_mfma_f32_16x16x32_bf16 v[110:113], v[156:159], v[198:201], v[110:113]
	v_mfma_f32_16x16x32_bf16 v[94:97], v[156:159], v[206:209], v[94:97]
	v_mfma_f32_16x16x32_bf16 v[94:97], v[160:163], v[210:213], v[94:97]
	v_mfma_f32_16x16x32_bf16 v[90:93], v[168:171], v[210:213], v[90:93]
	v_mfma_f32_16x16x32_bf16 v[90:93], v[164:167], v[206:209], v[90:93]
	v_mfma_f32_16x16x32_bf16 v[86:89], v[174:177], v[206:209], v[86:89]
	v_mfma_f32_16x16x32_bf16 v[86:89], v[178:181], v[210:213], v[86:89]
	v_mfma_f32_16x16x32_bf16 v[82:85], v[186:189], v[210:213], v[82:85]
	v_mfma_f32_16x16x32_bf16 v[82:85], v[182:185], v[206:209], v[82:85]
	v_mfma_f32_16x16x32_bf16 v[66:69], v[182:185], v[214:217], v[66:69]
	v_mfma_f32_16x16x32_bf16 v[66:69], v[186:189], v[218:221], v[66:69]
	v_mfma_f32_16x16x32_bf16 v[70:73], v[178:181], v[218:221], v[70:73]
	v_mfma_f32_16x16x32_bf16 v[70:73], v[174:177], v[214:217], v[70:73]
	v_mfma_f32_16x16x32_bf16 v[74:77], v[164:167], v[214:217], v[74:77]
	v_mfma_f32_16x16x32_bf16 v[74:77], v[168:171], v[218:221], v[74:77]
	v_mfma_f32_16x16x32_bf16 v[78:81], v[160:163], v[218:221], v[78:81]
	v_mfma_f32_16x16x32_bf16 v[78:81], v[156:159], v[214:217], v[78:81]
	v_mfma_f32_16x16x32_bf16 v[62:65], v[156:159], v[222:225], v[62:65]
	v_mfma_f32_16x16x32_bf16 v[62:65], v[160:163], v[226:229], v[62:65]
	v_mfma_f32_16x16x32_bf16 v[58:61], v[168:171], v[226:229], v[58:61]
	v_mfma_f32_16x16x32_bf16 v[58:61], v[164:167], v[222:225], v[58:61]
	v_mfma_f32_16x16x32_bf16 v[54:57], v[174:177], v[222:225], v[54:57]
	v_mfma_f32_16x16x32_bf16 v[54:57], v[178:181], v[226:229], v[54:57]
	v_mfma_f32_16x16x32_bf16 v[50:53], v[186:189], v[226:229], v[50:53]
	v_mfma_f32_16x16x32_bf16 v[50:53], v[182:185], v[222:225], v[50:53]
	v_mfma_f32_16x16x32_bf16 v[34:37], v[182:185], v[230:233], v[34:37]
	v_mfma_f32_16x16x32_bf16 v[34:37], v[186:189], v[234:237], v[34:37]
	v_mfma_f32_16x16x32_bf16 v[38:41], v[178:181], v[234:237], v[38:41]
	v_mfma_f32_16x16x32_bf16 v[38:41], v[174:177], v[230:233], v[38:41]
	v_mfma_f32_16x16x32_bf16 v[42:45], v[164:167], v[230:233], v[42:45]
	v_mfma_f32_16x16x32_bf16 v[42:45], v[168:171], v[234:237], v[42:45]
	v_mfma_f32_16x16x32_bf16 v[46:49], v[160:163], v[234:237], v[46:49]
	v_mfma_f32_16x16x32_bf16 v[46:49], v[156:159], v[230:233], v[46:49]
	v_mfma_f32_16x16x32_bf16 v[30:33], v[156:159], v[238:241], v[30:33]
	v_mfma_f32_16x16x32_bf16 v[30:33], v[160:163], v[242:245], v[30:33]
	v_mfma_f32_16x16x32_bf16 v[26:29], v[168:171], v[242:245], v[26:29]
	v_mfma_f32_16x16x32_bf16 v[26:29], v[164:167], v[238:241], v[26:29]
	v_mfma_f32_16x16x32_bf16 v[22:25], v[174:177], v[238:241], v[22:25]
	v_mfma_f32_16x16x32_bf16 v[22:25], v[178:181], v[242:245], v[22:25]
	v_mfma_f32_16x16x32_bf16 v[18:21], v[186:189], v[242:245], v[18:21]
	v_mfma_f32_16x16x32_bf16 v[18:21], v[182:185], v[238:241], v[18:21]
	v_mfma_f32_16x16x32_bf16 v[2:5], v[182:185], v[246:249], v[2:5]
	v_mfma_f32_16x16x32_bf16 v[2:5], v[186:189], v[250:253], v[2:5]
	v_mfma_f32_16x16x32_bf16 v[6:9], v[178:181], v[250:253], v[6:9]
	v_mfma_f32_16x16x32_bf16 v[6:9], v[174:177], v[246:249], v[6:9]
	v_mfma_f32_16x16x32_bf16 v[10:13], v[164:167], v[246:249], v[10:13]
	v_mfma_f32_16x16x32_bf16 v[10:13], v[168:171], v[250:253], v[10:13]
	v_mfma_f32_16x16x32_bf16 v[14:17], v[160:163], v[250:253], v[14:17]
	v_mfma_f32_16x16x32_bf16 v[14:17], v[156:159], v[246:249], v[14:17]
	s_setprio 0
	s_waitcnt vmcnt(0)
	s_barrier
; #define PG8_STAGE(bufoff, gbase, voff) do { _Pragma("unroll") for (int _i = 0; _i < 2; ++_i) \
;         __builtin_amdgcn_global_load_lds((const unsigned*)((const char*)(gbase) + (voff)[_i]), (PG8_LAS unsigned*)(lds + (bufoff) + ldsw + _i * 8192), 16, 0, 0); } while (0)
; #define PG8_LDA(dst, b, h) do { _Pragma("unroll") for (int m = 0; m < 4; ++m) _Pragma("unroll") for (int k = 0; k < 2; ++k) dst[m][k] = *(const PG8_LAS bf16x8*)(lds + PG8_SA(b, h) + aoff + m * 2048 + k * 1024); } while (0)
; #define PG8_LDB(dst, b, h) do { _Pragma("unroll") for (int n = 0; n < 2; ++n) _Pragma("unroll") for (int k = 0; k < 2; ++k) dst[n][k] = *(const PG8_LAS bf16x8*)(lds + PG8_SB(b, h) + boff + n * 2048 + k * 1024); } while (0)
; #define PG8_MMA(ai, bj, At, Bt) do { __builtin_amdgcn_s_setprio(1); _Pragma("unroll") for (int m = 0; m < 4; ++m) _Pragma("unroll") for (int n = 0; n < 2; ++n) _Pragma("unroll") for (int k = 0; k < 2; ++k) \
;         acc[ai][bj][m][n] = __builtin_amdgcn_mfma_f32_16x16x32_bf16(Bt[n][k], At[m][k], acc[ai][bj][m][n], 0, 0, 0); __builtin_amdgcn_s_setprio(0); } while (0)
; #define PG8_WAIT_V(n) asm volatile("s_waitcnt vmcnt(" #n ")" ::: "memory")
; template <class Epi, class Sched, bool ALIGN_EPI>
; __device__ __forceinline__ void gemm_phase(PG8_LAS unsigned char* lds, const Gemm g, const Sched& S, const Epi& E) {
;     ...
;             PG8_LDB(B0, 0, 0); PG8_LDB(B1, 0, 1); PG8_SCHED; PG8_LDA(At, 0, 0); PG8_STAGE(PG8_SA(1, 1), a1 + hstepA, voffA);
;             PG8_WAIT_V(8); PG8_WAIT_L(0); PG8_BAR; PG8_MMA(0, 0, At, B0); PG8_MMA(0, 1, At, B1); PG8_BAR; PG8_SCHED;
;             PG8_LDA(At, 0, 1); PG8_STAGE(PG8_SB(0, 0), b2, voffB); PG8_STAGE(PG8_SB(0, 1), b2 + hstepB, voffB); PG8_STAGE(PG8_SA(0, 0), a2, voffA);
;             PG8_WAIT_V(8); PG8_WAIT_L(0); PG8_BAR; PG8_MMA(1, 0, At, B0); PG8_MMA(1, 1, At, B1); PG8_BAR; PG8_SCHED;
;             PG8_LDB(B0, 1, 0); PG8_LDB(B1, 1, 1); PG8_SCHED; PG8_LDA(At, 1, 0); PG8_STAGE(PG8_SA(0, 1), a2 + hstepA, voffA);
;             PG8_WAIT_V(8); PG8_WAIT_L(0); PG8_BAR; PG8_MMA(0, 0, At, B0); PG8_MMA(0, 1, At, B1); PG8_BAR; PG8_SCHED;
;             PG8_LDA(At, 1, 1); PG8_STAGE(PG8_SB(1, 0), b3, voffB); PG8_STAGE(PG8_SB(1, 1), b3 + hstepB, voffB); PG8_STAGE(PG8_SA(1, 0), a3, voffA);
;             PG8_WAIT_V(8); PG8_WAIT_L(0); PG8_BAR; PG8_MMA(1, 0, At, B0); PG8_MMA(1, 1, At, B1); PG8_BAR; PG8_SCHED;
	s_setprio 2
	ds_read_b128 v[190:193], v155 offset:32768
	ds_read_b128 v[194:197], v155 offset:33792
	ds_read_b128 v[198:201], v155 offset:34816
	s_cmp_eq_u32 s49, 15
	s_cselect_b32 s28, s50, s28
	s_cselect_b32 s29, s51, s29
	s_add_i32 m0, s2, 0x10000
	s_nop 0
	global_load_lds_dwordx4 v134, s[28:29]
	ds_read_b128 v[202:205], v155 offset:35840
	ds_read_b128 v[206:209], v155 offset:36864
	ds_read_b128 v[210:213], v155 offset:37888
	s_add_i32 m0, s2, 0x12000
	s_nop 0
	global_load_lds_dwordx4 v130, s[28:29]
	ds_read_b128 v[214:217], v155 offset:38912
	ds_read_b128 v[218:221], v155 offset:39936
	ds_read_b128 v[156:159], v153 offset:32768
	s_add_u32 s30, s28, 0x20000
	s_addc_u32 s31, s29, 0
	s_add_i32 m0, s2, 0x11000
	s_nop 0
	global_load_lds_dwordx4 v134, s[30:31]
	ds_read_b128 v[160:163], v153 offset:33792
	ds_read_b128 v[164:167], v153 offset:34816
	ds_read_b128 v[168:171], v153 offset:35840
	s_add_i32 m0, s2, 0x13000
	s_nop 0
	global_load_lds_dwordx4 v130, s[30:31]
	ds_read_b128 v[174:177], v153 offset:49152
	ds_read_b128 v[178:181], v153 offset:50176
	ds_read_b128 v[182:185], v153 offset:51200
	s_add_u32 s30, s28, 0x80000
	s_addc_u32 s31, s29, 0
	s_add_i32 m0, s2, 0x14000
	s_nop 0
	global_load_lds_dwordx4 v134, s[30:31]
	ds_read_b128 v[186:189], v153 offset:52224
	ds_read_b128 v[222:225], v155 offset:49152
	ds_read_b128 v[226:229], v155 offset:50176
	s_add_i32 m0, s2, 0x16000
	s_nop 0
	global_load_lds_dwordx4 v130, s[30:31]
	ds_read_b128 v[230:233], v155 offset:51200
	ds_read_b128 v[234:237], v155 offset:52224
	ds_read_b128 v[238:241], v155 offset:53248
	s_add_u32 s30, s28, 0xa0000
	s_addc_u32 s31, s29, 0
	s_add_i32 m0, s2, 0x15000
	s_nop 0
	global_load_lds_dwordx4 v134, s[30:31]
	ds_read_b128 v[242:245], v155 offset:54272
	ds_read_b128 v[246:249], v155 offset:55296
	ds_read_b128 v[250:253], v155 offset:56320
	s_add_i32 m0, s2, 0x17000
	s_nop 0
	global_load_lds_dwordx4 v130, s[30:31]
	s_add_u32 s28, s28, 0x80
	s_addc_u32 s29, s29, 0
	s_waitcnt vmcnt(8) lgkmcnt(0)
	s_barrier
; #define PG8_STAGE(bufoff, gbase, voff) do { _Pragma("unroll") for (int _i = 0; _i < 2; ++_i) \
;         __builtin_amdgcn_global_load_lds((const unsigned*)((const char*)(gbase) + (voff)[_i]), (PG8_LAS unsigned*)(lds + (bufoff) + ldsw + _i * 8192), 16, 0, 0); } while (0)
; #define PG8_LDA(dst, b, h) do { _Pragma("unroll") for (int m = 0; m < 4; ++m) _Pragma("unroll") for (int k = 0; k < 2; ++k) dst[m][k] = *(const PG8_LAS bf16x8*)(lds + PG8_SA(b, h) + aoff + m * 2048 + k * 1024); } while (0)
; #define PG8_LDB(dst, b, h) do { _Pragma("unroll") for (int n = 0; n < 2; ++n) _Pragma("unroll") for (int k = 0; k < 2; ++k) dst[n][k] = *(const PG8_LAS bf16x8*)(lds + PG8_SB(b, h) + boff + n * 2048 + k * 1024); } while (0)
; #define PG8_MMA(ai, bj, At, Bt) do { __builtin_amdgcn_s_setprio(1); _Pragma("unroll") for (int m = 0; m < 4; ++m) _Pragma("unroll") for (int n = 0; n < 2; ++n) _Pragma("unroll") for (int k = 0; k < 2; ++k) \
;         acc[ai][bj][m][n] = __builtin_amdgcn_mfma_f32_16x16x32_bf16(Bt[n][k], At[m][k], acc[ai][bj][m][n], 0, 0, 0); __builtin_amdgcn_s_setprio(0); } while (0)
; #define PG8_WAIT_V(n) asm volatile("s_waitcnt vmcnt(" #n ")" ::: "memory")
; template <class Epi, class Sched, bool ALIGN_EPI>
; __device__ __forceinline__ void gemm_phase(PG8_LAS unsigned char* lds, const Gemm g, const Sched& S, const Epi& E) {
;     ...
;             PG8_LDB(B0, 0, 0); PG8_LDB(B1, 0, 1); PG8_SCHED; PG8_LDA(At, 0, 0); PG8_STAGE(PG8_SA(1, 1), a1 + hstepA, voffA);
;             PG8_WAIT_V(8); PG8_WAIT_L(0); PG8_BAR; PG8_MMA(0, 0, At, B0); PG8_MMA(0, 1, At, B1); PG8_BAR; PG8_SCHED;
;             PG8_LDA(At, 0, 1); PG8_STAGE(PG8_SB(0, 0), b2, voffB); PG8_STAGE(PG8_SB(0, 1), b2 + hstepB, voffB); PG8_STAGE(PG8_SA(0, 0), a2, voffA);
;             PG8_WAIT_V(8); PG8_WAIT_L(0); PG8_BAR; PG8_MMA(1, 0, At, B0); PG8_MMA(1, 1, At, B1); PG8_BAR; PG8_SCHED;
;             PG8_LDB(B0, 1, 0); PG8_LDB(B1, 1, 1); PG8_SCHED; PG8_LDA(At, 1, 0); PG8_STAGE(PG8_SA(0, 1), a2 + hstepA, voffA);
;             PG8_WAIT_V(8); PG8_WAIT_L(0); PG8_BAR; PG8_MMA(0, 0, At, B0); PG8_MMA(0, 1, At, B1); PG8_BAR; PG8_SCHED;
;             PG8_LDA(At, 1, 1); PG8_STAGE(PG8_SB(1, 0), b3, voffB); PG8_STAGE(PG8_SB(1, 1), b3 + hstepB, voffB); PG8_STAGE(PG8_SA(1, 0), a3, voffA);
;             PG8_WAIT_V(8); PG8_WAIT_L(0); PG8_BAR; PG8_MMA(1, 0, At, B0); PG8_MMA(1, 1, At, B1); PG8_BAR; PG8_SCHED;
	s_setprio 1
	v_mfma_f32_16x16x32_bf16 v[126:129], v[156:159], v[190:193], v[126:129]
	v_mfma_f32_16x16x32_bf16 v[126:129], v[160:163], v[194:197], v[126:129]
	v_mfma_f32_16x16x32_bf16 v[122:125], v[168:171], v[194:197], v[122:125]
	v_mfma_f32_16x16x32_bf16 v[122:125], v[164:167], v[190:193], v[122:125]
	v_mfma_f32_16x16x32_bf16 v[118:121], v[174:177], v[190:193], v[118:121]
	v_mfma_f32_16x16x32_bf16 v[118:121], v[178:181], v[194:197], v[118:121]
	v_mfma_f32_16x16x32_bf16 v[114:117], v[186:189], v[194:197], v[114:117]
	v_mfma_f32_16x16x32_bf16 v[114:117], v[182:185], v[190:193], v[114:117]
	v_mfma_f32_16x16x32_bf16 v[98:101], v[182:185], v[198:201], v[98:101]
	v_mfma_f32_16x16x32_bf16 v[98:101], v[186:189], v[202:205], v[98:101]
	v_mfma_f32_16x16x32_bf16 v[102:105], v[178:181], v[202:205], v[102:105]
	v_mfma_f32_16x16x32_bf16 v[102:105], v[174:177], v[198:201], v[102:105]
	v_mfma_f32_16x16x32_bf16 v[106:109], v[164:167], v[198:201], v[106:109]
	v_mfma_f32_16x16x32_bf16 v[106:109], v[168:171], v[202:205], v[106:109]
	v_mfma_f32_16x16x32_bf16 v[110:113], v[160:163], v[202:205], v[110:113]
	v_mfma_f32_16x16x32_bf16 v[110:113], v[156:159], v[198:201], v[110:113]
	v_mfma_f32_16x16x32_bf16 v[94:97], v[156:159], v[206:209], v[94:97]
	v_mfma_f32_16x16x32_bf16 v[94:97], v[160:163], v[210:213], v[94:97]
	v_mfma_f32_16x16x32_bf16 v[90:93], v[168:171], v[210:213], v[90:93]
	v_mfma_f32_16x16x32_bf16 v[90:93], v[164:167], v[206:209], v[90:93]
	v_mfma_f32_16x16x32_bf16 v[86:89], v[174:177], v[206:209], v[86:89]
	v_mfma_f32_16x16x32_bf16 v[86:89], v[178:181], v[210:213], v[86:89]
	v_mfma_f32_16x16x32_bf16 v[82:85], v[186:189], v[210:213], v[82:85]
	v_mfma_f32_16x16x32_bf16 v[82:85], v[182:185], v[206:209], v[82:85]
	v_mfma_f32_16x16x32_bf16 v[66:69], v[182:185], v[214:217], v[66:69]
	v_mfma_f32_16x16x32_bf16 v[66:69], v[186:189], v[218:221], v[66:69]
	v_mfma_f32_16x16x32_bf16 v[70:73], v[178:181], v[218:221], v[70:73]
	v_mfma_f32_16x16x32_bf16 v[70:73], v[174:177], v[214:217], v[70:73]
	v_mfma_f32_16x16x32_bf16 v[74:77], v[164:167], v[214:217], v[74:77]
	v_mfma_f32_16x16x32_bf16 v[74:77], v[168:171], v[218:221], v[74:77]
	v_mfma_f32_16x16x32_bf16 v[78:81], v[160:163], v[218:221], v[78:81]
	v_mfma_f32_16x16x32_bf16 v[78:81], v[156:159], v[214:217], v[78:81]
	v_mfma_f32_16x16x32_bf16 v[62:65], v[156:159], v[222:225], v[62:65]
	v_mfma_f32_16x16x32_bf16 v[62:65], v[160:163], v[226:229], v[62:65]
	v_mfma_f32_16x16x32_bf16 v[58:61], v[168:171], v[226:229], v[58:61]
	v_mfma_f32_16x16x32_bf16 v[58:61], v[164:167], v[222:225], v[58:61]
	v_mfma_f32_16x16x32_bf16 v[54:57], v[174:177], v[222:225], v[54:57]
	v_mfma_f32_16x16x32_bf16 v[54:57], v[178:181], v[226:229], v[54:57]
	v_mfma_f32_16x16x32_bf16 v[50:53], v[186:189], v[226:229], v[50:53]
	v_mfma_f32_16x16x32_bf16 v[50:53], v[182:185], v[222:225], v[50:53]
	v_mfma_f32_16x16x32_bf16 v[34:37], v[182:185], v[230:233], v[34:37]
	v_mfma_f32_16x16x32_bf16 v[34:37], v[186:189], v[234:237], v[34:37]
	v_mfma_f32_16x16x32_bf16 v[38:41], v[178:181], v[234:237], v[38:41]
	v_mfma_f32_16x16x32_bf16 v[38:41], v[174:177], v[230:233], v[38:41]
	v_mfma_f32_16x16x32_bf16 v[42:45], v[164:167], v[230:233], v[42:45]
	v_mfma_f32_16x16x32_bf16 v[42:45], v[168:171], v[234:237], v[42:45]
	v_mfma_f32_16x16x32_bf16 v[46:49], v[160:163], v[234:237], v[46:49]
	v_mfma_f32_16x16x32_bf16 v[46:49], v[156:159], v[230:233], v[46:49]
	v_mfma_f32_16x16x32_bf16 v[30:33], v[156:159], v[238:241], v[30:33]
	v_mfma_f32_16x16x32_bf16 v[30:33], v[160:163], v[242:245], v[30:33]
	v_mfma_f32_16x16x32_bf16 v[26:29], v[168:171], v[242:245], v[26:29]
	v_mfma_f32_16x16x32_bf16 v[26:29], v[164:167], v[238:241], v[26:29]
	v_mfma_f32_16x16x32_bf16 v[22:25], v[174:177], v[238:241], v[22:25]
	v_mfma_f32_16x16x32_bf16 v[22:25], v[178:181], v[242:245], v[22:25]
	v_mfma_f32_16x16x32_bf16 v[18:21], v[186:189], v[242:245], v[18:21]
	v_mfma_f32_16x16x32_bf16 v[18:21], v[182:185], v[238:241], v[18:21]
	v_mfma_f32_16x16x32_bf16 v[2:5], v[182:185], v[246:249], v[2:5]
	v_mfma_f32_16x16x32_bf16 v[2:5], v[186:189], v[250:253], v[2:5]
	v_mfma_f32_16x16x32_bf16 v[6:9], v[178:181], v[250:253], v[6:9]
	v_mfma_f32_16x16x32_bf16 v[6:9], v[174:177], v[246:249], v[6:9]
	v_mfma_f32_16x16x32_bf16 v[10:13], v[164:167], v[246:249], v[10:13]
	v_mfma_f32_16x16x32_bf16 v[10:13], v[168:171], v[250:253], v[10:13]
	v_mfma_f32_16x16x32_bf16 v[14:17], v[160:163], v[250:253], v[14:17]
	v_mfma_f32_16x16x32_bf16 v[14:17], v[156:159], v[246:249], v[14:17]
	s_setprio 0
	s_waitcnt vmcnt(0)
	s_barrier
	s_add_i32 s49, s49, 1
	s_cmp_lt_u32 s49, 16
	s_cbranch_scc1 .Lp8k_A_loop
	s_setprio 2
	ds_read_b128 v[190:193], v155 offset:0
	ds_read_b128 v[194:197], v155 offset:1024
	ds_read_b128 v[198:201], v155 offset:2048
	s_add_i32 m0, s2, 0x18000
	s_nop 0
	global_load_lds_dwordx4 v134, s[28:29]
	ds_read_b128 v[202:205], v155 offset:3072
	ds_read_b128 v[206:209], v155 offset:4096
	ds_read_b128 v[210:213], v155 offset:5120
	s_add_i32 m0, s2, 0x1a000
	s_nop 0
	global_load_lds_dwordx4 v130, s[28:29]
	ds_read_b128 v[214:217], v155 offset:6144
	ds_read_b128 v[218:221], v155 offset:7168
	ds_read_b128 v[164:167], v153 offset:2048
	s_add_u32 s30, s28, 0x20000
	s_addc_u32 s31, s29, 0
	s_add_i32 m0, s2, 0x19000
	s_nop 0
	global_load_lds_dwordx4 v134, s[30:31]
	ds_read_b128 v[168:171], v153 offset:3072
	ds_read_b128 v[174:177], v153 offset:16384
	ds_read_b128 v[178:181], v153 offset:17408
	s_add_i32 m0, s2, 0x1b000
	s_nop 0
	global_load_lds_dwordx4 v130, s[30:31]
	ds_read_b128 v[182:185], v153 offset:18432
	ds_read_b128 v[186:189], v153 offset:19456
	ds_read_b128 v[222:225], v155 offset:16384
	s_add_u32 s30, s28, 0x80000
	s_addc_u32 s31, s29, 0
	s_add_i32 m0, s2, 0x1c000
	s_nop 0
	global_load_lds_dwordx4 v134, s[30:31]
	ds_read_b128 v[226:229], v155 offset:17408
	ds_read_b128 v[230:233], v155 offset:18432
	ds_read_b128 v[234:237], v155 offset:19456
	s_add_i32 m0, s2, 0x1e000
	s_nop 0
	global_load_lds_dwordx4 v130, s[30:31]
	ds_read_b128 v[238:241], v155 offset:20480
	ds_read_b128 v[242:245], v155 offset:21504
	ds_read_b128 v[246:249], v155 offset:22528
	s_add_u32 s30, s28, 0xa0000
	s_addc_u32 s31, s29, 0
	s_add_i32 m0, s2, 0x1d000
	s_nop 0
	global_load_lds_dwordx4 v134, s[30:31]
	ds_read_b128 v[250:253], v155 offset:23552
	s_add_i32 m0, s2, 0x1f000
	s_nop 0
	global_load_lds_dwordx4 v130, s[30:31]
	s_add_u32 s28, s28, 0x80
	s_addc_u32 s29, s29, 0
	s_branch .Lp8k_done

; #define PG8_STAGE(bufoff, gbase, voff) do { _Pragma("unroll") for (int _i = 0; _i < 2; ++_i) \
;         __builtin_amdgcn_global_load_lds((const unsigned*)((const char*)(gbase) + (voff)[_i]), (PG8_LAS unsigned*)(lds + (bufoff) + ldsw + _i * 8192), 16, 0, 0); } while (0)
; #define PG8_LDA(dst, b, h) do { _Pragma("unroll") for (int m = 0; m < 4; ++m) _Pragma("unroll") for (int k = 0; k < 2; ++k) dst[m][k] = *(const PG8_LAS bf16x8*)(lds + PG8_SA(b, h) + aoff + m * 2048 + k * 1024); } while (0)
; #define PG8_LDB(dst, b, h) do { _Pragma("unroll") for (int n = 0; n < 2; ++n) _Pragma("unroll") for (int k = 0; k < 2; ++k) dst[n][k] = *(const PG8_LAS bf16x8*)(lds + PG8_SB(b, h) + boff + n * 2048 + k * 1024); } while (0)
; #define PG8_MMA(ai, bj, At, Bt) do { __builtin_amdgcn_s_setprio(1); _Pragma("unroll") for (int m = 0; m < 4; ++m) _Pragma("unroll") for (int n = 0; n < 2; ++n) _Pragma("unroll") for (int k = 0; k < 2; ++k) \
;         acc[ai][bj][m][n] = __builtin_amdgcn_mfma_f32_16x16x32_bf16(Bt[n][k], At[m][k], acc[ai][bj][m][n], 0, 0, 0); __builtin_amdgcn_s_setprio(0); } while (0)
; #define PG8_WAIT_V(n) asm volatile("s_waitcnt vmcnt(" #n ")" ::: "memory")
; template <class Epi, class Sched, bool ALIGN_EPI>
; __device__ __forceinline__ void gemm_phase(PG8_LAS unsigned char* lds, const Gemm g, const Sched& S, const Epi& E) {
;     ...
;             PG8_LDB(B0, 0, 0); PG8_LDB(B1, 0, 1); PG8_SCHED; PG8_LDA(At, 0, 0); PG8_STAGE(PG8_SA(1, 1), a1 + hstepA, voffA);
;             PG8_WAIT_V(8); PG8_WAIT_L(0); PG8_BAR; PG8_MMA(0, 0, At, B0); PG8_MMA(0, 1, At, B1); PG8_BAR; PG8_SCHED;
;             PG8_LDA(At, 0, 1); PG8_STAGE(PG8_SB(0, 0), b2, voffB); PG8_STAGE(PG8_SB(0, 1), b2 + hstepB, voffB); PG8_STAGE(PG8_SA(0, 0), a2, voffA);
;             PG8_WAIT_V(8); PG8_WAIT_L(0); PG8_BAR; PG8_MMA(1, 0, At, B0); PG8_MMA(1, 1, At, B1); PG8_BAR; PG8_SCHED;
;             PG8_LDB(B0, 1, 0); PG8_LDB(B1, 1, 1); PG8_SCHED; PG8_LDA(At, 1, 0); PG8_STAGE(PG8_SA(0, 1), a2 + hstepA, voffA);
;             PG8_WAIT_V(8); PG8_WAIT_L(0); PG8_BAR; PG8_MMA(0, 0, At, B0); PG8_MMA(0, 1, At, B1); PG8_BAR; PG8_SCHED;
;             PG8_LDA(At, 1, 1); PG8_STAGE(PG8_SB(1, 0), b3, voffB); PG8_STAGE(PG8_SB(1, 1), b3 + hstepB, voffB); PG8_STAGE(PG8_SA(1, 0), a3, voffA);
;             PG8_WAIT_V(8); PG8_WAIT_L(0); PG8_BAR; PG8_MMA(1, 0, At, B0); PG8_MMA(1, 1, At, B1); PG8_BAR; PG8_SCHED;
.Lp8k_B_nobar:
	s_setprio 2
	ds_read_b128 v[190:193], v155 offset:0
	ds_read_b128 v[194:197], v155 offset:1024
	ds_read_b128 v[198:201], v155 offset:2048
	s_add_i32 m0, s2, 0xa000
	s_nop 0
	global_load_lds_dwordx4 v132, s[28:29]
	ds_read_b128 v[202:205], v155 offset:3072
	ds_read_b128 v[206:209], v155 offset:4096
	ds_read_b128 v[210:213], v155 offset:5120
	s_add_u32 s30, s28, 0x20000
	s_addc_u32 s31, s29, 0
	s_add_i32 m0, s2, 0xb000
	s_nop 0
	global_load_lds_dwordx4 v132, s[30:31]
	ds_read_b128 v[214:217], v155 offset:6144
	ds_read_b128 v[218:221], v155 offset:7168
	ds_read_b128 v[156:159], v153 offset:0
	s_add_u32 s30, s28, 0x80000
	s_addc_u32 s31, s29, 0
	s_add_i32 m0, s2, 0xe000
	s_nop 0
	global_load_lds_dwordx4 v132, s[30:31]
	ds_read_b128 v[160:163], v153 offset:1024
	ds_read_b128 v[164:167], v153 offset:2048
	ds_read_b128 v[168:171], v153 offset:3072
	s_add_u32 s30, s28, 0xa0000
	s_addc_u32 s31, s29, 0
	s_add_i32 m0, s2, 0xf000
	s_nop 0
	global_load_lds_dwordx4 v132, s[30:31]
	ds_read_b128 v[174:177], v153 offset:16384
	ds_read_b128 v[178:181], v153 offset:17408
	ds_read_b128 v[182:185], v153 offset:18432
	s_add_u32 s34, s28, 0x80
	s_addc_u32 s35, s29, 0
	s_cmp_eq_u32 s49, 15
	s_cselect_b32 s34, s50, s34
	s_cselect_b32 s35, s51, s35
	s_add_i32 m0, s2, 0x0
	s_nop 0
	global_load_lds_dwordx4 v136, s[34:35]
	ds_read_b128 v[186:189], v153 offset:19456
	ds_read_b128 v[222:225], v155 offset:16384
	ds_read_b128 v[226:229], v155 offset:17408
	s_add_u32 s30, s34, 0x20000
	s_addc_u32 s31, s35, 0
	s_add_i32 m0, s2, 0x1000
	s_nop 0
	global_load_lds_dwordx4 v136, s[30:31]
	ds_read_b128 v[230:233], v155 offset:18432
	ds_read_b128 v[234:237], v155 offset:19456
	ds_read_b128 v[238:241], v155 offset:20480
	s_add_u32 s30, s34, 0x80000
	s_addc_u32 s31, s35, 0
	s_add_i32 m0, s2, 0x4000
	s_nop 0
	global_load_lds_dwordx4 v136, s[30:31]
	ds_read_b128 v[242:245], v155 offset:21504
	ds_read_b128 v[246:249], v155 offset:22528
	ds_read_b128 v[250:253], v155 offset:23552
	s_add_u32 s30, s34, 0xa0000
	s_addc_u32 s31, s35, 0
	s_add_i32 m0, s2, 0x5000
	s_nop 0
	global_load_lds_dwordx4 v136, s[30:31]
	s_add_u32 s28, s28, 0x80
	s_addc_u32 s29, s29, 0
	s_waitcnt vmcnt(8) lgkmcnt(0)
	s_barrier
	s_setprio 1
	v_mfma_f32_16x16x32_bf16 v[126:129], v[156:159], v[190:193], 0
	v_mfma_f32_16x16x32_bf16 v[126:129], v[160:163], v[194:197], v[126:129]
	v_mfma_f32_16x16x32_bf16 v[122:125], v[168:171], v[194:197], 0
	v_mfma_f32_16x16x32_bf16 v[122:125], v[164:167], v[190:193], v[122:125]
	v_mfma_f32_16x16x32_bf16 v[118:121], v[174:177], v[190:193], 0
	v_mfma_f32_16x16x32_bf16 v[118:121], v[178:181], v[194:197], v[118:121]
	v_mfma_f32_16x16x32_bf16 v[114:117], v[186:189], v[194:197], 0
	v_mfma_f32_16x16x32_bf16 v[114:117], v[182:185], v[190:193], v[114:117]
	v_mfma_f32_16x16x32_bf16 v[98:101], v[182:185], v[198:201], 0
	v_mfma_f32_16x16x32_bf16 v[98:101], v[186:189], v[202:205], v[98:101]
	v_mfma_f32_16x16x32_bf16 v[102:105], v[178:181], v[202:205], 0
	v_mfma_f32_16x16x32_bf16 v[102:105], v[174:177], v[198:201], v[102:105]
	v_mfma_f32_16x16x32_bf16 v[106:109], v[164:167], v[198:201], 0
	v_mfma_f32_16x16x32_bf16 v[106:109], v[168:171], v[202:205], v[106:109]
	v_mfma_f32_16x16x32_bf16 v[110:113], v[160:163], v[202:205], 0
	v_mfma_f32_16x16x32_bf16 v[110:113], v[156:159], v[198:201], v[110:113]
	v_mfma_f32_16x16x32_bf16 v[94:97], v[156:159], v[206:209], 0
	v_mfma_f32_16x16x32_bf16 v[94:97], v[160:163], v[210:213], v[94:97]
	v_mfma_f32_16x16x32_bf16 v[90:93], v[168:171], v[210:213], 0
	v_mfma_f32_16x16x32_bf16 v[90:93], v[164:167], v[206:209], v[90:93]
	v_mfma_f32_16x16x32_bf16 v[86:89], v[174:177], v[206:209], 0
	v_mfma_f32_16x16x32_bf16 v[86:89], v[178:181], v[210:213], v[86:89]
	v_mfma_f32_16x16x32_bf16 v[82:85], v[186:189], v[210:213], 0
	v_mfma_f32_16x16x32_bf16 v[82:85], v[182:185], v[206:209], v[82:85]
	v_mfma_f32_16x16x32_bf16 v[66:69], v[182:185], v[214:217], 0
	v_mfma_f32_16x16x32_bf16 v[66:69], v[186:189], v[218:221], v[66:69]
	v_mfma_f32_16x16x32_bf16 v[70:73], v[178:181], v[218:221], 0
	v_mfma_f32_16x16x32_bf16 v[70:73], v[174:177], v[214:217], v[70:73]
	v_mfma_f32_16x16x32_bf16 v[74:77], v[164:167], v[214:217], 0
	v_mfma_f32_16x16x32_bf16 v[74:77], v[168:171], v[218:221], v[74:77]
	v_mfma_f32_16x16x32_bf16 v[78:81], v[160:163], v[218:221], 0
	v_mfma_f32_16x16x32_bf16 v[78:81], v[156:159], v[214:217], v[78:81]
	v_mfma_f32_16x16x32_bf16 v[62:65], v[156:159], v[222:225], 0
	v_mfma_f32_16x16x32_bf16 v[62:65], v[160:163], v[226:229], v[62:65]
	v_mfma_f32_16x16x32_bf16 v[58:61], v[168:171], v[226:229], 0
	v_mfma_f32_16x16x32_bf16 v[58:61], v[164:167], v[222:225], v[58:61]
	v_mfma_f32_16x16x32_bf16 v[54:57], v[174:177], v[222:225], 0
	v_mfma_f32_16x16x32_bf16 v[54:57], v[178:181], v[226:229], v[54:57]
	v_mfma_f32_16x16x32_bf16 v[50:53], v[186:189], v[226:229], 0
	v_mfma_f32_16x16x32_bf16 v[50:53], v[182:185], v[222:225], v[50:53]
	v_mfma_f32_16x16x32_bf16 v[34:37], v[182:185], v[230:233], 0
	v_mfma_f32_16x16x32_bf16 v[34:37], v[186:189], v[234:237], v[34:37]
	v_mfma_f32_16x16x32_bf16 v[38:41], v[178:181], v[234:237], 0
	v_mfma_f32_16x16x32_bf16 v[38:41], v[174:177], v[230:233], v[38:41]
	v_mfma_f32_16x16x32_bf16 v[42:45], v[164:167], v[230:233], 0
	v_mfma_f32_16x16x32_bf16 v[42:45], v[168:171], v[234:237], v[42:45]
	v_mfma_f32_16x16x32_bf16 v[46:49], v[160:163], v[234:237], 0
	v_mfma_f32_16x16x32_bf16 v[46:49], v[156:159], v[230:233], v[46:49]
	v_mfma_f32_16x16x32_bf16 v[30:33], v[156:159], v[238:241], 0
	v_mfma_f32_16x16x32_bf16 v[30:33], v[160:163], v[242:245], v[30:33]
	v_mfma_f32_16x16x32_bf16 v[26:29], v[168:171], v[242:245], 0
	v_mfma_f32_16x16x32_bf16 v[26:29], v[164:167], v[238:241], v[26:29]
	v_mfma_f32_16x16x32_bf16 v[22:25], v[174:177], v[238:241], 0
	v_mfma_f32_16x16x32_bf16 v[22:25], v[178:181], v[242:245], v[22:25]
	v_mfma_f32_16x16x32_bf16 v[18:21], v[186:189], v[242:245], 0
	v_mfma_f32_16x16x32_bf16 v[18:21], v[182:185], v[238:241], v[18:21]
	v_mfma_f32_16x16x32_bf16 v[2:5], v[182:185], v[246:249], 0
	v_mfma_f32_16x16x32_bf16 v[2:5], v[186:189], v[250:253], v[2:5]
	v_mfma_f32_16x16x32_bf16 v[6:9], v[178:181], v[250:253], 0
	v_mfma_f32_16x16x32_bf16 v[6:9], v[174:177], v[246:249], v[6:9]
	v_mfma_f32_16x16x32_bf16 v[10:13], v[164:167], v[246:249], 0
	v_mfma_f32_16x16x32_bf16 v[10:13], v[168:171], v[250:253], v[10:13]
	v_mfma_f32_16x16x32_bf16 v[14:17], v[160:163], v[250:253], 0
	v_mfma_f32_16x16x32_bf16 v[14:17], v[156:159], v[246:249], v[14:17]
	s_setprio 0
	s_waitcnt vmcnt(0)
	s_barrier
; #define PG8_STAGE(bufoff, gbase, voff) do { _Pragma("unroll") for (int _i = 0; _i < 2; ++_i) \
;         __builtin_amdgcn_global_load_lds((const unsigned*)((const char*)(gbase) + (voff)[_i]), (PG8_LAS unsigned*)(lds + (bufoff) + ldsw + _i * 8192), 16, 0, 0); } while (0)
; #define PG8_LDA(dst, b, h) do { _Pragma("unroll") for (int m = 0; m < 4; ++m) _Pragma("unroll") for (int k = 0; k < 2; ++k) dst[m][k] = *(const PG8_LAS bf16x8*)(lds + PG8_SA(b, h) + aoff + m * 2048 + k * 1024); } while (0)
; #define PG8_LDB(dst, b, h) do { _Pragma("unroll") for (int n = 0; n < 2; ++n) _Pragma("unroll") for (int k = 0; k < 2; ++k) dst[n][k] = *(const PG8_LAS bf16x8*)(lds + PG8_SB(b, h) + boff + n * 2048 + k * 1024); } while (0)
; #define PG8_MMA(ai, bj, At, Bt) do { __builtin_amdgcn_s_setprio(1); _Pragma("unroll") for (int m = 0; m < 4; ++m) _Pragma("unroll") for (int n = 0; n < 2; ++n) _Pragma("unroll") for (int k = 0; k < 2; ++k) \
;         acc[ai][bj][m][n] = __builtin_amdgcn_mfma_f32_16x16x32_bf16(Bt[n][k], At[m][k], acc[ai][bj][m][n], 0, 0, 0); __builtin_amdgcn_s_setprio(0); } while (0)
; #define PG8_WAIT_V(n) asm volatile("s_waitcnt vmcnt(" #n ")" ::: "memory")
; template <class Epi, class Sched, bool ALIGN_EPI>
; __device__ __forceinline__ void gemm_phase(PG8_LAS unsigned char* lds, const Gemm g, const Sched& S, const Epi& E) {
;     ...
;             PG8_LDB(B0, 0, 0); PG8_LDB(B1, 0, 1); PG8_SCHED; PG8_LDA(At, 0, 0); PG8_STAGE(PG8_SA(1, 1), a1 + hstepA, voffA);
;             PG8_WAIT_V(8); PG8_WAIT_L(0); PG8_BAR; PG8_MMA(0, 0, At, B0); PG8_MMA(0, 1, At, B1); PG8_BAR; PG8_SCHED;
;             PG8_LDA(At, 0, 1); PG8_STAGE(PG8_SB(0, 0), b2, voffB); PG8_STAGE(PG8_SB(0, 1), b2 + hstepB, voffB); PG8_STAGE(PG8_SA(0, 0), a2, voffA);
;             PG8_WAIT_V(8); PG8_WAIT_L(0); PG8_BAR; PG8_MMA(1, 0, At, B0); PG8_MMA(1, 1, At, B1); PG8_BAR; PG8_SCHED;
;             PG8_LDB(B0, 1, 0); PG8_LDB(B1, 1, 1); PG8_SCHED; PG8_LDA(At, 1, 0); PG8_STAGE(PG8_SA(0, 1), a2 + hstepA, voffA);
;             PG8_WAIT_V(8); PG8_WAIT_L(0); PG8_BAR; PG8_MMA(0, 0, At, B0); PG8_MMA(0, 1, At, B1); PG8_BAR; PG8_SCHED;
;             PG8_LDA(At, 1, 1); PG8_STAGE(PG8_SB(1, 0), b3, voffB); PG8_STAGE(PG8_SB(1, 1), b3 + hstepB, voffB); PG8_STAGE(PG8_SA(1, 0), a3, voffA);
;             PG8_WAIT_V(8); PG8_WAIT_L(0); PG8_BAR; PG8_MMA(1, 0, At, B0); PG8_MMA(1, 1, At, B1); PG8_BAR; PG8_SCHED;
	s_setprio 2
	ds_read_b128 v[190:193], v155 offset:32768
	ds_read_b128 v[194:197], v155 offset:33792
	ds_read_b128 v[198:201], v155 offset:34816
	s_cmp_eq_u32 s49, 15
	s_cselect_b32 s28, s50, s28
	s_cselect_b32 s29, s51, s29
	s_add_i32 m0, s2, 0x2000
	s_nop 0
	global_load_lds_dwordx4 v132, s[28:29]
	ds_read_b128 v[202:205], v155 offset:35840
	ds_read_b128 v[206:209], v155 offset:36864
	ds_read_b128 v[210:213], v155 offset:37888
	s_add_u32 s30, s28, 0x20000
	s_addc_u32 s31, s29, 0
	s_add_i32 m0, s2, 0x3000
	s_nop 0
	global_load_lds_dwordx4 v132, s[30:31]
	ds_read_b128 v[214:217], v155 offset:38912
	ds_read_b128 v[218:221], v155 offset:39936
	ds_read_b128 v[156:159], v153 offset:32768
	s_add_u32 s30, s28, 0x80000
	s_addc_u32 s31, s29, 0
	s_add_i32 m0, s2, 0x6000
	s_nop 0
	global_load_lds_dwordx4 v132, s[30:31]
	ds_read_b128 v[160:163], v153 offset:33792
	ds_read_b128 v[164:167], v153 offset:34816
	ds_read_b128 v[168:171], v153 offset:35840
	s_add_u32 s30, s28, 0xa0000
	s_addc_u32 s31, s29, 0
	s_add_i32 m0, s2, 0x7000
	s_nop 0
	global_load_lds_dwordx4 v132, s[30:31]
	ds_read_b128 v[174:177], v153 offset:49152
	ds_read_b128 v[178:181], v153 offset:50176
	ds_read_b128 v[182:185], v153 offset:51200
	s_add_u32 s34, s28, 0x80
	s_addc_u32 s35, s29, 0
	s_add_i32 m0, s2, 0x8000
	s_nop 0
	global_load_lds_dwordx4 v136, s[34:35]
	ds_read_b128 v[186:189], v153 offset:52224
	ds_read_b128 v[222:225], v155 offset:49152
	ds_read_b128 v[226:229], v155 offset:50176
	s_add_u32 s30, s34, 0x20000
	s_addc_u32 s31, s35, 0
	s_add_i32 m0, s2, 0x9000
	s_nop 0
	global_load_lds_dwordx4 v136, s[30:31]
	ds_read_b128 v[230:233], v155 offset:51200
	ds_read_b128 v[234:237], v155 offset:52224
	ds_read_b128 v[238:241], v155 offset:53248
	s_add_u32 s30, s34, 0x80000
	s_addc_u32 s31, s35, 0
	s_add_i32 m0, s2, 0xc000
	s_nop 0
	global_load_lds_dwordx4 v136, s[30:31]
	ds_read_b128 v[242:245], v155 offset:54272
	ds_read_b128 v[246:249], v155 offset:55296
	ds_read_b128 v[250:253], v155 offset:56320
	s_add_u32 s30, s34, 0xa0000
	s_addc_u32 s31, s35, 0
	s_add_i32 m0, s2, 0xd000
	s_nop 0
	global_load_lds_dwordx4 v136, s[30:31]
	s_add_u32 s28, s28, 0x80
	s_addc_u32 s29, s29, 0
	s_waitcnt vmcnt(8) lgkmcnt(0)
	s_barrier
	s_setprio 1
	v_mfma_f32_16x16x32_bf16 v[126:129], v[156:159], v[190:193], v[126:129]
	v_mfma_f32_16x16x32_bf16 v[126:129], v[160:163], v[194:197], v[126:129]
	v_mfma_f32_16x16x32_bf16 v[122:125], v[168:171], v[194:197], v[122:125]
	v_mfma_f32_16x16x32_bf16 v[122:125], v[164:167], v[190:193], v[122:125]
	v_mfma_f32_16x16x32_bf16 v[118:121], v[174:177], v[190:193], v[118:121]
	v_mfma_f32_16x16x32_bf16 v[118:121], v[178:181], v[194:197], v[118:121]
	v_mfma_f32_16x16x32_bf16 v[114:117], v[186:189], v[194:197], v[114:117]
	v_mfma_f32_16x16x32_bf16 v[114:117], v[182:185], v[190:193], v[114:117]
	v_mfma_f32_16x16x32_bf16 v[98:101], v[182:185], v[198:201], v[98:101]
	v_mfma_f32_16x16x32_bf16 v[98:101], v[186:189], v[202:205], v[98:101]
	v_mfma_f32_16x16x32_bf16 v[102:105], v[178:181], v[202:205], v[102:105]
	v_mfma_f32_16x16x32_bf16 v[102:105], v[174:177], v[198:201], v[102:105]
	v_mfma_f32_16x16x32_bf16 v[106:109], v[164:167], v[198:201], v[106:109]
	v_mfma_f32_16x16x32_bf16 v[106:109], v[168:171], v[202:205], v[106:109]
	v_mfma_f32_16x16x32_bf16 v[110:113], v[160:163], v[202:205], v[110:113]
	v_mfma_f32_16x16x32_bf16 v[110:113], v[156:159], v[198:201], v[110:113]
	v_mfma_f32_16x16x32_bf16 v[94:97], v[156:159], v[206:209], v[94:97]
	v_mfma_f32_16x16x32_bf16 v[94:97], v[160:163], v[210:213], v[94:97]
	v_mfma_f32_16x16x32_bf16 v[90:93], v[168:171], v[210:213], v[90:93]
	v_mfma_f32_16x16x32_bf16 v[90:93], v[164:167], v[206:209], v[90:93]
	v_mfma_f32_16x16x32_bf16 v[86:89], v[174:177], v[206:209], v[86:89]
	v_mfma_f32_16x16x32_bf16 v[86:89], v[178:181], v[210:213], v[86:89]
	v_mfma_f32_16x16x32_bf16 v[82:85], v[186:189], v[210:213], v[82:85]
	v_mfma_f32_16x16x32_bf16 v[82:85], v[182:185], v[206:209], v[82:85]
	v_mfma_f32_16x16x32_bf16 v[66:69], v[182:185], v[214:217], v[66:69]
	v_mfma_f32_16x16x32_bf16 v[66:69], v[186:189], v[218:221], v[66:69]
	v_mfma_f32_16x16x32_bf16 v[70:73], v[178:181], v[218:221], v[70:73]
	v_mfma_f32_16x16x32_bf16 v[70:73], v[174:177], v[214:217], v[70:73]
	v_mfma_f32_16x16x32_bf16 v[74:77], v[164:167], v[214:217], v[74:77]
	v_mfma_f32_16x16x32_bf16 v[74:77], v[168:171], v[218:221], v[74:77]
	v_mfma_f32_16x16x32_bf16 v[78:81], v[160:163], v[218:221], v[78:81]
	v_mfma_f32_16x16x32_bf16 v[78:81], v[156:159], v[214:217], v[78:81]
	v_mfma_f32_16x16x32_bf16 v[62:65], v[156:159], v[222:225], v[62:65]
	v_mfma_f32_16x16x32_bf16 v[62:65], v[160:163], v[226:229], v[62:65]
	v_mfma_f32_16x16x32_bf16 v[58:61], v[168:171], v[226:229], v[58:61]
	v_mfma_f32_16x16x32_bf16 v[58:61], v[164:167], v[222:225], v[58:61]
	v_mfma_f32_16x16x32_bf16 v[54:57], v[174:177], v[222:225], v[54:57]
	v_mfma_f32_16x16x32_bf16 v[54:57], v[178:181], v[226:229], v[54:57]
	v_mfma_f32_16x16x32_bf16 v[50:53], v[186:189], v[226:229], v[50:53]
	v_mfma_f32_16x16x32_bf16 v[50:53], v[182:185], v[222:225], v[50:53]
	v_mfma_f32_16x16x32_bf16 v[34:37], v[182:185], v[230:233], v[34:37]
	v_mfma_f32_16x16x32_bf16 v[34:37], v[186:189], v[234:237], v[34:37]
	v_mfma_f32_16x16x32_bf16 v[38:41], v[178:181], v[234:237], v[38:41]
	v_mfma_f32_16x16x32_bf16 v[38:41], v[174:177], v[230:233], v[38:41]
	v_mfma_f32_16x16x32_bf16 v[42:45], v[164:167], v[230:233], v[42:45]
	v_mfma_f32_16x16x32_bf16 v[42:45], v[168:171], v[234:237], v[42:45]
	v_mfma_f32_16x16x32_bf16 v[46:49], v[160:163], v[234:237], v[46:49]
	v_mfma_f32_16x16x32_bf16 v[46:49], v[156:159], v[230:233], v[46:49]
	v_mfma_f32_16x16x32_bf16 v[30:33], v[156:159], v[238:241], v[30:33]
	v_mfma_f32_16x16x32_bf16 v[30:33], v[160:163], v[242:245], v[30:33]
	v_mfma_f32_16x16x32_bf16 v[26:29], v[168:171], v[242:245], v[26:29]
	v_mfma_f32_16x16x32_bf16 v[26:29], v[164:167], v[238:241], v[26:29]
	v_mfma_f32_16x16x32_bf16 v[22:25], v[174:177], v[238:241], v[22:25]
	v_mfma_f32_16x16x32_bf16 v[22:25], v[178:181], v[242:245], v[22:25]
	v_mfma_f32_16x16x32_bf16 v[18:21], v[186:189], v[242:245], v[18:21]
	v_mfma_f32_16x16x32_bf16 v[18:21], v[182:185], v[238:241], v[18:21]
	v_mfma_f32_16x16x32_bf16 v[2:5], v[182:185], v[246:249], v[2:5]
	v_mfma_f32_16x16x32_bf16 v[2:5], v[186:189], v[250:253], v[2:5]
	v_mfma_f32_16x16x32_bf16 v[6:9], v[178:181], v[250:253], v[6:9]
	v_mfma_f32_16x16x32_bf16 v[6:9], v[174:177], v[246:249], v[6:9]
	v_mfma_f32_16x16x32_bf16 v[10:13], v[164:167], v[246:249], v[10:13]
	v_mfma_f32_16x16x32_bf16 v[10:13], v[168:171], v[250:253], v[10:13]
	v_mfma_f32_16x16x32_bf16 v[14:17], v[160:163], v[250:253], v[14:17]
	v_mfma_f32_16x16x32_bf16 v[14:17], v[156:159], v[246:249], v[14:17]
	s_setprio 0
	s_waitcnt vmcnt(0)
	s_barrier
	s_add_i32 s49, s49, 1
; #define PG8_STAGE(bufoff, gbase, voff) do { _Pragma("unroll") for (int _i = 0; _i < 2; ++_i) \
;         __builtin_amdgcn_global_load_lds((const unsigned*)((const char*)(gbase) + (voff)[_i]), (PG8_LAS unsigned*)(lds + (bufoff) + ldsw + _i * 8192), 16, 0, 0); } while (0)
; #define PG8_LDA(dst, b, h) do { _Pragma("unroll") for (int m = 0; m < 4; ++m) _Pragma("unroll") for (int k = 0; k < 2; ++k) dst[m][k] = *(const PG8_LAS bf16x8*)(lds + PG8_SA(b, h) + aoff + m * 2048 + k * 1024); } while (0)
; #define PG8_LDB(dst, b, h) do { _Pragma("unroll") for (int n = 0; n < 2; ++n) _Pragma("unroll") for (int k = 0; k < 2; ++k) dst[n][k] = *(const PG8_LAS bf16x8*)(lds + PG8_SB(b, h) + boff + n * 2048 + k * 1024); } while (0)
; #define PG8_MMA(ai, bj, At, Bt) do { __builtin_amdgcn_s_setprio(1); _Pragma("unroll") for (int m = 0; m < 4; ++m) _Pragma("unroll") for (int n = 0; n < 2; ++n) _Pragma("unroll") for (int k = 0; k < 2; ++k) \
;         acc[ai][bj][m][n] = __builtin_amdgcn_mfma_f32_16x16x32_bf16(Bt[n][k], At[m][k], acc[ai][bj][m][n], 0, 0, 0); __builtin_amdgcn_s_setprio(0); } while (0)
; #define PG8_WAIT_V(n) asm volatile("s_waitcnt vmcnt(" #n ")" ::: "memory")
; template <class Epi, class Sched, bool ALIGN_EPI>
; __device__ __forceinline__ void gemm_phase(PG8_LAS unsigned char* lds, const Gemm g, const Sched& S, const Epi& E) {
;     ...
;             PG8_LDB(B0, 0, 0); PG8_LDB(B1, 0, 1); PG8_SCHED; PG8_LDA(At, 0, 0); PG8_STAGE(PG8_SA(1, 1), a1 + hstepA, voffA);
;             PG8_WAIT_V(8); PG8_WAIT_L(0); PG8_BAR; PG8_MMA(0, 0, At, B0); PG8_MMA(0, 1, At, B1); PG8_BAR; PG8_SCHED;
;             PG8_LDA(At, 0, 1); PG8_STAGE(PG8_SB(0, 0), b2, voffB); PG8_STAGE(PG8_SB(0, 1), b2 + hstepB, voffB); PG8_STAGE(PG8_SA(0, 0), a2, voffA);
;             PG8_WAIT_V(8); PG8_WAIT_L(0); PG8_BAR; PG8_MMA(1, 0, At, B0); PG8_MMA(1, 1, At, B1); PG8_BAR; PG8_SCHED;
;             PG8_LDB(B0, 1, 0); PG8_LDB(B1, 1, 1); PG8_SCHED; PG8_LDA(At, 1, 0); PG8_STAGE(PG8_SA(0, 1), a2 + hstepA, voffA);
;             PG8_WAIT_V(8); PG8_WAIT_L(0); PG8_BAR; PG8_MMA(0, 0, At, B0); PG8_MMA(0, 1, At, B1); PG8_BAR; PG8_SCHED;
;             PG8_LDA(At, 1, 1); PG8_STAGE(PG8_SB(1, 0), b3, voffB); PG8_STAGE(PG8_SB(1, 1), b3 + hstepB, voffB); PG8_STAGE(PG8_SA(1, 0), a3, voffA);
;             PG8_WAIT_V(8); PG8_WAIT_L(0); PG8_BAR; PG8_MMA(1, 0, At, B0); PG8_MMA(1, 1, At, B1); PG8_BAR; PG8_SCHED;
.Lp8k_B_loop:
	s_setprio 2
	ds_read_b128 v[190:193], v155 offset:0
	ds_read_b128 v[194:197], v155 offset:1024
	ds_read_b128 v[198:201], v155 offset:2048
	s_add_i32 m0, s2, 0xa000
	s_nop 0
	global_load_lds_dwordx4 v132, s[28:29]
	ds_read_b128 v[202:205], v155 offset:3072
	ds_read_b128 v[206:209], v155 offset:4096
	ds_read_b128 v[210:213], v155 offset:5120
	s_add_u32 s30, s28, 0x20000
	s_addc_u32 s31, s29, 0
	s_add_i32 m0, s2, 0xb000
	s_nop 0
	global_load_lds_dwordx4 v132, s[30:31]
	ds_read_b128 v[214:217], v155 offset:6144
	ds_read_b128 v[218:221], v155 offset:7168
	ds_read_b128 v[156:159], v153 offset:0
	s_add_u32 s30, s28, 0x80000
	s_addc_u32 s31, s29, 0
	s_add_i32 m0, s2, 0xe000
	s_nop 0
	global_load_lds_dwordx4 v132, s[30:31]
	ds_read_b128 v[160:163], v153 offset:1024
	ds_read_b128 v[164:167], v153 offset:2048
	ds_read_b128 v[168:171], v153 offset:3072
	s_add_u32 s30, s28, 0xa0000
	s_addc_u32 s31, s29, 0
	s_add_i32 m0, s2, 0xf000
	s_nop 0
	global_load_lds_dwordx4 v132, s[30:31]
	ds_read_b128 v[174:177], v153 offset:16384
	ds_read_b128 v[178:181], v153 offset:17408
	ds_read_b128 v[182:185], v153 offset:18432
	s_add_u32 s34, s28, 0x80
	s_addc_u32 s35, s29, 0
	s_cmp_eq_u32 s49, 15
	s_cselect_b32 s34, s50, s34
	s_cselect_b32 s35, s51, s35
	s_add_i32 m0, s2, 0x0
	s_nop 0
	global_load_lds_dwordx4 v136, s[34:35]
	ds_read_b128 v[186:189], v153 offset:19456
	ds_read_b128 v[222:225], v155 offset:16384
	ds_read_b128 v[226:229], v155 offset:17408
	s_add_u32 s30, s34, 0x20000
	s_addc_u32 s31, s35, 0
	s_add_i32 m0, s2, 0x1000
	s_nop 0
	global_load_lds_dwordx4 v136, s[30:31]
	ds_read_b128 v[230:233], v155 offset:18432
	ds_read_b128 v[234:237], v155 offset:19456
	ds_read_b128 v[238:241], v155 offset:20480
	s_add_u32 s30, s34, 0x80000
	s_addc_u32 s31, s35, 0
	s_add_i32 m0, s2, 0x4000
	s_nop 0
	global_load_lds_dwordx4 v136, s[30:31]
	ds_read_b128 v[242:245], v155 offset:21504
	ds_read_b128 v[246:249], v155 offset:22528
	ds_read_b128 v[250:253], v155 offset:23552
	s_add_u32 s30, s34, 0xa0000
	s_addc_u32 s31, s35, 0
	s_add_i32 m0, s2, 0x5000
	s_nop 0
	global_load_lds_dwordx4 v136, s[30:31]
	s_add_u32 s28, s28, 0x80
	s_addc_u32 s29, s29, 0
	s_waitcnt vmcnt(8) lgkmcnt(0)
	s_barrier
	s_setprio 1
	v_mfma_f32_16x16x32_bf16 v[126:129], v[156:159], v[190:193], v[126:129]
	v_mfma_f32_16x16x32_bf16 v[126:129], v[160:163], v[194:197], v[126:129]
	v_mfma_f32_16x16x32_bf16 v[122:125], v[168:171], v[194:197], v[122:125]
	v_mfma_f32_16x16x32_bf16 v[122:125], v[164:167], v[190:193], v[122:125]
	v_mfma_f32_16x16x32_bf16 v[118:121], v[174:177], v[190:193], v[118:121]
	v_mfma_f32_16x16x32_bf16 v[118:121], v[178:181], v[194:197], v[118:121]
	v_mfma_f32_16x16x32_bf16 v[114:117], v[186:189], v[194:197], v[114:117]
	v_mfma_f32_16x16x32_bf16 v[114:117], v[182:185], v[190:193], v[114:117]
	v_mfma_f32_16x16x32_bf16 v[98:101], v[182:185], v[198:201], v[98:101]
	v_mfma_f32_16x16x32_bf16 v[98:101], v[186:189], v[202:205], v[98:101]
	v_mfma_f32_16x16x32_bf16 v[102:105], v[178:181], v[202:205], v[102:105]
	v_mfma_f32_16x16x32_bf16 v[102:105], v[174:177], v[198:201], v[102:105]
	v_mfma_f32_16x16x32_bf16 v[106:109], v[164:167], v[198:201], v[106:109]
	v_mfma_f32_16x16x32_bf16 v[106:109], v[168:171], v[202:205], v[106:109]
	v_mfma_f32_16x16x32_bf16 v[110:113], v[160:163], v[202:205], v[110:113]
	v_mfma_f32_16x16x32_bf16 v[110:113], v[156:159], v[198:201], v[110:113]
	v_mfma_f32_16x16x32_bf16 v[94:97], v[156:159], v[206:209], v[94:97]
	v_mfma_f32_16x16x32_bf16 v[94:97], v[160:163], v[210:213], v[94:97]
	v_mfma_f32_16x16x32_bf16 v[90:93], v[168:171], v[210:213], v[90:93]
	v_mfma_f32_16x16x32_bf16 v[90:93], v[164:167], v[206:209], v[90:93]
	v_mfma_f32_16x16x32_bf16 v[86:89], v[174:177], v[206:209], v[86:89]
	v_mfma_f32_16x16x32_bf16 v[86:89], v[178:181], v[210:213], v[86:89]
	v_mfma_f32_16x16x32_bf16 v[82:85], v[186:189], v[210:213], v[82:85]
	v_mfma_f32_16x16x32_bf16 v[82:85], v[182:185], v[206:209], v[82:85]
	v_mfma_f32_16x16x32_bf16 v[66:69], v[182:185], v[214:217], v[66:69]
	v_mfma_f32_16x16x32_bf16 v[66:69], v[186:189], v[218:221], v[66:69]
	v_mfma_f32_16x16x32_bf16 v[70:73], v[178:181], v[218:221], v[70:73]
	v_mfma_f32_16x16x32_bf16 v[70:73], v[174:177], v[214:217], v[70:73]
	v_mfma_f32_16x16x32_bf16 v[74:77], v[164:167], v[214:217], v[74:77]
	v_mfma_f32_16x16x32_bf16 v[74:77], v[168:171], v[218:221], v[74:77]
	v_mfma_f32_16x16x32_bf16 v[78:81], v[160:163], v[218:221], v[78:81]
	v_mfma_f32_16x16x32_bf16 v[78:81], v[156:159], v[214:217], v[78:81]
	v_mfma_f32_16x16x32_bf16 v[62:65], v[156:159], v[222:225], v[62:65]
	v_mfma_f32_16x16x32_bf16 v[62:65], v[160:163], v[226:229], v[62:65]
	v_mfma_f32_16x16x32_bf16 v[58:61], v[168:171], v[226:229], v[58:61]
	v_mfma_f32_16x16x32_bf16 v[58:61], v[164:167], v[222:225], v[58:61]
	v_mfma_f32_16x16x32_bf16 v[54:57], v[174:177], v[222:225], v[54:57]
	v_mfma_f32_16x16x32_bf16 v[54:57], v[178:181], v[226:229], v[54:57]
	v_mfma_f32_16x16x32_bf16 v[50:53], v[186:189], v[226:229], v[50:53]
	v_mfma_f32_16x16x32_bf16 v[50:53], v[182:185], v[222:225], v[50:53]
	v_mfma_f32_16x16x32_bf16 v[34:37], v[182:185], v[230:233], v[34:37]
	v_mfma_f32_16x16x32_bf16 v[34:37], v[186:189], v[234:237], v[34:37]
	v_mfma_f32_16x16x32_bf16 v[38:41], v[178:181], v[234:237], v[38:41]
	v_mfma_f32_16x16x32_bf16 v[38:41], v[174:177], v[230:233], v[38:41]
	v_mfma_f32_16x16x32_bf16 v[42:45], v[164:167], v[230:233], v[42:45]
	v_mfma_f32_16x16x32_bf16 v[42:45], v[168:171], v[234:237], v[42:45]
	v_mfma_f32_16x16x32_bf16 v[46:49], v[160:163], v[234:237], v[46:49]
	v_mfma_f32_16x16x32_bf16 v[46:49], v[156:159], v[230:233], v[46:49]
	v_mfma_f32_16x16x32_bf16 v[30:33], v[156:159], v[238:241], v[30:33]
	v_mfma_f32_16x16x32_bf16 v[30:33], v[160:163], v[242:245], v[30:33]
	v_mfma_f32_16x16x32_bf16 v[26:29], v[168:171], v[242:245], v[26:29]
	v_mfma_f32_16x16x32_bf16 v[26:29], v[164:167], v[238:241], v[26:29]
	v_mfma_f32_16x16x32_bf16 v[22:25], v[174:177], v[238:241], v[22:25]
	v_mfma_f32_16x16x32_bf16 v[22:25], v[178:181], v[242:245], v[22:25]
	v_mfma_f32_16x16x32_bf16 v[18:21], v[186:189], v[242:245], v[18:21]
	v_mfma_f32_16x16x32_bf16 v[18:21], v[182:185], v[238:241], v[18:21]
	v_mfma_f32_16x16x32_bf16 v[2:5], v[182:185], v[246:249], v[2:5]
	v_mfma_f32_16x16x32_bf16 v[2:5], v[186:189], v[250:253], v[2:5]
	v_mfma_f32_16x16x32_bf16 v[6:9], v[178:181], v[250:253], v[6:9]
	v_mfma_f32_16x16x32_bf16 v[6:9], v[174:177], v[246:249], v[6:9]
	v_mfma_f32_16x16x32_bf16 v[10:13], v[164:167], v[246:249], v[10:13]
	v_mfma_f32_16x16x32_bf16 v[10:13], v[168:171], v[250:253], v[10:13]
	v_mfma_f32_16x16x32_bf16 v[14:17], v[160:163], v[250:253], v[14:17]
	v_mfma_f32_16x16x32_bf16 v[14:17], v[156:159], v[246:249], v[14:17]
	s_setprio 0
	s_waitcnt vmcnt(0)
	s_barrier
; #define PG8_STAGE(bufoff, gbase, voff) do { _Pragma("unroll") for (int _i = 0; _i < 2; ++_i) \
;         __builtin_amdgcn_global_load_lds((const unsigned*)((const char*)(gbase) + (voff)[_i]), (PG8_LAS unsigned*)(lds + (bufoff) + ldsw + _i * 8192), 16, 0, 0); } while (0)
; #define PG8_LDA(dst, b, h) do { _Pragma("unroll") for (int m = 0; m < 4; ++m) _Pragma("unroll") for (int k = 0; k < 2; ++k) dst[m][k] = *(const PG8_LAS bf16x8*)(lds + PG8_SA(b, h) + aoff + m * 2048 + k * 1024); } while (0)
; #define PG8_LDB(dst, b, h) do { _Pragma("unroll") for (int n = 0; n < 2; ++n) _Pragma("unroll") for (int k = 0; k < 2; ++k) dst[n][k] = *(const PG8_LAS bf16x8*)(lds + PG8_SB(b, h) + boff + n * 2048 + k * 1024); } while (0)
; #define PG8_MMA(ai, bj, At, Bt) do { __builtin_amdgcn_s_setprio(1); _Pragma("unroll") for (int m = 0; m < 4; ++m) _Pragma("unroll") for (int n = 0; n < 2; ++n) _Pragma("unroll") for (int k = 0; k < 2; ++k) \
;         acc[ai][bj][m][n] = __builtin_amdgcn_mfma_f32_16x16x32_bf16(Bt[n][k], At[m][k], acc[ai][bj][m][n], 0, 0, 0); __builtin_amdgcn_s_setprio(0); } while (0)
; #define PG8_WAIT_V(n) asm volatile("s_waitcnt vmcnt(" #n ")" ::: "memory")
; template <class Epi, class Sched, bool ALIGN_EPI>
; __device__ __forceinline__ void gemm_phase(PG8_LAS unsigned char* lds, const Gemm g, const Sched& S, const Epi& E) {
;     ...
;             PG8_LDB(B0, 0, 0); PG8_LDB(B1, 0, 1); PG8_SCHED; PG8_LDA(At, 0, 0); PG8_STAGE(PG8_SA(1, 1), a1 + hstepA, voffA);
;             PG8_WAIT_V(8); PG8_WAIT_L(0); PG8_BAR; PG8_MMA(0, 0, At, B0); PG8_MMA(0, 1, At, B1); PG8_BAR; PG8_SCHED;
;             PG8_LDA(At, 0, 1); PG8_STAGE(PG8_SB(0, 0), b2, voffB); PG8_STAGE(PG8_SB(0, 1), b2 + hstepB, voffB); PG8_STAGE(PG8_SA(0, 0), a2, voffA);
;             PG8_WAIT_V(8); PG8_WAIT_L(0); PG8_BAR; PG8_MMA(1, 0, At, B0); PG8_MMA(1, 1, At, B1); PG8_BAR; PG8_SCHED;
;             PG8_LDB(B0, 1, 0); PG8_LDB(B1, 1, 1); PG8_SCHED; PG8_LDA(At, 1, 0); PG8_STAGE(PG8_SA(0, 1), a2 + hstepA, voffA);
;             PG8_WAIT_V(8); PG8_WAIT_L(0); PG8_BAR; PG8_MMA(0, 0, At, B0); PG8_MMA(0, 1, At, B1); PG8_BAR; PG8_SCHED;
;             PG8_LDA(At, 1, 1); PG8_STAGE(PG8_SB(1, 0), b3, voffB); PG8_STAGE(PG8_SB(1, 1), b3 + hstepB, voffB); PG8_STAGE(PG8_SA(1, 0), a3, voffA);
;             PG8_WAIT_V(8); PG8_WAIT_L(0); PG8_BAR; PG8_MMA(1, 0, At, B0); PG8_MMA(1, 1, At, B1); PG8_BAR; PG8_SCHED;
	s_setprio 2
	ds_read_b128 v[190:193], v155 offset:32768
	ds_read_b128 v[194:197], v155 offset:33792
	ds_read_b128 v[198:201], v155 offset:34816
	s_cmp_eq_u32 s49, 15
	s_cselect_b32 s28, s50, s28
	s_cselect_b32 s29, s51, s29
	s_add_i32 m0, s2, 0x2000
	s_nop 0
	global_load_lds_dwordx4 v132, s[28:29]
	ds_read_b128 v[202:205], v155 offset:35840
	ds_read_b128 v[206:209], v155 offset:36864
	ds_read_b128 v[210:213], v155 offset:37888
	s_add_u32 s30, s28, 0x20000
	s_addc_u32 s31, s29, 0
	s_add_i32 m0, s2, 0x3000
	s_nop 0
	global_load_lds_dwordx4 v132, s[30:31]
	ds_read_b128 v[214:217], v155 offset:38912
	ds_read_b128 v[218:221], v155 offset:39936
	ds_read_b128 v[156:159], v153 offset:32768
	s_add_u32 s30, s28, 0x80000
	s_addc_u32 s31, s29, 0
	s_add_i32 m0, s2, 0x6000
	s_nop 0
	global_load_lds_dwordx4 v132, s[30:31]
	ds_read_b128 v[160:163], v153 offset:33792
	ds_read_b128 v[164:167], v153 offset:34816
	ds_read_b128 v[168:171], v153 offset:35840
	s_add_u32 s30, s28, 0xa0000
	s_addc_u32 s31, s29, 0
	s_add_i32 m0, s2, 0x7000
	s_nop 0
	global_load_lds_dwordx4 v132, s[30:31]
	ds_read_b128 v[174:177], v153 offset:49152
	ds_read_b128 v[178:181], v153 offset:50176
	ds_read_b128 v[182:185], v153 offset:51200
	s_add_u32 s34, s28, 0x80
	s_addc_u32 s35, s29, 0
	s_add_i32 m0, s2, 0x8000
	s_nop 0
	global_load_lds_dwordx4 v136, s[34:35]
	ds_read_b128 v[186:189], v153 offset:52224
	ds_read_b128 v[222:225], v155 offset:49152
	ds_read_b128 v[226:229], v155 offset:50176
	s_add_u32 s30, s34, 0x20000
	s_addc_u32 s31, s35, 0
	s_add_i32 m0, s2, 0x9000
	s_nop 0
	global_load_lds_dwordx4 v136, s[30:31]
	ds_read_b128 v[230:233], v155 offset:51200
	ds_read_b128 v[234:237], v155 offset:52224
	ds_read_b128 v[238:241], v155 offset:53248
	s_add_u32 s30, s34, 0x80000
	s_addc_u32 s31, s35, 0
	s_add_i32 m0, s2, 0xc000
	s_nop 0
	global_load_lds_dwordx4 v136, s[30:31]
	ds_read_b128 v[242:245], v155 offset:54272
	ds_read_b128 v[246:249], v155 offset:55296
	ds_read_b128 v[250:253], v155 offset:56320
	s_add_u32 s30, s34, 0xa0000
	s_addc_u32 s31, s35, 0
	s_add_i32 m0, s2, 0xd000
	s_nop 0
	global_load_lds_dwordx4 v136, s[30:31]
	s_add_u32 s28, s28, 0x80
	s_addc_u32 s29, s29, 0
	s_waitcnt vmcnt(8) lgkmcnt(0)
	s_barrier
	s_setprio 1
	v_mfma_f32_16x16x32_bf16 v[126:129], v[156:159], v[190:193], v[126:129]
	v_mfma_f32_16x16x32_bf16 v[126:129], v[160:163], v[194:197], v[126:129]
	v_mfma_f32_16x16x32_bf16 v[122:125], v[168:171], v[194:197], v[122:125]
	v_mfma_f32_16x16x32_bf16 v[122:125], v[164:167], v[190:193], v[122:125]
	v_mfma_f32_16x16x32_bf16 v[118:121], v[174:177], v[190:193], v[118:121]
	v_mfma_f32_16x16x32_bf16 v[118:121], v[178:181], v[194:197], v[118:121]
	v_mfma_f32_16x16x32_bf16 v[114:117], v[186:189], v[194:197], v[114:117]
	v_mfma_f32_16x16x32_bf16 v[114:117], v[182:185], v[190:193], v[114:117]
	v_mfma_f32_16x16x32_bf16 v[98:101], v[182:185], v[198:201], v[98:101]
	v_mfma_f32_16x16x32_bf16 v[98:101], v[186:189], v[202:205], v[98:101]
	v_mfma_f32_16x16x32_bf16 v[102:105], v[178:181], v[202:205], v[102:105]
	v_mfma_f32_16x16x32_bf16 v[102:105], v[174:177], v[198:201], v[102:105]
	v_mfma_f32_16x16x32_bf16 v[106:109], v[164:167], v[198:201], v[106:109]
	v_mfma_f32_16x16x32_bf16 v[106:109], v[168:171], v[202:205], v[106:109]
	v_mfma_f32_16x16x32_bf16 v[110:113], v[160:163], v[202:205], v[110:113]
	v_mfma_f32_16x16x32_bf16 v[110:113], v[156:159], v[198:201], v[110:113]
	v_mfma_f32_16x16x32_bf16 v[94:97], v[156:159], v[206:209], v[94:97]
	v_mfma_f32_16x16x32_bf16 v[94:97], v[160:163], v[210:213], v[94:97]
	v_mfma_f32_16x16x32_bf16 v[90:93], v[168:171], v[210:213], v[90:93]
	v_mfma_f32_16x16x32_bf16 v[90:93], v[164:167], v[206:209], v[90:93]
	v_mfma_f32_16x16x32_bf16 v[86:89], v[174:177], v[206:209], v[86:89]
	v_mfma_f32_16x16x32_bf16 v[86:89], v[178:181], v[210:213], v[86:89]
	v_mfma_f32_16x16x32_bf16 v[82:85], v[186:189], v[210:213], v[82:85]
	v_mfma_f32_16x16x32_bf16 v[82:85], v[182:185], v[206:209], v[82:85]
	v_mfma_f32_16x16x32_bf16 v[66:69], v[182:185], v[214:217], v[66:69]
	v_mfma_f32_16x16x32_bf16 v[66:69], v[186:189], v[218:221], v[66:69]
	v_mfma_f32_16x16x32_bf16 v[70:73], v[178:181], v[218:221], v[70:73]
	v_mfma_f32_16x16x32_bf16 v[70:73], v[174:177], v[214:217], v[70:73]
	v_mfma_f32_16x16x32_bf16 v[74:77], v[164:167], v[214:217], v[74:77]
	v_mfma_f32_16x16x32_bf16 v[74:77], v[168:171], v[218:221], v[74:77]
	v_mfma_f32_16x16x32_bf16 v[78:81], v[160:163], v[218:221], v[78:81]
	v_mfma_f32_16x16x32_bf16 v[78:81], v[156:159], v[214:217], v[78:81]
	v_mfma_f32_16x16x32_bf16 v[62:65], v[156:159], v[222:225], v[62:65]
	v_mfma_f32_16x16x32_bf16 v[62:65], v[160:163], v[226:229], v[62:65]
	v_mfma_f32_16x16x32_bf16 v[58:61], v[168:171], v[226:229], v[58:61]
	v_mfma_f32_16x16x32_bf16 v[58:61], v[164:167], v[222:225], v[58:61]
	v_mfma_f32_16x16x32_bf16 v[54:57], v[174:177], v[222:225], v[54:57]
	v_mfma_f32_16x16x32_bf16 v[54:57], v[178:181], v[226:229], v[54:57]
	v_mfma_f32_16x16x32_bf16 v[50:53], v[186:189], v[226:229], v[50:53]
	v_mfma_f32_16x16x32_bf16 v[50:53], v[182:185], v[222:225], v[50:53]
	v_mfma_f32_16x16x32_bf16 v[34:37], v[182:185], v[230:233], v[34:37]
	v_mfma_f32_16x16x32_bf16 v[34:37], v[186:189], v[234:237], v[34:37]
	v_mfma_f32_16x16x32_bf16 v[38:41], v[178:181], v[234:237], v[38:41]
	v_mfma_f32_16x16x32_bf16 v[38:41], v[174:177], v[230:233], v[38:41]
	v_mfma_f32_16x16x32_bf16 v[42:45], v[164:167], v[230:233], v[42:45]
	v_mfma_f32_16x16x32_bf16 v[42:45], v[168:171], v[234:237], v[42:45]
	v_mfma_f32_16x16x32_bf16 v[46:49], v[160:163], v[234:237], v[46:49]
	v_mfma_f32_16x16x32_bf16 v[46:49], v[156:159], v[230:233], v[46:49]
	v_mfma_f32_16x16x32_bf16 v[30:33], v[156:159], v[238:241], v[30:33]
	v_mfma_f32_16x16x32_bf16 v[30:33], v[160:163], v[242:245], v[30:33]
	v_mfma_f32_16x16x32_bf16 v[26:29], v[168:171], v[242:245], v[26:29]
	v_mfma_f32_16x16x32_bf16 v[26:29], v[164:167], v[238:241], v[26:29]
	v_mfma_f32_16x16x32_bf16 v[22:25], v[174:177], v[238:241], v[22:25]
	v_mfma_f32_16x16x32_bf16 v[22:25], v[178:181], v[242:245], v[22:25]
	v_mfma_f32_16x16x32_bf16 v[18:21], v[186:189], v[242:245], v[18:21]
	v_mfma_f32_16x16x32_bf16 v[18:21], v[182:185], v[238:241], v[18:21]
	v_mfma_f32_16x16x32_bf16 v[2:5], v[182:185], v[246:249], v[2:5]
	v_mfma_f32_16x16x32_bf16 v[2:5], v[186:189], v[250:253], v[2:5]
	v_mfma_f32_16x16x32_bf16 v[6:9], v[178:181], v[250:253], v[6:9]
	v_mfma_f32_16x16x32_bf16 v[6:9], v[174:177], v[246:249], v[6:9]
	v_mfma_f32_16x16x32_bf16 v[10:13], v[164:167], v[246:249], v[10:13]
	v_mfma_f32_16x16x32_bf16 v[10:13], v[168:171], v[250:253], v[10:13]
	v_mfma_f32_16x16x32_bf16 v[14:17], v[160:163], v[250:253], v[14:17]
	v_mfma_f32_16x16x32_bf16 v[14:17], v[156:159], v[246:249], v[14:17]
	s_setprio 0
	s_waitcnt vmcnt(0)
	s_add_i32 s49, s49, 1
	s_cmp_lt_u32 s49, 16
	s_cbranch_scc0 .Lp8k_B_exit
	s_barrier
	s_branch .Lp8k_B_loop

; #define PG8_STAGE(bufoff, gbase, voff) do { _Pragma("unroll") for (int _i = 0; _i < 2; ++_i) \
;         __builtin_amdgcn_global_load_lds((const unsigned*)((const char*)(gbase) + (voff)[_i]), (PG8_LAS unsigned*)(lds + (bufoff) + ldsw + _i * 8192), 16, 0, 0); } while (0)
; #define PG8_LDA(dst, b, h) do { _Pragma("unroll") for (int m = 0; m < 4; ++m) _Pragma("unroll") for (int k = 0; k < 2; ++k) dst[m][k] = *(const PG8_LAS bf16x8*)(lds + PG8_SA(b, h) + aoff + m * 2048 + k * 1024); } while (0)
; #define PG8_LDB(dst, b, h) do { _Pragma("unroll") for (int n = 0; n < 2; ++n) _Pragma("unroll") for (int k = 0; k < 2; ++k) dst[n][k] = *(const PG8_LAS bf16x8*)(lds + PG8_SB(b, h) + boff + n * 2048 + k * 1024); } while (0)
; #define PG8_WAIT_V(n) asm volatile("s_waitcnt vmcnt(" #n ")" ::: "memory")
; #define PG8_WAIT_L(n) asm volatile("s_waitcnt lgkmcnt(" #n ")" ::: "memory")
; template <class Epi, class Sched, bool ALIGN_EPI>
; __device__ __forceinline__ void gemm_phase(PG8_LAS unsigned char* lds, const Gemm g, const Sched& S, const Epi& E) {
;     ...
;             PG8_LDB(B0, 0, 0); PG8_LDB(B1, 0, 1); PG8_SCHED; PG8_LDA(At, 0, 0); PG8_STAGE(PG8_SA(1, 1), a1 + hstepA, voffA);
;             PG8_WAIT_V(8); PG8_WAIT_L(0); PG8_BAR; PG8_MMA(0, 0, At, B0); PG8_MMA(0, 1, At, B1); PG8_BAR; PG8_SCHED;
;             PG8_LDA(At, 0, 1); PG8_STAGE(PG8_SB(0, 0), b2, voffB); PG8_STAGE(PG8_SB(0, 1), b2 + hstepB, voffB); PG8_STAGE(PG8_SA(0, 0), a2, voffA);
;             PG8_WAIT_V(8); PG8_WAIT_L(0); PG8_BAR; PG8_MMA(1, 0, At, B0); PG8_MMA(1, 1, At, B1); PG8_BAR; PG8_SCHED;
;             PG8_LDB(B0, 1, 0); PG8_LDB(B1, 1, 1); PG8_SCHED; PG8_LDA(At, 1, 0); PG8_STAGE(PG8_SA(0, 1), a2 + hstepA, voffA);
;             PG8_WAIT_V(8); PG8_WAIT_L(0); PG8_BAR; PG8_MMA(0, 0, At, B0); PG8_MMA(0, 1, At, B1); PG8_BAR; PG8_SCHED;
;             PG8_LDA(At, 1, 1); PG8_STAGE(PG8_SB(1, 0), b3, voffB); PG8_STAGE(PG8_SB(1, 1), b3 + hstepB, voffB); PG8_STAGE(PG8_SA(1, 0), a3, voffA);
;             PG8_WAIT_V(8); PG8_WAIT_L(0); PG8_BAR; PG8_MMA(1, 0, At, B0); PG8_MMA(1, 1, At, B1); PG8_BAR; PG8_SCHED;
; __global__ void __launch_bounds__(NWAVES * 64, 2) hymba_fwd(Args a) {
;     ...
;         pg8::Gemm g{HID, Wd_t, D_FF, D_FF, D_FF}; pg8::StaticOrder S; S.init(M, DM, G, bx);
;         pg8::EpiBf16P E{MIX, DM};
;         pg8::gemm_phase<pg8::EpiBf16P, pg8::StaticOrder, true>(lds, g, S, E);
.LBB0_947:
	s_add_u32 s6, s6, s30
	s_addc_u32 s7, s7, s31
	s_add_u32 s24, s34, s24
	s_addc_u32 s25, s35, s25
	s_add_u32 s57, s28, 0x100
	s_addc_u32 s58, s29, 0
	s_mov_b32 s59, -2
	s_and_b32 s60, s37, 0xfff
	s_mov_b32 s57, 0
	s_cmp_lt_u32 s37, 0x1000
	s_cbranch_scc0 .Lp9k_B_init
	s_add_u32 s28, s28, 0x80
	s_addc_u32 s29, s29, 0
	s_mov_b64 s[58:59], s[24:25]
	s_setprio 2
	ds_read_b128 v[194:197], v157 offset:0
	ds_read_b128 v[198:201], v157 offset:1024
	ds_read_b128 v[202:205], v157 offset:2048
	s_add_i32 m0, s60, 0x18000
	s_nop 0
	global_load_lds_dwordx4 v132, s[28:29]
	ds_read_b128 v[206:209], v157 offset:3072
	ds_read_b128 v[210:213], v157 offset:4096
	ds_read_b128 v[214:217], v157 offset:5120
	s_add_i32 m0, s60, 0x1a000
	s_nop 0
	global_load_lds_dwordx4 v136, s[28:29]
	ds_read_b128 v[218:221], v157 offset:6144
	ds_read_b128 v[222:225], v157 offset:7168
	ds_read_b128 v[158:161], v155 offset:0
	s_add_u32 s30, s28, 0x58000
	s_addc_u32 s31, s29, 0
	s_add_i32 m0, s60, 0x19000
	s_nop 0
	global_load_lds_dwordx4 v132, s[30:31]
	ds_read_b128 v[162:165], v155 offset:1024
	ds_read_b128 v[166:169], v155 offset:2048
	ds_read_b128 v[174:177], v155 offset:3072
	s_add_i32 m0, s60, 0x1b000
	s_nop 0
	global_load_lds_dwordx4 v136, s[30:31]
	ds_read_b128 v[178:181], v155 offset:16384
	ds_read_b128 v[182:185], v155 offset:17408
	ds_read_b128 v[186:189], v155 offset:18432
	s_add_u32 s30, s28, 0x160000
	s_addc_u32 s31, s29, 0
	s_add_i32 m0, s60, 0x1c000
	s_nop 0
	global_load_lds_dwordx4 v132, s[30:31]
	ds_read_b128 v[190:193], v155 offset:19456
	ds_read_b128 v[226:229], v157 offset:16384
	ds_read_b128 v[230:233], v157 offset:17408
	s_add_i32 m0, s60, 0x1e000
	s_nop 0
	global_load_lds_dwordx4 v136, s[30:31]
	ds_read_b128 v[234:237], v157 offset:18432
	ds_read_b128 v[238:241], v157 offset:19456
	ds_read_b128 v[242:245], v157 offset:20480
	s_add_u32 s30, s28, 0x1b8000
	s_addc_u32 s31, s29, 0
	s_add_i32 m0, s60, 0x1d000
	s_nop 0
	global_load_lds_dwordx4 v132, s[30:31]
	ds_read_b128 v[246:249], v157 offset:21504
	ds_read_b128 v[250:253], v157 offset:22528
	ds_read_b128 v[142:145], v157 offset:23552
	s_add_i32 m0, s60, 0x1f000
	s_nop 0
	global_load_lds_dwordx4 v136, s[30:31]
	s_add_u32 s28, s28, 0x80
	s_addc_u32 s29, s29, 0
	s_waitcnt vmcnt(8) lgkmcnt(0)
	s_barrier
	s_setprio 1
	v_mfma_f32_16x16x32_bf16 v[126:129], v[158:161], v[194:197], 0
	v_mfma_f32_16x16x32_bf16 v[126:129], v[162:165], v[198:201], v[126:129]
	v_mfma_f32_16x16x32_bf16 v[122:125], v[174:177], v[198:201], 0
	v_mfma_f32_16x16x32_bf16 v[122:125], v[166:169], v[194:197], v[122:125]
	v_mfma_f32_16x16x32_bf16 v[114:117], v[178:181], v[194:197], 0
	v_mfma_f32_16x16x32_bf16 v[114:117], v[182:185], v[198:201], v[114:117]
	v_mfma_f32_16x16x32_bf16 v[106:109], v[190:193], v[198:201], 0
	v_mfma_f32_16x16x32_bf16 v[106:109], v[186:189], v[194:197], v[106:109]
	v_mfma_f32_16x16x32_bf16 v[90:93], v[186:189], v[202:205], 0
	v_mfma_f32_16x16x32_bf16 v[90:93], v[190:193], v[206:209], v[90:93]
	v_mfma_f32_16x16x32_bf16 v[98:101], v[182:185], v[206:209], 0
	v_mfma_f32_16x16x32_bf16 v[98:101], v[178:181], v[202:205], v[98:101]
	v_mfma_f32_16x16x32_bf16 v[110:113], v[166:169], v[202:205], 0
	v_mfma_f32_16x16x32_bf16 v[110:113], v[174:177], v[206:209], v[110:113]
	v_mfma_f32_16x16x32_bf16 v[118:121], v[162:165], v[206:209], 0
	v_mfma_f32_16x16x32_bf16 v[118:121], v[158:161], v[202:205], v[118:121]
	v_mfma_f32_16x16x32_bf16 v[102:105], v[158:161], v[210:213], 0
	v_mfma_f32_16x16x32_bf16 v[102:105], v[162:165], v[214:217], v[102:105]
	v_mfma_f32_16x16x32_bf16 v[94:97], v[174:177], v[214:217], 0
	v_mfma_f32_16x16x32_bf16 v[94:97], v[166:169], v[210:213], v[94:97]
	v_mfma_f32_16x16x32_bf16 v[82:85], v[178:181], v[210:213], 0
	v_mfma_f32_16x16x32_bf16 v[82:85], v[182:185], v[214:217], v[82:85]
	v_mfma_f32_16x16x32_bf16 v[74:77], v[190:193], v[214:217], 0
	v_mfma_f32_16x16x32_bf16 v[74:77], v[186:189], v[210:213], v[74:77]
	v_mfma_f32_16x16x32_bf16 v[66:69], v[186:189], v[218:221], 0
	v_mfma_f32_16x16x32_bf16 v[66:69], v[190:193], v[222:225], v[66:69]
	v_mfma_f32_16x16x32_bf16 v[70:73], v[182:185], v[222:225], 0
	v_mfma_f32_16x16x32_bf16 v[70:73], v[178:181], v[218:221], v[70:73]
	v_mfma_f32_16x16x32_bf16 v[78:81], v[166:169], v[218:221], 0
	v_mfma_f32_16x16x32_bf16 v[78:81], v[174:177], v[222:225], v[78:81]
	v_mfma_f32_16x16x32_bf16 v[86:89], v[162:165], v[222:225], 0
	v_mfma_f32_16x16x32_bf16 v[86:89], v[158:161], v[218:221], v[86:89]
	v_mfma_f32_16x16x32_bf16 v[62:65], v[158:161], v[226:229], 0
	v_mfma_f32_16x16x32_bf16 v[62:65], v[162:165], v[230:233], v[62:65]
	v_mfma_f32_16x16x32_bf16 v[58:61], v[174:177], v[230:233], 0
	v_mfma_f32_16x16x32_bf16 v[58:61], v[166:169], v[226:229], v[58:61]
	v_mfma_f32_16x16x32_bf16 v[50:53], v[178:181], v[226:229], 0
	v_mfma_f32_16x16x32_bf16 v[50:53], v[182:185], v[230:233], v[50:53]
	v_mfma_f32_16x16x32_bf16 v[42:45], v[190:193], v[230:233], 0
	v_mfma_f32_16x16x32_bf16 v[42:45], v[186:189], v[226:229], v[42:45]
	v_mfma_f32_16x16x32_bf16 v[26:29], v[186:189], v[234:237], 0
	v_mfma_f32_16x16x32_bf16 v[26:29], v[190:193], v[238:241], v[26:29]
	v_mfma_f32_16x16x32_bf16 v[34:37], v[182:185], v[238:241], 0
	v_mfma_f32_16x16x32_bf16 v[34:37], v[178:181], v[234:237], v[34:37]
	v_mfma_f32_16x16x32_bf16 v[46:49], v[166:169], v[234:237], 0
	v_mfma_f32_16x16x32_bf16 v[46:49], v[174:177], v[238:241], v[46:49]
	v_mfma_f32_16x16x32_bf16 v[54:57], v[162:165], v[238:241], 0
	v_mfma_f32_16x16x32_bf16 v[54:57], v[158:161], v[234:237], v[54:57]
	v_mfma_f32_16x16x32_bf16 v[38:41], v[158:161], v[242:245], 0
	v_mfma_f32_16x16x32_bf16 v[38:41], v[162:165], v[246:249], v[38:41]
	v_mfma_f32_16x16x32_bf16 v[30:33], v[174:177], v[246:249], 0
	v_mfma_f32_16x16x32_bf16 v[30:33], v[166:169], v[242:245], v[30:33]
	v_mfma_f32_16x16x32_bf16 v[18:21], v[178:181], v[242:245], 0
	v_mfma_f32_16x16x32_bf16 v[18:21], v[182:185], v[246:249], v[18:21]
	v_mfma_f32_16x16x32_bf16 v[10:13], v[190:193], v[246:249], 0
	v_mfma_f32_16x16x32_bf16 v[10:13], v[186:189], v[242:245], v[10:13]
	v_mfma_f32_16x16x32_bf16 v[2:5], v[186:189], v[250:253], 0
	v_mfma_f32_16x16x32_bf16 v[2:5], v[190:193], v[142:145], v[2:5]
	v_mfma_f32_16x16x32_bf16 v[6:9], v[182:185], v[142:145], 0
	v_mfma_f32_16x16x32_bf16 v[6:9], v[178:181], v[250:253], v[6:9]
	v_mfma_f32_16x16x32_bf16 v[14:17], v[166:169], v[250:253], 0
	v_mfma_f32_16x16x32_bf16 v[14:17], v[174:177], v[142:145], v[14:17]
	v_mfma_f32_16x16x32_bf16 v[22:25], v[162:165], v[142:145], 0
	v_mfma_f32_16x16x32_bf16 v[22:25], v[158:161], v[250:253], v[22:25]
	s_setprio 0
	s_waitcnt vmcnt(0)
	s_barrier
; #define PG8_STAGE(bufoff, gbase, voff) do { _Pragma("unroll") for (int _i = 0; _i < 2; ++_i) \
;         __builtin_amdgcn_global_load_lds((const unsigned*)((const char*)(gbase) + (voff)[_i]), (PG8_LAS unsigned*)(lds + (bufoff) + ldsw + _i * 8192), 16, 0, 0); } while (0)
; #define PG8_LDA(dst, b, h) do { _Pragma("unroll") for (int m = 0; m < 4; ++m) _Pragma("unroll") for (int k = 0; k < 2; ++k) dst[m][k] = *(const PG8_LAS bf16x8*)(lds + PG8_SA(b, h) + aoff + m * 2048 + k * 1024); } while (0)
; #define PG8_LDB(dst, b, h) do { _Pragma("unroll") for (int n = 0; n < 2; ++n) _Pragma("unroll") for (int k = 0; k < 2; ++k) dst[n][k] = *(const PG8_LAS bf16x8*)(lds + PG8_SB(b, h) + boff + n * 2048 + k * 1024); } while (0)
; #define PG8_WAIT_V(n) asm volatile("s_waitcnt vmcnt(" #n ")" ::: "memory")
; #define PG8_WAIT_L(n) asm volatile("s_waitcnt lgkmcnt(" #n ")" ::: "memory")
; #define PG8_BAR __builtin_amdgcn_s_barrier()
; #define PG8_SCHED __builtin_amdgcn_sched_barrier(0)
; template <class Epi, class Sched, bool ALIGN_EPI>
; __device__ __forceinline__ void gemm_phase(PG8_LAS unsigned char* lds, const Gemm g, const Sched& S, const Epi& E) {
;     ...
;             const char* a2 = last ? nA : cA + (size_t)(t + 2) * kstepA; const char* b2 = last ? nB : cB + (size_t)(t + 2) * kstep;
;             const char* a3 = a2 + kstepA; const char* b3 = b2 + kstep;
;             PG8_LDB(B0, 0, 0); PG8_LDB(B1, 0, 1); PG8_SCHED; PG8_LDA(At, 0, 0); PG8_STAGE(PG8_SA(1, 1), a1 + hstepA, voffA);
;             PG8_WAIT_V(8); PG8_WAIT_L(0); PG8_BAR; PG8_MMA(0, 0, At, B0); PG8_MMA(0, 1, At, B1); PG8_BAR; PG8_SCHED;
;             PG8_LDA(At, 0, 1); PG8_STAGE(PG8_SB(0, 0), b2, voffB); PG8_STAGE(PG8_SB(0, 1), b2 + hstepB, voffB); PG8_STAGE(PG8_SA(0, 0), a2, voffA);
;             PG8_WAIT_V(8); PG8_WAIT_L(0); PG8_BAR; PG8_MMA(1, 0, At, B0); PG8_MMA(1, 1, At, B1); PG8_BAR; PG8_SCHED;
;             PG8_LDB(B0, 1, 0); PG8_LDB(B1, 1, 1); PG8_SCHED; PG8_LDA(At, 1, 0); PG8_STAGE(PG8_SA(0, 1), a2 + hstepA, voffA);
;             PG8_WAIT_V(8); PG8_WAIT_L(0); PG8_BAR; PG8_MMA(0, 0, At, B0); PG8_MMA(0, 1, At, B1); PG8_BAR; PG8_SCHED;
;             PG8_LDA(At, 1, 1); PG8_STAGE(PG8_SB(1, 0), b3, voffB); PG8_STAGE(PG8_SB(1, 1), b3 + hstepB, voffB); PG8_STAGE(PG8_SA(1, 0), a3, voffA);
;             PG8_WAIT_V(8); PG8_WAIT_L(0); PG8_BAR; PG8_MMA(1, 0, At, B0); PG8_MMA(1, 1, At, B1); PG8_BAR; PG8_SCHED;
	s_setprio 2
	ds_read_b128 v[194:197], v157 offset:32768
	ds_read_b128 v[198:201], v157 offset:33792
	ds_read_b128 v[202:205], v157 offset:34816
	s_cmp_eq_u32 s57, 43
	s_cselect_b32 s28, s58, s28
	s_cselect_b32 s29, s59, s29
	s_add_i32 m0, s60, 0x10000
	s_nop 0
	global_load_lds_dwordx4 v132, s[28:29]
	ds_read_b128 v[206:209], v157 offset:35840
	ds_read_b128 v[210:213], v157 offset:36864
	ds_read_b128 v[214:217], v157 offset:37888
	s_add_i32 m0, s60, 0x12000
	s_nop 0
	global_load_lds_dwordx4 v136, s[28:29]
	ds_read_b128 v[218:221], v157 offset:38912
	ds_read_b128 v[222:225], v157 offset:39936
	ds_read_b128 v[158:161], v155 offset:32768
	s_add_u32 s30, s28, 0x58000
	s_addc_u32 s31, s29, 0
	s_add_i32 m0, s60, 0x11000
	s_nop 0
	global_load_lds_dwordx4 v132, s[30:31]
	ds_read_b128 v[162:165], v155 offset:33792
	ds_read_b128 v[166:169], v155 offset:34816
	ds_read_b128 v[174:177], v155 offset:35840
	s_add_i32 m0, s60, 0x13000
	s_nop 0
	global_load_lds_dwordx4 v136, s[30:31]
	ds_read_b128 v[178:181], v155 offset:49152
	ds_read_b128 v[182:185], v155 offset:50176
	ds_read_b128 v[186:189], v155 offset:51200
	s_add_u32 s30, s28, 0x160000
	s_addc_u32 s31, s29, 0
	s_add_i32 m0, s60, 0x14000
	s_nop 0
	global_load_lds_dwordx4 v132, s[30:31]
	ds_read_b128 v[190:193], v155 offset:52224
	ds_read_b128 v[226:229], v157 offset:49152
	ds_read_b128 v[230:233], v157 offset:50176
	s_add_i32 m0, s60, 0x16000
	s_nop 0
	global_load_lds_dwordx4 v136, s[30:31]
	ds_read_b128 v[234:237], v157 offset:51200
	ds_read_b128 v[238:241], v157 offset:52224
	ds_read_b128 v[242:245], v157 offset:53248
	s_add_u32 s30, s28, 0x1b8000
	s_addc_u32 s31, s29, 0
	s_add_i32 m0, s60, 0x15000
	s_nop 0
	global_load_lds_dwordx4 v132, s[30:31]
	ds_read_b128 v[246:249], v157 offset:54272
	ds_read_b128 v[250:253], v157 offset:55296
	ds_read_b128 v[142:145], v157 offset:56320
	s_add_i32 m0, s60, 0x17000
	s_nop 0
	global_load_lds_dwordx4 v136, s[30:31]
	s_add_u32 s28, s28, 0x80
	s_addc_u32 s29, s29, 0
	s_waitcnt vmcnt(8) lgkmcnt(0)
	s_barrier
	s_setprio 1
	v_mfma_f32_16x16x32_bf16 v[126:129], v[158:161], v[194:197], v[126:129]
	v_mfma_f32_16x16x32_bf16 v[126:129], v[162:165], v[198:201], v[126:129]
	v_mfma_f32_16x16x32_bf16 v[122:125], v[174:177], v[198:201], v[122:125]
	v_mfma_f32_16x16x32_bf16 v[122:125], v[166:169], v[194:197], v[122:125]
	v_mfma_f32_16x16x32_bf16 v[114:117], v[178:181], v[194:197], v[114:117]
	v_mfma_f32_16x16x32_bf16 v[114:117], v[182:185], v[198:201], v[114:117]
	v_mfma_f32_16x16x32_bf16 v[106:109], v[190:193], v[198:201], v[106:109]
	v_mfma_f32_16x16x32_bf16 v[106:109], v[186:189], v[194:197], v[106:109]
	v_mfma_f32_16x16x32_bf16 v[90:93], v[186:189], v[202:205], v[90:93]
	v_mfma_f32_16x16x32_bf16 v[90:93], v[190:193], v[206:209], v[90:93]
	v_mfma_f32_16x16x32_bf16 v[98:101], v[182:185], v[206:209], v[98:101]
	v_mfma_f32_16x16x32_bf16 v[98:101], v[178:181], v[202:205], v[98:101]
	v_mfma_f32_16x16x32_bf16 v[110:113], v[166:169], v[202:205], v[110:113]
	v_mfma_f32_16x16x32_bf16 v[110:113], v[174:177], v[206:209], v[110:113]
	v_mfma_f32_16x16x32_bf16 v[118:121], v[162:165], v[206:209], v[118:121]
	v_mfma_f32_16x16x32_bf16 v[118:121], v[158:161], v[202:205], v[118:121]
	v_mfma_f32_16x16x32_bf16 v[102:105], v[158:161], v[210:213], v[102:105]
	v_mfma_f32_16x16x32_bf16 v[102:105], v[162:165], v[214:217], v[102:105]
	v_mfma_f32_16x16x32_bf16 v[94:97], v[174:177], v[214:217], v[94:97]
	v_mfma_f32_16x16x32_bf16 v[94:97], v[166:169], v[210:213], v[94:97]
	v_mfma_f32_16x16x32_bf16 v[82:85], v[178:181], v[210:213], v[82:85]
	v_mfma_f32_16x16x32_bf16 v[82:85], v[182:185], v[214:217], v[82:85]
	v_mfma_f32_16x16x32_bf16 v[74:77], v[190:193], v[214:217], v[74:77]
	v_mfma_f32_16x16x32_bf16 v[74:77], v[186:189], v[210:213], v[74:77]
	v_mfma_f32_16x16x32_bf16 v[66:69], v[186:189], v[218:221], v[66:69]
	v_mfma_f32_16x16x32_bf16 v[66:69], v[190:193], v[222:225], v[66:69]
	v_mfma_f32_16x16x32_bf16 v[70:73], v[182:185], v[222:225], v[70:73]
	v_mfma_f32_16x16x32_bf16 v[70:73], v[178:181], v[218:221], v[70:73]
	v_mfma_f32_16x16x32_bf16 v[78:81], v[166:169], v[218:221], v[78:81]
	v_mfma_f32_16x16x32_bf16 v[78:81], v[174:177], v[222:225], v[78:81]
	v_mfma_f32_16x16x32_bf16 v[86:89], v[162:165], v[222:225], v[86:89]
	v_mfma_f32_16x16x32_bf16 v[86:89], v[158:161], v[218:221], v[86:89]
	v_mfma_f32_16x16x32_bf16 v[62:65], v[158:161], v[226:229], v[62:65]
	v_mfma_f32_16x16x32_bf16 v[62:65], v[162:165], v[230:233], v[62:65]
	v_mfma_f32_16x16x32_bf16 v[58:61], v[174:177], v[230:233], v[58:61]
	v_mfma_f32_16x16x32_bf16 v[58:61], v[166:169], v[226:229], v[58:61]
	v_mfma_f32_16x16x32_bf16 v[50:53], v[178:181], v[226:229], v[50:53]
	v_mfma_f32_16x16x32_bf16 v[50:53], v[182:185], v[230:233], v[50:53]
	v_mfma_f32_16x16x32_bf16 v[42:45], v[190:193], v[230:233], v[42:45]
	v_mfma_f32_16x16x32_bf16 v[42:45], v[186:189], v[226:229], v[42:45]
	v_mfma_f32_16x16x32_bf16 v[26:29], v[186:189], v[234:237], v[26:29]
	v_mfma_f32_16x16x32_bf16 v[26:29], v[190:193], v[238:241], v[26:29]
	v_mfma_f32_16x16x32_bf16 v[34:37], v[182:185], v[238:241], v[34:37]
	v_mfma_f32_16x16x32_bf16 v[34:37], v[178:181], v[234:237], v[34:37]
	v_mfma_f32_16x16x32_bf16 v[46:49], v[166:169], v[234:237], v[46:49]
	v_mfma_f32_16x16x32_bf16 v[46:49], v[174:177], v[238:241], v[46:49]
	v_mfma_f32_16x16x32_bf16 v[54:57], v[162:165], v[238:241], v[54:57]
	v_mfma_f32_16x16x32_bf16 v[54:57], v[158:161], v[234:237], v[54:57]
	v_mfma_f32_16x16x32_bf16 v[38:41], v[158:161], v[242:245], v[38:41]
	v_mfma_f32_16x16x32_bf16 v[38:41], v[162:165], v[246:249], v[38:41]
	v_mfma_f32_16x16x32_bf16 v[30:33], v[174:177], v[246:249], v[30:33]
	v_mfma_f32_16x16x32_bf16 v[30:33], v[166:169], v[242:245], v[30:33]
	v_mfma_f32_16x16x32_bf16 v[18:21], v[178:181], v[242:245], v[18:21]
	v_mfma_f32_16x16x32_bf16 v[18:21], v[182:185], v[246:249], v[18:21]
	v_mfma_f32_16x16x32_bf16 v[10:13], v[190:193], v[246:249], v[10:13]
	v_mfma_f32_16x16x32_bf16 v[10:13], v[186:189], v[242:245], v[10:13]
	v_mfma_f32_16x16x32_bf16 v[2:5], v[186:189], v[250:253], v[2:5]
	v_mfma_f32_16x16x32_bf16 v[2:5], v[190:193], v[142:145], v[2:5]
	v_mfma_f32_16x16x32_bf16 v[6:9], v[182:185], v[142:145], v[6:9]
	v_mfma_f32_16x16x32_bf16 v[6:9], v[178:181], v[250:253], v[6:9]
	v_mfma_f32_16x16x32_bf16 v[14:17], v[166:169], v[250:253], v[14:17]
	v_mfma_f32_16x16x32_bf16 v[14:17], v[174:177], v[142:145], v[14:17]
	v_mfma_f32_16x16x32_bf16 v[22:25], v[162:165], v[142:145], v[22:25]
	v_mfma_f32_16x16x32_bf16 v[22:25], v[158:161], v[250:253], v[22:25]
	s_setprio 0
	s_waitcnt vmcnt(0)
	s_barrier
	s_add_i32 s57, s57, 1
; #define PG8_STAGE(bufoff, gbase, voff) do { _Pragma("unroll") for (int _i = 0; _i < 2; ++_i) \
;         __builtin_amdgcn_global_load_lds((const unsigned*)((const char*)(gbase) + (voff)[_i]), (PG8_LAS unsigned*)(lds + (bufoff) + ldsw + _i * 8192), 16, 0, 0); } while (0)
; #define PG8_LDA(dst, b, h) do { _Pragma("unroll") for (int m = 0; m < 4; ++m) _Pragma("unroll") for (int k = 0; k < 2; ++k) dst[m][k] = *(const PG8_LAS bf16x8*)(lds + PG8_SA(b, h) + aoff + m * 2048 + k * 1024); } while (0)
; #define PG8_LDB(dst, b, h) do { _Pragma("unroll") for (int n = 0; n < 2; ++n) _Pragma("unroll") for (int k = 0; k < 2; ++k) dst[n][k] = *(const PG8_LAS bf16x8*)(lds + PG8_SB(b, h) + boff + n * 2048 + k * 1024); } while (0)
; #define PG8_MMA(ai, bj, At, Bt) do { __builtin_amdgcn_s_setprio(1); _Pragma("unroll") for (int m = 0; m < 4; ++m) _Pragma("unroll") for (int n = 0; n < 2; ++n) _Pragma("unroll") for (int k = 0; k < 2; ++k) \
;         acc[ai][bj][m][n] = __builtin_amdgcn_mfma_f32_16x16x32_bf16(Bt[n][k], At[m][k], acc[ai][bj][m][n], 0, 0, 0); __builtin_amdgcn_s_setprio(0); } while (0)
; #define PG8_WAIT_V(n) asm volatile("s_waitcnt vmcnt(" #n ")" ::: "memory")
; #define PG8_WAIT_L(n) asm volatile("s_waitcnt lgkmcnt(" #n ")" ::: "memory")
; #define PG8_BAR __builtin_amdgcn_s_barrier()
; #define PG8_SCHED __builtin_amdgcn_sched_barrier(0)
; template <class Epi, class Sched, bool ALIGN_EPI>
; __device__ __forceinline__ void gemm_phase(PG8_LAS unsigned char* lds, const Gemm g, const Sched& S, const Epi& E) {
;     ...
;             PG8_LDB(B0, 0, 0); PG8_LDB(B1, 0, 1); PG8_SCHED; PG8_LDA(At, 0, 0); PG8_STAGE(PG8_SA(1, 1), a1 + hstepA, voffA);
;             PG8_WAIT_V(8); PG8_WAIT_L(0); PG8_BAR; PG8_MMA(0, 0, At, B0); PG8_MMA(0, 1, At, B1); PG8_BAR; PG8_SCHED;
;             PG8_LDA(At, 0, 1); PG8_STAGE(PG8_SB(0, 0), b2, voffB); PG8_STAGE(PG8_SB(0, 1), b2 + hstepB, voffB); PG8_STAGE(PG8_SA(0, 0), a2, voffA);
;             PG8_WAIT_V(8); PG8_WAIT_L(0); PG8_BAR; PG8_MMA(1, 0, At, B0); PG8_MMA(1, 1, At, B1); PG8_BAR; PG8_SCHED;
.Lp9k_A_loop:
	s_setprio 2
	ds_read_b128 v[194:197], v157 offset:0
	ds_read_b128 v[198:201], v157 offset:1024
	ds_read_b128 v[202:205], v157 offset:2048
	s_add_i32 m0, s60, 0x18000
	s_nop 0
	global_load_lds_dwordx4 v132, s[28:29]
	ds_read_b128 v[206:209], v157 offset:3072
	ds_read_b128 v[210:213], v157 offset:4096
	ds_read_b128 v[214:217], v157 offset:5120
	s_add_i32 m0, s60, 0x1a000
	s_nop 0
	global_load_lds_dwordx4 v136, s[28:29]
	ds_read_b128 v[218:221], v157 offset:6144
	ds_read_b128 v[222:225], v157 offset:7168
	ds_read_b128 v[158:161], v155 offset:0
	s_add_u32 s30, s28, 0x58000
	s_addc_u32 s31, s29, 0
	s_add_i32 m0, s60, 0x19000
	s_nop 0
	global_load_lds_dwordx4 v132, s[30:31]
	ds_read_b128 v[162:165], v155 offset:1024
	ds_read_b128 v[166:169], v155 offset:2048
	ds_read_b128 v[174:177], v155 offset:3072
	s_add_i32 m0, s60, 0x1b000
	s_nop 0
	global_load_lds_dwordx4 v136, s[30:31]
	ds_read_b128 v[178:181], v155 offset:16384
	ds_read_b128 v[182:185], v155 offset:17408
	ds_read_b128 v[186:189], v155 offset:18432
	s_add_u32 s30, s28, 0x160000
	s_addc_u32 s31, s29, 0
	s_add_i32 m0, s60, 0x1c000
	s_nop 0
	global_load_lds_dwordx4 v132, s[30:31]
	ds_read_b128 v[190:193], v155 offset:19456
	ds_read_b128 v[226:229], v157 offset:16384
	ds_read_b128 v[230:233], v157 offset:17408
	s_add_i32 m0, s60, 0x1e000
	s_nop 0
	global_load_lds_dwordx4 v136, s[30:31]
	ds_read_b128 v[234:237], v157 offset:18432
	ds_read_b128 v[238:241], v157 offset:19456
	ds_read_b128 v[242:245], v157 offset:20480
	s_add_u32 s30, s28, 0x1b8000
	s_addc_u32 s31, s29, 0
	s_add_i32 m0, s60, 0x1d000
	s_nop 0
	global_load_lds_dwordx4 v132, s[30:31]
	ds_read_b128 v[246:249], v157 offset:21504
	ds_read_b128 v[250:253], v157 offset:22528
	ds_read_b128 v[142:145], v157 offset:23552
	s_add_i32 m0, s60, 0x1f000
	s_nop 0
	global_load_lds_dwordx4 v136, s[30:31]
	s_add_u32 s28, s28, 0x80
	s_addc_u32 s29, s29, 0
	s_waitcnt vmcnt(8) lgkmcnt(0)
	s_barrier
	s_setprio 1
	v_mfma_f32_16x16x32_bf16 v[126:129], v[158:161], v[194:197], v[126:129]
	v_mfma_f32_16x16x32_bf16 v[126:129], v[162:165], v[198:201], v[126:129]
	v_mfma_f32_16x16x32_bf16 v[122:125], v[174:177], v[198:201], v[122:125]
	v_mfma_f32_16x16x32_bf16 v[122:125], v[166:169], v[194:197], v[122:125]
	v_mfma_f32_16x16x32_bf16 v[114:117], v[178:181], v[194:197], v[114:117]
	v_mfma_f32_16x16x32_bf16 v[114:117], v[182:185], v[198:201], v[114:117]
	v_mfma_f32_16x16x32_bf16 v[106:109], v[190:193], v[198:201], v[106:109]
	v_mfma_f32_16x16x32_bf16 v[106:109], v[186:189], v[194:197], v[106:109]
	v_mfma_f32_16x16x32_bf16 v[90:93], v[186:189], v[202:205], v[90:93]
	v_mfma_f32_16x16x32_bf16 v[90:93], v[190:193], v[206:209], v[90:93]
	v_mfma_f32_16x16x32_bf16 v[98:101], v[182:185], v[206:209], v[98:101]
	v_mfma_f32_16x16x32_bf16 v[98:101], v[178:181], v[202:205], v[98:101]
	v_mfma_f32_16x16x32_bf16 v[110:113], v[166:169], v[202:205], v[110:113]
	v_mfma_f32_16x16x32_bf16 v[110:113], v[174:177], v[206:209], v[110:113]
	v_mfma_f32_16x16x32_bf16 v[118:121], v[162:165], v[206:209], v[118:121]
	v_mfma_f32_16x16x32_bf16 v[118:121], v[158:161], v[202:205], v[118:121]
	v_mfma_f32_16x16x32_bf16 v[102:105], v[158:161], v[210:213], v[102:105]
	v_mfma_f32_16x16x32_bf16 v[102:105], v[162:165], v[214:217], v[102:105]
	v_mfma_f32_16x16x32_bf16 v[94:97], v[174:177], v[214:217], v[94:97]
	v_mfma_f32_16x16x32_bf16 v[94:97], v[166:169], v[210:213], v[94:97]
	v_mfma_f32_16x16x32_bf16 v[82:85], v[178:181], v[210:213], v[82:85]
	v_mfma_f32_16x16x32_bf16 v[82:85], v[182:185], v[214:217], v[82:85]
	v_mfma_f32_16x16x32_bf16 v[74:77], v[190:193], v[214:217], v[74:77]
	v_mfma_f32_16x16x32_bf16 v[74:77], v[186:189], v[210:213], v[74:77]
	v_mfma_f32_16x16x32_bf16 v[66:69], v[186:189], v[218:221], v[66:69]
	v_mfma_f32_16x16x32_bf16 v[66:69], v[190:193], v[222:225], v[66:69]
	v_mfma_f32_16x16x32_bf16 v[70:73], v[182:185], v[222:225], v[70:73]
	v_mfma_f32_16x16x32_bf16 v[70:73], v[178:181], v[218:221], v[70:73]
	v_mfma_f32_16x16x32_bf16 v[78:81], v[166:169], v[218:221], v[78:81]
	v_mfma_f32_16x16x32_bf16 v[78:81], v[174:177], v[222:225], v[78:81]
	v_mfma_f32_16x16x32_bf16 v[86:89], v[162:165], v[222:225], v[86:89]
	v_mfma_f32_16x16x32_bf16 v[86:89], v[158:161], v[218:221], v[86:89]
	v_mfma_f32_16x16x32_bf16 v[62:65], v[158:161], v[226:229], v[62:65]
	v_mfma_f32_16x16x32_bf16 v[62:65], v[162:165], v[230:233], v[62:65]
	v_mfma_f32_16x16x32_bf16 v[58:61], v[174:177], v[230:233], v[58:61]
	v_mfma_f32_16x16x32_bf16 v[58:61], v[166:169], v[226:229], v[58:61]
	v_mfma_f32_16x16x32_bf16 v[50:53], v[178:181], v[226:229], v[50:53]
	v_mfma_f32_16x16x32_bf16 v[50:53], v[182:185], v[230:233], v[50:53]
	v_mfma_f32_16x16x32_bf16 v[42:45], v[190:193], v[230:233], v[42:45]
	v_mfma_f32_16x16x32_bf16 v[42:45], v[186:189], v[226:229], v[42:45]
	v_mfma_f32_16x16x32_bf16 v[26:29], v[186:189], v[234:237], v[26:29]
	v_mfma_f32_16x16x32_bf16 v[26:29], v[190:193], v[238:241], v[26:29]
	v_mfma_f32_16x16x32_bf16 v[34:37], v[182:185], v[238:241], v[34:37]
	v_mfma_f32_16x16x32_bf16 v[34:37], v[178:181], v[234:237], v[34:37]
	v_mfma_f32_16x16x32_bf16 v[46:49], v[166:169], v[234:237], v[46:49]
	v_mfma_f32_16x16x32_bf16 v[46:49], v[174:177], v[238:241], v[46:49]
	v_mfma_f32_16x16x32_bf16 v[54:57], v[162:165], v[238:241], v[54:57]
	v_mfma_f32_16x16x32_bf16 v[54:57], v[158:161], v[234:237], v[54:57]
	v_mfma_f32_16x16x32_bf16 v[38:41], v[158:161], v[242:245], v[38:41]
	v_mfma_f32_16x16x32_bf16 v[38:41], v[162:165], v[246:249], v[38:41]
	v_mfma_f32_16x16x32_bf16 v[30:33], v[174:177], v[246:249], v[30:33]
	v_mfma_f32_16x16x32_bf16 v[30:33], v[166:169], v[242:245], v[30:33]
	v_mfma_f32_16x16x32_bf16 v[18:21], v[178:181], v[242:245], v[18:21]
	v_mfma_f32_16x16x32_bf16 v[18:21], v[182:185], v[246:249], v[18:21]
	v_mfma_f32_16x16x32_bf16 v[10:13], v[190:193], v[246:249], v[10:13]
	v_mfma_f32_16x16x32_bf16 v[10:13], v[186:189], v[242:245], v[10:13]
	v_mfma_f32_16x16x32_bf16 v[2:5], v[186:189], v[250:253], v[2:5]
	v_mfma_f32_16x16x32_bf16 v[2:5], v[190:193], v[142:145], v[2:5]
	v_mfma_f32_16x16x32_bf16 v[6:9], v[182:185], v[142:145], v[6:9]
	v_mfma_f32_16x16x32_bf16 v[6:9], v[178:181], v[250:253], v[6:9]
	v_mfma_f32_16x16x32_bf16 v[14:17], v[166:169], v[250:253], v[14:17]
	v_mfma_f32_16x16x32_bf16 v[14:17], v[174:177], v[142:145], v[14:17]
	v_mfma_f32_16x16x32_bf16 v[22:25], v[162:165], v[142:145], v[22:25]
	v_mfma_f32_16x16x32_bf16 v[22:25], v[158:161], v[250:253], v[22:25]
	s_setprio 0
	s_waitcnt vmcnt(0)
	s_barrier
; #define PG8_STAGE(bufoff, gbase, voff) do { _Pragma("unroll") for (int _i = 0; _i < 2; ++_i) \
;         __builtin_amdgcn_global_load_lds((const unsigned*)((const char*)(gbase) + (voff)[_i]), (PG8_LAS unsigned*)(lds + (bufoff) + ldsw + _i * 8192), 16, 0, 0); } while (0)
; #define PG8_LDA(dst, b, h) do { _Pragma("unroll") for (int m = 0; m < 4; ++m) _Pragma("unroll") for (int k = 0; k < 2; ++k) dst[m][k] = *(const PG8_LAS bf16x8*)(lds + PG8_SA(b, h) + aoff + m * 2048 + k * 1024); } while (0)
; #define PG8_LDB(dst, b, h) do { _Pragma("unroll") for (int n = 0; n < 2; ++n) _Pragma("unroll") for (int k = 0; k < 2; ++k) dst[n][k] = *(const PG8_LAS bf16x8*)(lds + PG8_SB(b, h) + boff + n * 2048 + k * 1024); } while (0)
; #define PG8_MMA(ai, bj, At, Bt) do { __builtin_amdgcn_s_setprio(1); _Pragma("unroll") for (int m = 0; m < 4; ++m) _Pragma("unroll") for (int n = 0; n < 2; ++n) _Pragma("unroll") for (int k = 0; k < 2; ++k) \
;         acc[ai][bj][m][n] = __builtin_amdgcn_mfma_f32_16x16x32_bf16(Bt[n][k], At[m][k], acc[ai][bj][m][n], 0, 0, 0); __builtin_amdgcn_s_setprio(0); } while (0)
; #define PG8_WAIT_V(n) asm volatile("s_waitcnt vmcnt(" #n ")" ::: "memory")
; #define PG8_WAIT_L(n) asm volatile("s_waitcnt lgkmcnt(" #n ")" ::: "memory")
; #define PG8_BAR __builtin_amdgcn_s_barrier()
; #define PG8_SCHED __builtin_amdgcn_sched_barrier(0)
; template <class Epi, class Sched, bool ALIGN_EPI>
; __device__ __forceinline__ void gemm_phase(PG8_LAS unsigned char* lds, const Gemm g, const Sched& S, const Epi& E) {
;     ...
;             PG8_LDB(B0, 1, 0); PG8_LDB(B1, 1, 1); PG8_SCHED; PG8_LDA(At, 1, 0); PG8_STAGE(PG8_SA(0, 1), a2 + hstepA, voffA);
;             PG8_WAIT_V(8); PG8_WAIT_L(0); PG8_BAR; PG8_MMA(0, 0, At, B0); PG8_MMA(0, 1, At, B1); PG8_BAR; PG8_SCHED;
;             PG8_LDA(At, 1, 1); PG8_STAGE(PG8_SB(1, 0), b3, voffB); PG8_STAGE(PG8_SB(1, 1), b3 + hstepB, voffB); PG8_STAGE(PG8_SA(1, 0), a3, voffA);
;             PG8_WAIT_V(8); PG8_WAIT_L(0); PG8_BAR; PG8_MMA(1, 0, At, B0); PG8_MMA(1, 1, At, B1); PG8_BAR; PG8_SCHED;
;         }
	s_setprio 2
	ds_read_b128 v[194:197], v157 offset:32768
	ds_read_b128 v[198:201], v157 offset:33792
	ds_read_b128 v[202:205], v157 offset:34816
	s_cmp_eq_u32 s57, 43
	s_cselect_b32 s28, s58, s28
	s_cselect_b32 s29, s59, s29
	s_add_i32 m0, s60, 0x10000
	s_nop 0
	global_load_lds_dwordx4 v132, s[28:29]
	ds_read_b128 v[206:209], v157 offset:35840
	ds_read_b128 v[210:213], v157 offset:36864
	ds_read_b128 v[214:217], v157 offset:37888
	s_add_i32 m0, s60, 0x12000
	s_nop 0
	global_load_lds_dwordx4 v136, s[28:29]
	ds_read_b128 v[218:221], v157 offset:38912
	ds_read_b128 v[222:225], v157 offset:39936
	ds_read_b128 v[158:161], v155 offset:32768
	s_add_u32 s30, s28, 0x58000
	s_addc_u32 s31, s29, 0
	s_add_i32 m0, s60, 0x11000
	s_nop 0
	global_load_lds_dwordx4 v132, s[30:31]
	ds_read_b128 v[162:165], v155 offset:33792
	ds_read_b128 v[166:169], v155 offset:34816
	ds_read_b128 v[174:177], v155 offset:35840
	s_add_i32 m0, s60, 0x13000
	s_nop 0
	global_load_lds_dwordx4 v136, s[30:31]
	ds_read_b128 v[178:181], v155 offset:49152
	ds_read_b128 v[182:185], v155 offset:50176
	ds_read_b128 v[186:189], v155 offset:51200
	s_add_u32 s30, s28, 0x160000
	s_addc_u32 s31, s29, 0
	s_add_i32 m0, s60, 0x14000
	s_nop 0
	global_load_lds_dwordx4 v132, s[30:31]
	ds_read_b128 v[190:193], v155 offset:52224
	ds_read_b128 v[226:229], v157 offset:49152
	ds_read_b128 v[230:233], v157 offset:50176
	s_add_i32 m0, s60, 0x16000
	s_nop 0
	global_load_lds_dwordx4 v136, s[30:31]
	ds_read_b128 v[234:237], v157 offset:51200
	ds_read_b128 v[238:241], v157 offset:52224
	ds_read_b128 v[242:245], v157 offset:53248
	s_add_u32 s30, s28, 0x1b8000
	s_addc_u32 s31, s29, 0
	s_add_i32 m0, s60, 0x15000
	s_nop 0
	global_load_lds_dwordx4 v132, s[30:31]
	ds_read_b128 v[246:249], v157 offset:54272
	ds_read_b128 v[250:253], v157 offset:55296
	ds_read_b128 v[142:145], v157 offset:56320
	s_add_i32 m0, s60, 0x17000
	s_nop 0
	global_load_lds_dwordx4 v136, s[30:31]
	s_add_u32 s28, s28, 0x80
	s_addc_u32 s29, s29, 0
	s_waitcnt vmcnt(8) lgkmcnt(0)
	s_barrier
	s_setprio 1
	v_mfma_f32_16x16x32_bf16 v[126:129], v[158:161], v[194:197], v[126:129]
	v_mfma_f32_16x16x32_bf16 v[126:129], v[162:165], v[198:201], v[126:129]
	v_mfma_f32_16x16x32_bf16 v[122:125], v[174:177], v[198:201], v[122:125]
	v_mfma_f32_16x16x32_bf16 v[122:125], v[166:169], v[194:197], v[122:125]
	v_mfma_f32_16x16x32_bf16 v[114:117], v[178:181], v[194:197], v[114:117]
	v_mfma_f32_16x16x32_bf16 v[114:117], v[182:185], v[198:201], v[114:117]
	v_mfma_f32_16x16x32_bf16 v[106:109], v[190:193], v[198:201], v[106:109]
	v_mfma_f32_16x16x32_bf16 v[106:109], v[186:189], v[194:197], v[106:109]
	v_mfma_f32_16x16x32_bf16 v[90:93], v[186:189], v[202:205], v[90:93]
	v_mfma_f32_16x16x32_bf16 v[90:93], v[190:193], v[206:209], v[90:93]
	v_mfma_f32_16x16x32_bf16 v[98:101], v[182:185], v[206:209], v[98:101]
	v_mfma_f32_16x16x32_bf16 v[98:101], v[178:181], v[202:205], v[98:101]
	v_mfma_f32_16x16x32_bf16 v[110:113], v[166:169], v[202:205], v[110:113]
	v_mfma_f32_16x16x32_bf16 v[110:113], v[174:177], v[206:209], v[110:113]
	v_mfma_f32_16x16x32_bf16 v[118:121], v[162:165], v[206:209], v[118:121]
	v_mfma_f32_16x16x32_bf16 v[118:121], v[158:161], v[202:205], v[118:121]
	v_mfma_f32_16x16x32_bf16 v[102:105], v[158:161], v[210:213], v[102:105]
	v_mfma_f32_16x16x32_bf16 v[102:105], v[162:165], v[214:217], v[102:105]
	v_mfma_f32_16x16x32_bf16 v[94:97], v[174:177], v[214:217], v[94:97]
	v_mfma_f32_16x16x32_bf16 v[94:97], v[166:169], v[210:213], v[94:97]
	v_mfma_f32_16x16x32_bf16 v[82:85], v[178:181], v[210:213], v[82:85]
	v_mfma_f32_16x16x32_bf16 v[82:85], v[182:185], v[214:217], v[82:85]
	v_mfma_f32_16x16x32_bf16 v[74:77], v[190:193], v[214:217], v[74:77]
	v_mfma_f32_16x16x32_bf16 v[74:77], v[186:189], v[210:213], v[74:77]
	v_mfma_f32_16x16x32_bf16 v[66:69], v[186:189], v[218:221], v[66:69]
	v_mfma_f32_16x16x32_bf16 v[66:69], v[190:193], v[222:225], v[66:69]
	v_mfma_f32_16x16x32_bf16 v[70:73], v[182:185], v[222:225], v[70:73]
	v_mfma_f32_16x16x32_bf16 v[70:73], v[178:181], v[218:221], v[70:73]
	v_mfma_f32_16x16x32_bf16 v[78:81], v[166:169], v[218:221], v[78:81]
	v_mfma_f32_16x16x32_bf16 v[78:81], v[174:177], v[222:225], v[78:81]
	v_mfma_f32_16x16x32_bf16 v[86:89], v[162:165], v[222:225], v[86:89]
	v_mfma_f32_16x16x32_bf16 v[86:89], v[158:161], v[218:221], v[86:89]
	v_mfma_f32_16x16x32_bf16 v[62:65], v[158:161], v[226:229], v[62:65]
	v_mfma_f32_16x16x32_bf16 v[62:65], v[162:165], v[230:233], v[62:65]
	v_mfma_f32_16x16x32_bf16 v[58:61], v[174:177], v[230:233], v[58:61]
	v_mfma_f32_16x16x32_bf16 v[58:61], v[166:169], v[226:229], v[58:61]
	v_mfma_f32_16x16x32_bf16 v[50:53], v[178:181], v[226:229], v[50:53]
	v_mfma_f32_16x16x32_bf16 v[50:53], v[182:185], v[230:233], v[50:53]
	v_mfma_f32_16x16x32_bf16 v[42:45], v[190:193], v[230:233], v[42:45]
	v_mfma_f32_16x16x32_bf16 v[42:45], v[186:189], v[226:229], v[42:45]
	v_mfma_f32_16x16x32_bf16 v[26:29], v[186:189], v[234:237], v[26:29]
	v_mfma_f32_16x16x32_bf16 v[26:29], v[190:193], v[238:241], v[26:29]
	v_mfma_f32_16x16x32_bf16 v[34:37], v[182:185], v[238:241], v[34:37]
	v_mfma_f32_16x16x32_bf16 v[34:37], v[178:181], v[234:237], v[34:37]
	v_mfma_f32_16x16x32_bf16 v[46:49], v[166:169], v[234:237], v[46:49]
	v_mfma_f32_16x16x32_bf16 v[46:49], v[174:177], v[238:241], v[46:49]
	v_mfma_f32_16x16x32_bf16 v[54:57], v[162:165], v[238:241], v[54:57]
	v_mfma_f32_16x16x32_bf16 v[54:57], v[158:161], v[234:237], v[54:57]
	v_mfma_f32_16x16x32_bf16 v[38:41], v[158:161], v[242:245], v[38:41]
	v_mfma_f32_16x16x32_bf16 v[38:41], v[162:165], v[246:249], v[38:41]
	v_mfma_f32_16x16x32_bf16 v[30:33], v[174:177], v[246:249], v[30:33]
	v_mfma_f32_16x16x32_bf16 v[30:33], v[166:169], v[242:245], v[30:33]
	v_mfma_f32_16x16x32_bf16 v[18:21], v[178:181], v[242:245], v[18:21]
	v_mfma_f32_16x16x32_bf16 v[18:21], v[182:185], v[246:249], v[18:21]
	v_mfma_f32_16x16x32_bf16 v[10:13], v[190:193], v[246:249], v[10:13]
	v_mfma_f32_16x16x32_bf16 v[10:13], v[186:189], v[242:245], v[10:13]
	v_mfma_f32_16x16x32_bf16 v[2:5], v[186:189], v[250:253], v[2:5]
	v_mfma_f32_16x16x32_bf16 v[2:5], v[190:193], v[142:145], v[2:5]
	v_mfma_f32_16x16x32_bf16 v[6:9], v[182:185], v[142:145], v[6:9]
	v_mfma_f32_16x16x32_bf16 v[6:9], v[178:181], v[250:253], v[6:9]
	v_mfma_f32_16x16x32_bf16 v[14:17], v[166:169], v[250:253], v[14:17]
	v_mfma_f32_16x16x32_bf16 v[14:17], v[174:177], v[142:145], v[14:17]
	v_mfma_f32_16x16x32_bf16 v[22:25], v[162:165], v[142:145], v[22:25]
	v_mfma_f32_16x16x32_bf16 v[22:25], v[158:161], v[250:253], v[22:25]
	s_setprio 0
	s_waitcnt vmcnt(0)
	s_barrier
	s_add_i32 s57, s57, 1
	s_cmp_lt_u32 s57, 44
	s_cbranch_scc1 .Lp9k_A_loop
	s_branch .Lp9k_done
; #define PG8_STAGE(bufoff, gbase, voff) do { _Pragma("unroll") for (int _i = 0; _i < 2; ++_i) \
;         __builtin_amdgcn_global_load_lds((const unsigned*)((const char*)(gbase) + (voff)[_i]), (PG8_LAS unsigned*)(lds + (bufoff) + ldsw + _i * 8192), 16, 0, 0); } while (0)
; #define PG8_LDA(dst, b, h) do { _Pragma("unroll") for (int m = 0; m < 4; ++m) _Pragma("unroll") for (int k = 0; k < 2; ++k) dst[m][k] = *(const PG8_LAS bf16x8*)(lds + PG8_SA(b, h) + aoff + m * 2048 + k * 1024); } while (0)
; #define PG8_LDB(dst, b, h) do { _Pragma("unroll") for (int n = 0; n < 2; ++n) _Pragma("unroll") for (int k = 0; k < 2; ++k) dst[n][k] = *(const PG8_LAS bf16x8*)(lds + PG8_SB(b, h) + boff + n * 2048 + k * 1024); } while (0)
; #define PG8_MMA(ai, bj, At, Bt) do { __builtin_amdgcn_s_setprio(1); _Pragma("unroll") for (int m = 0; m < 4; ++m) _Pragma("unroll") for (int n = 0; n < 2; ++n) _Pragma("unroll") for (int k = 0; k < 2; ++k) \
;         acc[ai][bj][m][n] = __builtin_amdgcn_mfma_f32_16x16x32_bf16(Bt[n][k], At[m][k], acc[ai][bj][m][n], 0, 0, 0); __builtin_amdgcn_s_setprio(0); } while (0)
; #define PG8_WAIT_V(n) asm volatile("s_waitcnt vmcnt(" #n ")" ::: "memory")
; #define PG8_WAIT_L(n) asm volatile("s_waitcnt lgkmcnt(" #n ")" ::: "memory")
; #define PG8_BAR __builtin_amdgcn_s_barrier()
; #define PG8_SCHED __builtin_amdgcn_sched_barrier(0)
; template <class Epi, class Sched, bool ALIGN_EPI>
; __device__ __forceinline__ void gemm_phase(PG8_LAS unsigned char* lds, const Gemm g, const Sched& S, const Epi& E) {
;     ...
;             const char* a2 = last ? nA : cA + (size_t)(t + 2) * kstepA; const char* b2 = last ? nB : cB + (size_t)(t + 2) * kstep;
;             const char* a3 = a2 + kstepA; const char* b3 = b2 + kstep;
;             PG8_LDB(B0, 0, 0); PG8_LDB(B1, 0, 1); PG8_SCHED; PG8_LDA(At, 0, 0); PG8_STAGE(PG8_SA(1, 1), a1 + hstepA, voffA);
;             PG8_WAIT_V(8); PG8_WAIT_L(0); PG8_BAR; PG8_MMA(0, 0, At, B0); PG8_MMA(0, 1, At, B1); PG8_BAR; PG8_SCHED;
;             PG8_LDA(At, 0, 1); PG8_STAGE(PG8_SB(0, 0), b2, voffB); PG8_STAGE(PG8_SB(0, 1), b2 + hstepB, voffB); PG8_STAGE(PG8_SA(0, 0), a2, voffA);
;             PG8_WAIT_V(8); PG8_WAIT_L(0); PG8_BAR; PG8_MMA(1, 0, At, B0); PG8_MMA(1, 1, At, B1); PG8_BAR; PG8_SCHED;
.Lp9k_B_init:
	s_sub_u32 s28, s26, 0x57f80
	s_subb_u32 s29, s27, 0
	s_sub_u32 s58, s6, 0x58000
	s_subb_u32 s59, s7, 0
	s_setprio 2
	ds_read_b128 v[194:197], v157 offset:0
	ds_read_b128 v[198:201], v157 offset:1024
	ds_read_b128 v[202:205], v157 offset:2048
	s_add_i32 m0, s60, 0xa000
	s_nop 0
	global_load_lds_dwordx4 v134, s[28:29]
	ds_read_b128 v[206:209], v157 offset:3072
	ds_read_b128 v[210:213], v157 offset:4096
	ds_read_b128 v[214:217], v157 offset:5120
	s_add_u32 s30, s28, 0x58000
	s_addc_u32 s31, s29, 0
	s_add_i32 m0, s60, 0xb000
	s_nop 0
	global_load_lds_dwordx4 v134, s[30:31]
	ds_read_b128 v[218:221], v157 offset:6144
	ds_read_b128 v[222:225], v157 offset:7168
	ds_read_b128 v[158:161], v155 offset:0
	s_add_u32 s30, s28, 0x160000
	s_addc_u32 s31, s29, 0
	s_add_i32 m0, s60, 0xe000
	s_nop 0
	global_load_lds_dwordx4 v134, s[30:31]
	ds_read_b128 v[162:165], v155 offset:1024
	ds_read_b128 v[166:169], v155 offset:2048
	ds_read_b128 v[174:177], v155 offset:3072
	s_add_u32 s30, s28, 0x1b8000
	s_addc_u32 s31, s29, 0
	s_add_i32 m0, s60, 0xf000
	s_nop 0
	global_load_lds_dwordx4 v134, s[30:31]
	ds_read_b128 v[178:181], v155 offset:16384
	ds_read_b128 v[182:185], v155 offset:17408
	ds_read_b128 v[186:189], v155 offset:18432
	s_add_u32 s34, s28, 0x80
	s_addc_u32 s35, s29, 0
	s_cmp_eq_u32 s57, 43
	s_cselect_b32 s34, s58, s34
	s_cselect_b32 s35, s59, s35
	s_add_i32 m0, s60, 0x0
	s_nop 0
	global_load_lds_dwordx4 v130, s[34:35]
	ds_read_b128 v[190:193], v155 offset:19456
	ds_read_b128 v[226:229], v157 offset:16384
	ds_read_b128 v[230:233], v157 offset:17408
	s_add_u32 s30, s34, 0x58000
	s_addc_u32 s31, s35, 0
	s_add_i32 m0, s60, 0x1000
	s_nop 0
	global_load_lds_dwordx4 v130, s[30:31]
	ds_read_b128 v[234:237], v157 offset:18432
	ds_read_b128 v[238:241], v157 offset:19456
	ds_read_b128 v[242:245], v157 offset:20480
	s_add_u32 s30, s34, 0x160000
	s_addc_u32 s31, s35, 0
	s_add_i32 m0, s60, 0x4000
	s_nop 0
	global_load_lds_dwordx4 v130, s[30:31]
	ds_read_b128 v[246:249], v157 offset:21504
	ds_read_b128 v[250:253], v157 offset:22528
	ds_read_b128 v[142:145], v157 offset:23552
	s_add_u32 s30, s34, 0x1b8000
	s_addc_u32 s31, s35, 0
	s_add_i32 m0, s60, 0x5000
	s_nop 0
	global_load_lds_dwordx4 v130, s[30:31]
	s_add_u32 s28, s28, 0x80
	s_addc_u32 s29, s29, 0
	s_waitcnt vmcnt(8) lgkmcnt(0)
	s_barrier
	s_setprio 1
	v_mfma_f32_16x16x32_bf16 v[126:129], v[158:161], v[194:197], 0
	v_mfma_f32_16x16x32_bf16 v[126:129], v[162:165], v[198:201], v[126:129]
	v_mfma_f32_16x16x32_bf16 v[122:125], v[174:177], v[198:201], 0
	v_mfma_f32_16x16x32_bf16 v[122:125], v[166:169], v[194:197], v[122:125]
	v_mfma_f32_16x16x32_bf16 v[114:117], v[178:181], v[194:197], 0
	v_mfma_f32_16x16x32_bf16 v[114:117], v[182:185], v[198:201], v[114:117]
	v_mfma_f32_16x16x32_bf16 v[106:109], v[190:193], v[198:201], 0
	v_mfma_f32_16x16x32_bf16 v[106:109], v[186:189], v[194:197], v[106:109]
	v_mfma_f32_16x16x32_bf16 v[90:93], v[186:189], v[202:205], 0
	v_mfma_f32_16x16x32_bf16 v[90:93], v[190:193], v[206:209], v[90:93]
	v_mfma_f32_16x16x32_bf16 v[98:101], v[182:185], v[206:209], 0
	v_mfma_f32_16x16x32_bf16 v[98:101], v[178:181], v[202:205], v[98:101]
	v_mfma_f32_16x16x32_bf16 v[110:113], v[166:169], v[202:205], 0
	v_mfma_f32_16x16x32_bf16 v[110:113], v[174:177], v[206:209], v[110:113]
	v_mfma_f32_16x16x32_bf16 v[118:121], v[162:165], v[206:209], 0
	v_mfma_f32_16x16x32_bf16 v[118:121], v[158:161], v[202:205], v[118:121]
	v_mfma_f32_16x16x32_bf16 v[102:105], v[158:161], v[210:213], 0
	v_mfma_f32_16x16x32_bf16 v[102:105], v[162:165], v[214:217], v[102:105]
	v_mfma_f32_16x16x32_bf16 v[94:97], v[174:177], v[214:217], 0
	v_mfma_f32_16x16x32_bf16 v[94:97], v[166:169], v[210:213], v[94:97]
	v_mfma_f32_16x16x32_bf16 v[82:85], v[178:181], v[210:213], 0
	v_mfma_f32_16x16x32_bf16 v[82:85], v[182:185], v[214:217], v[82:85]
	v_mfma_f32_16x16x32_bf16 v[74:77], v[190:193], v[214:217], 0
	v_mfma_f32_16x16x32_bf16 v[74:77], v[186:189], v[210:213], v[74:77]
	v_mfma_f32_16x16x32_bf16 v[66:69], v[186:189], v[218:221], 0
	v_mfma_f32_16x16x32_bf16 v[66:69], v[190:193], v[222:225], v[66:69]
	v_mfma_f32_16x16x32_bf16 v[70:73], v[182:185], v[222:225], 0
	v_mfma_f32_16x16x32_bf16 v[70:73], v[178:181], v[218:221], v[70:73]
	v_mfma_f32_16x16x32_bf16 v[78:81], v[166:169], v[218:221], 0
	v_mfma_f32_16x16x32_bf16 v[78:81], v[174:177], v[222:225], v[78:81]
	v_mfma_f32_16x16x32_bf16 v[86:89], v[162:165], v[222:225], 0
	v_mfma_f32_16x16x32_bf16 v[86:89], v[158:161], v[218:221], v[86:89]
	v_mfma_f32_16x16x32_bf16 v[62:65], v[158:161], v[226:229], 0
	v_mfma_f32_16x16x32_bf16 v[62:65], v[162:165], v[230:233], v[62:65]
	v_mfma_f32_16x16x32_bf16 v[58:61], v[174:177], v[230:233], 0
	v_mfma_f32_16x16x32_bf16 v[58:61], v[166:169], v[226:229], v[58:61]
	v_mfma_f32_16x16x32_bf16 v[50:53], v[178:181], v[226:229], 0
	v_mfma_f32_16x16x32_bf16 v[50:53], v[182:185], v[230:233], v[50:53]
	v_mfma_f32_16x16x32_bf16 v[42:45], v[190:193], v[230:233], 0
	v_mfma_f32_16x16x32_bf16 v[42:45], v[186:189], v[226:229], v[42:45]
	v_mfma_f32_16x16x32_bf16 v[26:29], v[186:189], v[234:237], 0
	v_mfma_f32_16x16x32_bf16 v[26:29], v[190:193], v[238:241], v[26:29]
	v_mfma_f32_16x16x32_bf16 v[34:37], v[182:185], v[238:241], 0
	v_mfma_f32_16x16x32_bf16 v[34:37], v[178:181], v[234:237], v[34:37]
	v_mfma_f32_16x16x32_bf16 v[46:49], v[166:169], v[234:237], 0
	v_mfma_f32_16x16x32_bf16 v[46:49], v[174:177], v[238:241], v[46:49]
	v_mfma_f32_16x16x32_bf16 v[54:57], v[162:165], v[238:241], 0
	v_mfma_f32_16x16x32_bf16 v[54:57], v[158:161], v[234:237], v[54:57]
	v_mfma_f32_16x16x32_bf16 v[38:41], v[158:161], v[242:245], 0
	v_mfma_f32_16x16x32_bf16 v[38:41], v[162:165], v[246:249], v[38:41]
	v_mfma_f32_16x16x32_bf16 v[30:33], v[174:177], v[246:249], 0
	v_mfma_f32_16x16x32_bf16 v[30:33], v[166:169], v[242:245], v[30:33]
	v_mfma_f32_16x16x32_bf16 v[18:21], v[178:181], v[242:245], 0
	v_mfma_f32_16x16x32_bf16 v[18:21], v[182:185], v[246:249], v[18:21]
	v_mfma_f32_16x16x32_bf16 v[10:13], v[190:193], v[246:249], 0
	v_mfma_f32_16x16x32_bf16 v[10:13], v[186:189], v[242:245], v[10:13]
	v_mfma_f32_16x16x32_bf16 v[2:5], v[186:189], v[250:253], 0
	v_mfma_f32_16x16x32_bf16 v[2:5], v[190:193], v[142:145], v[2:5]
	v_mfma_f32_16x16x32_bf16 v[6:9], v[182:185], v[142:145], 0
	v_mfma_f32_16x16x32_bf16 v[6:9], v[178:181], v[250:253], v[6:9]
	v_mfma_f32_16x16x32_bf16 v[14:17], v[166:169], v[250:253], 0
	v_mfma_f32_16x16x32_bf16 v[14:17], v[174:177], v[142:145], v[14:17]
	v_mfma_f32_16x16x32_bf16 v[22:25], v[162:165], v[142:145], 0
	v_mfma_f32_16x16x32_bf16 v[22:25], v[158:161], v[250:253], v[22:25]
	s_setprio 0
	s_waitcnt vmcnt(0)
	s_barrier
; #define PG8_STAGE(bufoff, gbase, voff) do { _Pragma("unroll") for (int _i = 0; _i < 2; ++_i) \
;         __builtin_amdgcn_global_load_lds((const unsigned*)((const char*)(gbase) + (voff)[_i]), (PG8_LAS unsigned*)(lds + (bufoff) + ldsw + _i * 8192), 16, 0, 0); } while (0)
; #define PG8_LDA(dst, b, h) do { _Pragma("unroll") for (int m = 0; m < 4; ++m) _Pragma("unroll") for (int k = 0; k < 2; ++k) dst[m][k] = *(const PG8_LAS bf16x8*)(lds + PG8_SA(b, h) + aoff + m * 2048 + k * 1024); } while (0)
; #define PG8_LDB(dst, b, h) do { _Pragma("unroll") for (int n = 0; n < 2; ++n) _Pragma("unroll") for (int k = 0; k < 2; ++k) dst[n][k] = *(const PG8_LAS bf16x8*)(lds + PG8_SB(b, h) + boff + n * 2048 + k * 1024); } while (0)
; #define PG8_MMA(ai, bj, At, Bt) do { __builtin_amdgcn_s_setprio(1); _Pragma("unroll") for (int m = 0; m < 4; ++m) _Pragma("unroll") for (int n = 0; n < 2; ++n) _Pragma("unroll") for (int k = 0; k < 2; ++k) \
;         acc[ai][bj][m][n] = __builtin_amdgcn_mfma_f32_16x16x32_bf16(Bt[n][k], At[m][k], acc[ai][bj][m][n], 0, 0, 0); __builtin_amdgcn_s_setprio(0); } while (0)
; #define PG8_WAIT_V(n) asm volatile("s_waitcnt vmcnt(" #n ")" ::: "memory")
; #define PG8_WAIT_L(n) asm volatile("s_waitcnt lgkmcnt(" #n ")" ::: "memory")
; #define PG8_BAR __builtin_amdgcn_s_barrier()
; #define PG8_SCHED __builtin_amdgcn_sched_barrier(0)
; template <class Epi, class Sched, bool ALIGN_EPI>
; __device__ __forceinline__ void gemm_phase(PG8_LAS unsigned char* lds, const Gemm g, const Sched& S, const Epi& E) {
;     ...
;             PG8_LDB(B0, 1, 0); PG8_LDB(B1, 1, 1); PG8_SCHED; PG8_LDA(At, 1, 0); PG8_STAGE(PG8_SA(0, 1), a2 + hstepA, voffA);
;             PG8_WAIT_V(8); PG8_WAIT_L(0); PG8_BAR; PG8_MMA(0, 0, At, B0); PG8_MMA(0, 1, At, B1); PG8_BAR; PG8_SCHED;
;             PG8_LDA(At, 1, 1); PG8_STAGE(PG8_SB(1, 0), b3, voffB); PG8_STAGE(PG8_SB(1, 1), b3 + hstepB, voffB); PG8_STAGE(PG8_SA(1, 0), a3, voffA);
;             PG8_WAIT_V(8); PG8_WAIT_L(0); PG8_BAR; PG8_MMA(1, 0, At, B0); PG8_MMA(1, 1, At, B1); PG8_BAR; PG8_SCHED;
	s_setprio 2
	ds_read_b128 v[194:197], v157 offset:32768
	ds_read_b128 v[198:201], v157 offset:33792
	ds_read_b128 v[202:205], v157 offset:34816
	s_cmp_eq_u32 s57, 43
	s_cselect_b32 s28, s58, s28
	s_cselect_b32 s29, s59, s29
	s_add_i32 m0, s60, 0x2000
	s_nop 0
	global_load_lds_dwordx4 v134, s[28:29]
	ds_read_b128 v[206:209], v157 offset:35840
	ds_read_b128 v[210:213], v157 offset:36864
	ds_read_b128 v[214:217], v157 offset:37888
	s_add_u32 s30, s28, 0x58000
	s_addc_u32 s31, s29, 0
	s_add_i32 m0, s60, 0x3000
	s_nop 0
	global_load_lds_dwordx4 v134, s[30:31]
	ds_read_b128 v[218:221], v157 offset:38912
	ds_read_b128 v[222:225], v157 offset:39936
	ds_read_b128 v[158:161], v155 offset:32768
	s_add_u32 s30, s28, 0x160000
	s_addc_u32 s31, s29, 0
	s_add_i32 m0, s60, 0x6000
	s_nop 0
	global_load_lds_dwordx4 v134, s[30:31]
	ds_read_b128 v[162:165], v155 offset:33792
	ds_read_b128 v[166:169], v155 offset:34816
	ds_read_b128 v[174:177], v155 offset:35840
	s_add_u32 s30, s28, 0x1b8000
	s_addc_u32 s31, s29, 0
	s_add_i32 m0, s60, 0x7000
	s_nop 0
	global_load_lds_dwordx4 v134, s[30:31]
	ds_read_b128 v[178:181], v155 offset:49152
	ds_read_b128 v[182:185], v155 offset:50176
	ds_read_b128 v[186:189], v155 offset:51200
	s_add_u32 s34, s28, 0x80
	s_addc_u32 s35, s29, 0
	s_add_i32 m0, s60, 0x8000
	s_nop 0
	global_load_lds_dwordx4 v130, s[34:35]
	ds_read_b128 v[190:193], v155 offset:52224
	ds_read_b128 v[226:229], v157 offset:49152
	ds_read_b128 v[230:233], v157 offset:50176
	s_add_u32 s30, s34, 0x58000
	s_addc_u32 s31, s35, 0
	s_add_i32 m0, s60, 0x9000
	s_nop 0
	global_load_lds_dwordx4 v130, s[30:31]
	ds_read_b128 v[234:237], v157 offset:51200
	ds_read_b128 v[238:241], v157 offset:52224
	ds_read_b128 v[242:245], v157 offset:53248
	s_add_u32 s30, s34, 0x160000
	s_addc_u32 s31, s35, 0
	s_add_i32 m0, s60, 0xc000
	s_nop 0
	global_load_lds_dwordx4 v130, s[30:31]
	ds_read_b128 v[246:249], v157 offset:54272
	ds_read_b128 v[250:253], v157 offset:55296
	ds_read_b128 v[142:145], v157 offset:56320
	s_add_u32 s30, s34, 0x1b8000
	s_addc_u32 s31, s35, 0
	s_add_i32 m0, s60, 0xd000
	s_nop 0
	global_load_lds_dwordx4 v130, s[30:31]
	s_add_u32 s28, s28, 0x80
	s_addc_u32 s29, s29, 0
	s_waitcnt vmcnt(8) lgkmcnt(0)
	s_barrier
	s_setprio 1
	v_mfma_f32_16x16x32_bf16 v[126:129], v[158:161], v[194:197], v[126:129]
	v_mfma_f32_16x16x32_bf16 v[126:129], v[162:165], v[198:201], v[126:129]
	v_mfma_f32_16x16x32_bf16 v[122:125], v[174:177], v[198:201], v[122:125]
	v_mfma_f32_16x16x32_bf16 v[122:125], v[166:169], v[194:197], v[122:125]
	v_mfma_f32_16x16x32_bf16 v[114:117], v[178:181], v[194:197], v[114:117]
	v_mfma_f32_16x16x32_bf16 v[114:117], v[182:185], v[198:201], v[114:117]
	v_mfma_f32_16x16x32_bf16 v[106:109], v[190:193], v[198:201], v[106:109]
	v_mfma_f32_16x16x32_bf16 v[106:109], v[186:189], v[194:197], v[106:109]
	v_mfma_f32_16x16x32_bf16 v[90:93], v[186:189], v[202:205], v[90:93]
	v_mfma_f32_16x16x32_bf16 v[90:93], v[190:193], v[206:209], v[90:93]
	v_mfma_f32_16x16x32_bf16 v[98:101], v[182:185], v[206:209], v[98:101]
	v_mfma_f32_16x16x32_bf16 v[98:101], v[178:181], v[202:205], v[98:101]
	v_mfma_f32_16x16x32_bf16 v[110:113], v[166:169], v[202:205], v[110:113]
	v_mfma_f32_16x16x32_bf16 v[110:113], v[174:177], v[206:209], v[110:113]
	v_mfma_f32_16x16x32_bf16 v[118:121], v[162:165], v[206:209], v[118:121]
	v_mfma_f32_16x16x32_bf16 v[118:121], v[158:161], v[202:205], v[118:121]
	v_mfma_f32_16x16x32_bf16 v[102:105], v[158:161], v[210:213], v[102:105]
	v_mfma_f32_16x16x32_bf16 v[102:105], v[162:165], v[214:217], v[102:105]
	v_mfma_f32_16x16x32_bf16 v[94:97], v[174:177], v[214:217], v[94:97]
	v_mfma_f32_16x16x32_bf16 v[94:97], v[166:169], v[210:213], v[94:97]
	v_mfma_f32_16x16x32_bf16 v[82:85], v[178:181], v[210:213], v[82:85]
	v_mfma_f32_16x16x32_bf16 v[82:85], v[182:185], v[214:217], v[82:85]
	v_mfma_f32_16x16x32_bf16 v[74:77], v[190:193], v[214:217], v[74:77]
	v_mfma_f32_16x16x32_bf16 v[74:77], v[186:189], v[210:213], v[74:77]
	v_mfma_f32_16x16x32_bf16 v[66:69], v[186:189], v[218:221], v[66:69]
	v_mfma_f32_16x16x32_bf16 v[66:69], v[190:193], v[222:225], v[66:69]
	v_mfma_f32_16x16x32_bf16 v[70:73], v[182:185], v[222:225], v[70:73]
	v_mfma_f32_16x16x32_bf16 v[70:73], v[178:181], v[218:221], v[70:73]
	v_mfma_f32_16x16x32_bf16 v[78:81], v[166:169], v[218:221], v[78:81]
	v_mfma_f32_16x16x32_bf16 v[78:81], v[174:177], v[222:225], v[78:81]
	v_mfma_f32_16x16x32_bf16 v[86:89], v[162:165], v[222:225], v[86:89]
	v_mfma_f32_16x16x32_bf16 v[86:89], v[158:161], v[218:221], v[86:89]
	v_mfma_f32_16x16x32_bf16 v[62:65], v[158:161], v[226:229], v[62:65]
	v_mfma_f32_16x16x32_bf16 v[62:65], v[162:165], v[230:233], v[62:65]
	v_mfma_f32_16x16x32_bf16 v[58:61], v[174:177], v[230:233], v[58:61]
	v_mfma_f32_16x16x32_bf16 v[58:61], v[166:169], v[226:229], v[58:61]
	v_mfma_f32_16x16x32_bf16 v[50:53], v[178:181], v[226:229], v[50:53]
	v_mfma_f32_16x16x32_bf16 v[50:53], v[182:185], v[230:233], v[50:53]
	v_mfma_f32_16x16x32_bf16 v[42:45], v[190:193], v[230:233], v[42:45]
	v_mfma_f32_16x16x32_bf16 v[42:45], v[186:189], v[226:229], v[42:45]
	v_mfma_f32_16x16x32_bf16 v[26:29], v[186:189], v[234:237], v[26:29]
	v_mfma_f32_16x16x32_bf16 v[26:29], v[190:193], v[238:241], v[26:29]
	v_mfma_f32_16x16x32_bf16 v[34:37], v[182:185], v[238:241], v[34:37]
	v_mfma_f32_16x16x32_bf16 v[34:37], v[178:181], v[234:237], v[34:37]
	v_mfma_f32_16x16x32_bf16 v[46:49], v[166:169], v[234:237], v[46:49]
	v_mfma_f32_16x16x32_bf16 v[46:49], v[174:177], v[238:241], v[46:49]
	v_mfma_f32_16x16x32_bf16 v[54:57], v[162:165], v[238:241], v[54:57]
	v_mfma_f32_16x16x32_bf16 v[54:57], v[158:161], v[234:237], v[54:57]
	v_mfma_f32_16x16x32_bf16 v[38:41], v[158:161], v[242:245], v[38:41]
	v_mfma_f32_16x16x32_bf16 v[38:41], v[162:165], v[246:249], v[38:41]
	v_mfma_f32_16x16x32_bf16 v[30:33], v[174:177], v[246:249], v[30:33]
	v_mfma_f32_16x16x32_bf16 v[30:33], v[166:169], v[242:245], v[30:33]
	v_mfma_f32_16x16x32_bf16 v[18:21], v[178:181], v[242:245], v[18:21]
	v_mfma_f32_16x16x32_bf16 v[18:21], v[182:185], v[246:249], v[18:21]
	v_mfma_f32_16x16x32_bf16 v[10:13], v[190:193], v[246:249], v[10:13]
	v_mfma_f32_16x16x32_bf16 v[10:13], v[186:189], v[242:245], v[10:13]
	v_mfma_f32_16x16x32_bf16 v[2:5], v[186:189], v[250:253], v[2:5]
	v_mfma_f32_16x16x32_bf16 v[2:5], v[190:193], v[142:145], v[2:5]
	v_mfma_f32_16x16x32_bf16 v[6:9], v[182:185], v[142:145], v[6:9]
	v_mfma_f32_16x16x32_bf16 v[6:9], v[178:181], v[250:253], v[6:9]
	v_mfma_f32_16x16x32_bf16 v[14:17], v[166:169], v[250:253], v[14:17]
	v_mfma_f32_16x16x32_bf16 v[14:17], v[174:177], v[142:145], v[14:17]
	v_mfma_f32_16x16x32_bf16 v[22:25], v[162:165], v[142:145], v[22:25]
	v_mfma_f32_16x16x32_bf16 v[22:25], v[158:161], v[250:253], v[22:25]
	s_setprio 0
	s_waitcnt vmcnt(0)
	s_barrier
	s_add_i32 s57, s57, 1
; #define PG8_STAGE(bufoff, gbase, voff) do { _Pragma("unroll") for (int _i = 0; _i < 2; ++_i) \
;         __builtin_amdgcn_global_load_lds((const unsigned*)((const char*)(gbase) + (voff)[_i]), (PG8_LAS unsigned*)(lds + (bufoff) + ldsw + _i * 8192), 16, 0, 0); } while (0)
; #define PG8_LDA(dst, b, h) do { _Pragma("unroll") for (int m = 0; m < 4; ++m) _Pragma("unroll") for (int k = 0; k < 2; ++k) dst[m][k] = *(const PG8_LAS bf16x8*)(lds + PG8_SA(b, h) + aoff + m * 2048 + k * 1024); } while (0)
; #define PG8_LDB(dst, b, h) do { _Pragma("unroll") for (int n = 0; n < 2; ++n) _Pragma("unroll") for (int k = 0; k < 2; ++k) dst[n][k] = *(const PG8_LAS bf16x8*)(lds + PG8_SB(b, h) + boff + n * 2048 + k * 1024); } while (0)
; #define PG8_MMA(ai, bj, At, Bt) do { __builtin_amdgcn_s_setprio(1); _Pragma("unroll") for (int m = 0; m < 4; ++m) _Pragma("unroll") for (int n = 0; n < 2; ++n) _Pragma("unroll") for (int k = 0; k < 2; ++k) \
;         acc[ai][bj][m][n] = __builtin_amdgcn_mfma_f32_16x16x32_bf16(Bt[n][k], At[m][k], acc[ai][bj][m][n], 0, 0, 0); __builtin_amdgcn_s_setprio(0); } while (0)
; #define PG8_WAIT_V(n) asm volatile("s_waitcnt vmcnt(" #n ")" ::: "memory")
; #define PG8_WAIT_L(n) asm volatile("s_waitcnt lgkmcnt(" #n ")" ::: "memory")
; #define PG8_BAR __builtin_amdgcn_s_barrier()
; #define PG8_SCHED __builtin_amdgcn_sched_barrier(0)
; template <class Epi, class Sched, bool ALIGN_EPI>
; __device__ __forceinline__ void gemm_phase(PG8_LAS unsigned char* lds, const Gemm g, const Sched& S, const Epi& E) {
;     ...
;             PG8_LDB(B0, 0, 0); PG8_LDB(B1, 0, 1); PG8_SCHED; PG8_LDA(At, 0, 0); PG8_STAGE(PG8_SA(1, 1), a1 + hstepA, voffA);
;             PG8_WAIT_V(8); PG8_WAIT_L(0); PG8_BAR; PG8_MMA(0, 0, At, B0); PG8_MMA(0, 1, At, B1); PG8_BAR; PG8_SCHED;
;             PG8_LDA(At, 0, 1); PG8_STAGE(PG8_SB(0, 0), b2, voffB); PG8_STAGE(PG8_SB(0, 1), b2 + hstepB, voffB); PG8_STAGE(PG8_SA(0, 0), a2, voffA);
;             PG8_WAIT_V(8); PG8_WAIT_L(0); PG8_BAR; PG8_MMA(1, 0, At, B0); PG8_MMA(1, 1, At, B1); PG8_BAR; PG8_SCHED;
.Lp9k_B_loop:
	s_setprio 2
	ds_read_b128 v[194:197], v157 offset:0
	ds_read_b128 v[198:201], v157 offset:1024
	ds_read_b128 v[202:205], v157 offset:2048
	s_add_i32 m0, s60, 0xa000
	s_nop 0
	global_load_lds_dwordx4 v134, s[28:29]
	ds_read_b128 v[206:209], v157 offset:3072
	ds_read_b128 v[210:213], v157 offset:4096
	ds_read_b128 v[214:217], v157 offset:5120
	s_add_u32 s30, s28, 0x58000
	s_addc_u32 s31, s29, 0
	s_add_i32 m0, s60, 0xb000
	s_nop 0
	global_load_lds_dwordx4 v134, s[30:31]
	ds_read_b128 v[218:221], v157 offset:6144
	ds_read_b128 v[222:225], v157 offset:7168
	ds_read_b128 v[158:161], v155 offset:0
	s_add_u32 s30, s28, 0x160000
	s_addc_u32 s31, s29, 0
	s_add_i32 m0, s60, 0xe000
	s_nop 0
	global_load_lds_dwordx4 v134, s[30:31]
	ds_read_b128 v[162:165], v155 offset:1024
	ds_read_b128 v[166:169], v155 offset:2048
	ds_read_b128 v[174:177], v155 offset:3072
	s_add_u32 s30, s28, 0x1b8000
	s_addc_u32 s31, s29, 0
	s_add_i32 m0, s60, 0xf000
	s_nop 0
	global_load_lds_dwordx4 v134, s[30:31]
	ds_read_b128 v[178:181], v155 offset:16384
	ds_read_b128 v[182:185], v155 offset:17408
	ds_read_b128 v[186:189], v155 offset:18432
	s_add_u32 s34, s28, 0x80
	s_addc_u32 s35, s29, 0
	s_cmp_eq_u32 s57, 43
	s_cselect_b32 s34, s58, s34
	s_cselect_b32 s35, s59, s35
	s_add_i32 m0, s60, 0x0
	s_nop 0
	global_load_lds_dwordx4 v130, s[34:35]
	ds_read_b128 v[190:193], v155 offset:19456
	ds_read_b128 v[226:229], v157 offset:16384
	ds_read_b128 v[230:233], v157 offset:17408
	s_add_u32 s30, s34, 0x58000
	s_addc_u32 s31, s35, 0
	s_add_i32 m0, s60, 0x1000
	s_nop 0
	global_load_lds_dwordx4 v130, s[30:31]
	ds_read_b128 v[234:237], v157 offset:18432
	ds_read_b128 v[238:241], v157 offset:19456
	ds_read_b128 v[242:245], v157 offset:20480
	s_add_u32 s30, s34, 0x160000
	s_addc_u32 s31, s35, 0
	s_add_i32 m0, s60, 0x4000
	s_nop 0
	global_load_lds_dwordx4 v130, s[30:31]
	ds_read_b128 v[246:249], v157 offset:21504
	ds_read_b128 v[250:253], v157 offset:22528
	ds_read_b128 v[142:145], v157 offset:23552
	s_add_u32 s30, s34, 0x1b8000
	s_addc_u32 s31, s35, 0
	s_add_i32 m0, s60, 0x5000
	s_nop 0
	global_load_lds_dwordx4 v130, s[30:31]
	s_add_u32 s28, s28, 0x80
	s_addc_u32 s29, s29, 0
	s_waitcnt vmcnt(8) lgkmcnt(0)
	s_barrier
	s_setprio 1
	v_mfma_f32_16x16x32_bf16 v[126:129], v[158:161], v[194:197], v[126:129]
	v_mfma_f32_16x16x32_bf16 v[126:129], v[162:165], v[198:201], v[126:129]
	v_mfma_f32_16x16x32_bf16 v[122:125], v[174:177], v[198:201], v[122:125]
	v_mfma_f32_16x16x32_bf16 v[122:125], v[166:169], v[194:197], v[122:125]
	v_mfma_f32_16x16x32_bf16 v[114:117], v[178:181], v[194:197], v[114:117]
	v_mfma_f32_16x16x32_bf16 v[114:117], v[182:185], v[198:201], v[114:117]
	v_mfma_f32_16x16x32_bf16 v[106:109], v[190:193], v[198:201], v[106:109]
	v_mfma_f32_16x16x32_bf16 v[106:109], v[186:189], v[194:197], v[106:109]
	v_mfma_f32_16x16x32_bf16 v[90:93], v[186:189], v[202:205], v[90:93]
	v_mfma_f32_16x16x32_bf16 v[90:93], v[190:193], v[206:209], v[90:93]
	v_mfma_f32_16x16x32_bf16 v[98:101], v[182:185], v[206:209], v[98:101]
	v_mfma_f32_16x16x32_bf16 v[98:101], v[178:181], v[202:205], v[98:101]
	v_mfma_f32_16x16x32_bf16 v[110:113], v[166:169], v[202:205], v[110:113]
	v_mfma_f32_16x16x32_bf16 v[110:113], v[174:177], v[206:209], v[110:113]
	v_mfma_f32_16x16x32_bf16 v[118:121], v[162:165], v[206:209], v[118:121]
	v_mfma_f32_16x16x32_bf16 v[118:121], v[158:161], v[202:205], v[118:121]
	v_mfma_f32_16x16x32_bf16 v[102:105], v[158:161], v[210:213], v[102:105]
	v_mfma_f32_16x16x32_bf16 v[102:105], v[162:165], v[214:217], v[102:105]
	v_mfma_f32_16x16x32_bf16 v[94:97], v[174:177], v[214:217], v[94:97]
	v_mfma_f32_16x16x32_bf16 v[94:97], v[166:169], v[210:213], v[94:97]
	v_mfma_f32_16x16x32_bf16 v[82:85], v[178:181], v[210:213], v[82:85]
	v_mfma_f32_16x16x32_bf16 v[82:85], v[182:185], v[214:217], v[82:85]
	v_mfma_f32_16x16x32_bf16 v[74:77], v[190:193], v[214:217], v[74:77]
	v_mfma_f32_16x16x32_bf16 v[74:77], v[186:189], v[210:213], v[74:77]
	v_mfma_f32_16x16x32_bf16 v[66:69], v[186:189], v[218:221], v[66:69]
	v_mfma_f32_16x16x32_bf16 v[66:69], v[190:193], v[222:225], v[66:69]
	v_mfma_f32_16x16x32_bf16 v[70:73], v[182:185], v[222:225], v[70:73]
	v_mfma_f32_16x16x32_bf16 v[70:73], v[178:181], v[218:221], v[70:73]
	v_mfma_f32_16x16x32_bf16 v[78:81], v[166:169], v[218:221], v[78:81]
	v_mfma_f32_16x16x32_bf16 v[78:81], v[174:177], v[222:225], v[78:81]
	v_mfma_f32_16x16x32_bf16 v[86:89], v[162:165], v[222:225], v[86:89]
	v_mfma_f32_16x16x32_bf16 v[86:89], v[158:161], v[218:221], v[86:89]
	v_mfma_f32_16x16x32_bf16 v[62:65], v[158:161], v[226:229], v[62:65]
	v_mfma_f32_16x16x32_bf16 v[62:65], v[162:165], v[230:233], v[62:65]
	v_mfma_f32_16x16x32_bf16 v[58:61], v[174:177], v[230:233], v[58:61]
	v_mfma_f32_16x16x32_bf16 v[58:61], v[166:169], v[226:229], v[58:61]
	v_mfma_f32_16x16x32_bf16 v[50:53], v[178:181], v[226:229], v[50:53]
	v_mfma_f32_16x16x32_bf16 v[50:53], v[182:185], v[230:233], v[50:53]
	v_mfma_f32_16x16x32_bf16 v[42:45], v[190:193], v[230:233], v[42:45]
	v_mfma_f32_16x16x32_bf16 v[42:45], v[186:189], v[226:229], v[42:45]
	v_mfma_f32_16x16x32_bf16 v[26:29], v[186:189], v[234:237], v[26:29]
	v_mfma_f32_16x16x32_bf16 v[26:29], v[190:193], v[238:241], v[26:29]
	v_mfma_f32_16x16x32_bf16 v[34:37], v[182:185], v[238:241], v[34:37]
	v_mfma_f32_16x16x32_bf16 v[34:37], v[178:181], v[234:237], v[34:37]
	v_mfma_f32_16x16x32_bf16 v[46:49], v[166:169], v[234:237], v[46:49]
	v_mfma_f32_16x16x32_bf16 v[46:49], v[174:177], v[238:241], v[46:49]
	v_mfma_f32_16x16x32_bf16 v[54:57], v[162:165], v[238:241], v[54:57]
	v_mfma_f32_16x16x32_bf16 v[54:57], v[158:161], v[234:237], v[54:57]
	v_mfma_f32_16x16x32_bf16 v[38:41], v[158:161], v[242:245], v[38:41]
	v_mfma_f32_16x16x32_bf16 v[38:41], v[162:165], v[246:249], v[38:41]
	v_mfma_f32_16x16x32_bf16 v[30:33], v[174:177], v[246:249], v[30:33]
	v_mfma_f32_16x16x32_bf16 v[30:33], v[166:169], v[242:245], v[30:33]
	v_mfma_f32_16x16x32_bf16 v[18:21], v[178:181], v[242:245], v[18:21]
	v_mfma_f32_16x16x32_bf16 v[18:21], v[182:185], v[246:249], v[18:21]
	v_mfma_f32_16x16x32_bf16 v[10:13], v[190:193], v[246:249], v[10:13]
	v_mfma_f32_16x16x32_bf16 v[10:13], v[186:189], v[242:245], v[10:13]
	v_mfma_f32_16x16x32_bf16 v[2:5], v[186:189], v[250:253], v[2:5]
	v_mfma_f32_16x16x32_bf16 v[2:5], v[190:193], v[142:145], v[2:5]
	v_mfma_f32_16x16x32_bf16 v[6:9], v[182:185], v[142:145], v[6:9]
	v_mfma_f32_16x16x32_bf16 v[6:9], v[178:181], v[250:253], v[6:9]
	v_mfma_f32_16x16x32_bf16 v[14:17], v[166:169], v[250:253], v[14:17]
	v_mfma_f32_16x16x32_bf16 v[14:17], v[174:177], v[142:145], v[14:17]
	v_mfma_f32_16x16x32_bf16 v[22:25], v[162:165], v[142:145], v[22:25]
	v_mfma_f32_16x16x32_bf16 v[22:25], v[158:161], v[250:253], v[22:25]
	s_setprio 0
	s_waitcnt vmcnt(0)
	s_barrier
; #define PG8_STAGE(bufoff, gbase, voff) do { _Pragma("unroll") for (int _i = 0; _i < 2; ++_i) \
;         __builtin_amdgcn_global_load_lds((const unsigned*)((const char*)(gbase) + (voff)[_i]), (PG8_LAS unsigned*)(lds + (bufoff) + ldsw + _i * 8192), 16, 0, 0); } while (0)
; #define PG8_LDA(dst, b, h) do { _Pragma("unroll") for (int m = 0; m < 4; ++m) _Pragma("unroll") for (int k = 0; k < 2; ++k) dst[m][k] = *(const PG8_LAS bf16x8*)(lds + PG8_SA(b, h) + aoff + m * 2048 + k * 1024); } while (0)
; #define PG8_LDB(dst, b, h) do { _Pragma("unroll") for (int n = 0; n < 2; ++n) _Pragma("unroll") for (int k = 0; k < 2; ++k) dst[n][k] = *(const PG8_LAS bf16x8*)(lds + PG8_SB(b, h) + boff + n * 2048 + k * 1024); } while (0)
; #define PG8_MMA(ai, bj, At, Bt) do { __builtin_amdgcn_s_setprio(1); _Pragma("unroll") for (int m = 0; m < 4; ++m) _Pragma("unroll") for (int n = 0; n < 2; ++n) _Pragma("unroll") for (int k = 0; k < 2; ++k) \
;         acc[ai][bj][m][n] = __builtin_amdgcn_mfma_f32_16x16x32_bf16(Bt[n][k], At[m][k], acc[ai][bj][m][n], 0, 0, 0); __builtin_amdgcn_s_setprio(0); } while (0)
; #define PG8_WAIT_V(n) asm volatile("s_waitcnt vmcnt(" #n ")" ::: "memory")
; #define PG8_WAIT_L(n) asm volatile("s_waitcnt lgkmcnt(" #n ")" ::: "memory")
; #define PG8_BAR __builtin_amdgcn_s_barrier()
; #define PG8_SCHED __builtin_amdgcn_sched_barrier(0)
; template <class Epi, class Sched, bool ALIGN_EPI>
; __device__ __forceinline__ void gemm_phase(PG8_LAS unsigned char* lds, const Gemm g, const Sched& S, const Epi& E) {
;     ...
;             PG8_LDB(B0, 1, 0); PG8_LDB(B1, 1, 1); PG8_SCHED; PG8_LDA(At, 1, 0); PG8_STAGE(PG8_SA(0, 1), a2 + hstepA, voffA);
;             PG8_WAIT_V(8); PG8_WAIT_L(0); PG8_BAR; PG8_MMA(0, 0, At, B0); PG8_MMA(0, 1, At, B1); PG8_BAR; PG8_SCHED;
;             PG8_LDA(At, 1, 1); PG8_STAGE(PG8_SB(1, 0), b3, voffB); PG8_STAGE(PG8_SB(1, 1), b3 + hstepB, voffB); PG8_STAGE(PG8_SA(1, 0), a3, voffA);
;             PG8_WAIT_V(8); PG8_WAIT_L(0); PG8_BAR; PG8_MMA(1, 0, At, B0); PG8_MMA(1, 1, At, B1); PG8_BAR; PG8_SCHED;
;         }
	s_setprio 2
	ds_read_b128 v[194:197], v157 offset:32768
	ds_read_b128 v[198:201], v157 offset:33792
	ds_read_b128 v[202:205], v157 offset:34816
	s_cmp_eq_u32 s57, 43
	s_cselect_b32 s28, s58, s28
	s_cselect_b32 s29, s59, s29
	s_add_i32 m0, s60, 0x2000
	s_nop 0
	global_load_lds_dwordx4 v134, s[28:29]
	ds_read_b128 v[206:209], v157 offset:35840
	ds_read_b128 v[210:213], v157 offset:36864
	ds_read_b128 v[214:217], v157 offset:37888
	s_add_u32 s30, s28, 0x58000
	s_addc_u32 s31, s29, 0
	s_add_i32 m0, s60, 0x3000
	s_nop 0
	global_load_lds_dwordx4 v134, s[30:31]
	ds_read_b128 v[218:221], v157 offset:38912
	ds_read_b128 v[222:225], v157 offset:39936
	ds_read_b128 v[158:161], v155 offset:32768
	s_add_u32 s30, s28, 0x160000
	s_addc_u32 s31, s29, 0
	s_add_i32 m0, s60, 0x6000
	s_nop 0
	global_load_lds_dwordx4 v134, s[30:31]
	ds_read_b128 v[162:165], v155 offset:33792
	ds_read_b128 v[166:169], v155 offset:34816
	ds_read_b128 v[174:177], v155 offset:35840
	s_add_u32 s30, s28, 0x1b8000
	s_addc_u32 s31, s29, 0
	s_add_i32 m0, s60, 0x7000
	s_nop 0
	global_load_lds_dwordx4 v134, s[30:31]
	ds_read_b128 v[178:181], v155 offset:49152
	ds_read_b128 v[182:185], v155 offset:50176
	ds_read_b128 v[186:189], v155 offset:51200
	s_add_u32 s34, s28, 0x80
	s_addc_u32 s35, s29, 0
	s_add_i32 m0, s60, 0x8000
	s_nop 0
	global_load_lds_dwordx4 v130, s[34:35]
	ds_read_b128 v[190:193], v155 offset:52224
	ds_read_b128 v[226:229], v157 offset:49152
	ds_read_b128 v[230:233], v157 offset:50176
	s_add_u32 s30, s34, 0x58000
	s_addc_u32 s31, s35, 0
	s_add_i32 m0, s60, 0x9000
	s_nop 0
	global_load_lds_dwordx4 v130, s[30:31]
	ds_read_b128 v[234:237], v157 offset:51200
	ds_read_b128 v[238:241], v157 offset:52224
	ds_read_b128 v[242:245], v157 offset:53248
	s_add_u32 s30, s34, 0x160000
	s_addc_u32 s31, s35, 0
	s_add_i32 m0, s60, 0xc000
	s_nop 0
	global_load_lds_dwordx4 v130, s[30:31]
	ds_read_b128 v[246:249], v157 offset:54272
	ds_read_b128 v[250:253], v157 offset:55296
	ds_read_b128 v[142:145], v157 offset:56320
	s_add_u32 s30, s34, 0x1b8000
	s_addc_u32 s31, s35, 0
	s_add_i32 m0, s60, 0xd000
	s_nop 0
	global_load_lds_dwordx4 v130, s[30:31]
	s_add_u32 s28, s28, 0x80
	s_addc_u32 s29, s29, 0
	s_waitcnt vmcnt(8) lgkmcnt(0)
	s_barrier
	s_setprio 1
	v_mfma_f32_16x16x32_bf16 v[126:129], v[158:161], v[194:197], v[126:129]
	v_mfma_f32_16x16x32_bf16 v[126:129], v[162:165], v[198:201], v[126:129]
	v_mfma_f32_16x16x32_bf16 v[122:125], v[174:177], v[198:201], v[122:125]
	v_mfma_f32_16x16x32_bf16 v[122:125], v[166:169], v[194:197], v[122:125]
	v_mfma_f32_16x16x32_bf16 v[114:117], v[178:181], v[194:197], v[114:117]
	v_mfma_f32_16x16x32_bf16 v[114:117], v[182:185], v[198:201], v[114:117]
	v_mfma_f32_16x16x32_bf16 v[106:109], v[190:193], v[198:201], v[106:109]
	v_mfma_f32_16x16x32_bf16 v[106:109], v[186:189], v[194:197], v[106:109]
	v_mfma_f32_16x16x32_bf16 v[90:93], v[186:189], v[202:205], v[90:93]
	v_mfma_f32_16x16x32_bf16 v[90:93], v[190:193], v[206:209], v[90:93]
	v_mfma_f32_16x16x32_bf16 v[98:101], v[182:185], v[206:209], v[98:101]
	v_mfma_f32_16x16x32_bf16 v[98:101], v[178:181], v[202:205], v[98:101]
	v_mfma_f32_16x16x32_bf16 v[110:113], v[166:169], v[202:205], v[110:113]
	v_mfma_f32_16x16x32_bf16 v[110:113], v[174:177], v[206:209], v[110:113]
	v_mfma_f32_16x16x32_bf16 v[118:121], v[162:165], v[206:209], v[118:121]
	v_mfma_f32_16x16x32_bf16 v[118:121], v[158:161], v[202:205], v[118:121]
	v_mfma_f32_16x16x32_bf16 v[102:105], v[158:161], v[210:213], v[102:105]
	v_mfma_f32_16x16x32_bf16 v[102:105], v[162:165], v[214:217], v[102:105]
	v_mfma_f32_16x16x32_bf16 v[94:97], v[174:177], v[214:217], v[94:97]
	v_mfma_f32_16x16x32_bf16 v[94:97], v[166:169], v[210:213], v[94:97]
	v_mfma_f32_16x16x32_bf16 v[82:85], v[178:181], v[210:213], v[82:85]
	v_mfma_f32_16x16x32_bf16 v[82:85], v[182:185], v[214:217], v[82:85]
	v_mfma_f32_16x16x32_bf16 v[74:77], v[190:193], v[214:217], v[74:77]
	v_mfma_f32_16x16x32_bf16 v[74:77], v[186:189], v[210:213], v[74:77]
	v_mfma_f32_16x16x32_bf16 v[66:69], v[186:189], v[218:221], v[66:69]
	v_mfma_f32_16x16x32_bf16 v[66:69], v[190:193], v[222:225], v[66:69]
	v_mfma_f32_16x16x32_bf16 v[70:73], v[182:185], v[222:225], v[70:73]
	v_mfma_f32_16x16x32_bf16 v[70:73], v[178:181], v[218:221], v[70:73]
	v_mfma_f32_16x16x32_bf16 v[78:81], v[166:169], v[218:221], v[78:81]
	v_mfma_f32_16x16x32_bf16 v[78:81], v[174:177], v[222:225], v[78:81]
	v_mfma_f32_16x16x32_bf16 v[86:89], v[162:165], v[222:225], v[86:89]
	v_mfma_f32_16x16x32_bf16 v[86:89], v[158:161], v[218:221], v[86:89]
	v_mfma_f32_16x16x32_bf16 v[62:65], v[158:161], v[226:229], v[62:65]
	v_mfma_f32_16x16x32_bf16 v[62:65], v[162:165], v[230:233], v[62:65]
	v_mfma_f32_16x16x32_bf16 v[58:61], v[174:177], v[230:233], v[58:61]
	v_mfma_f32_16x16x32_bf16 v[58:61], v[166:169], v[226:229], v[58:61]
	v_mfma_f32_16x16x32_bf16 v[50:53], v[178:181], v[226:229], v[50:53]
	v_mfma_f32_16x16x32_bf16 v[50:53], v[182:185], v[230:233], v[50:53]
	v_mfma_f32_16x16x32_bf16 v[42:45], v[190:193], v[230:233], v[42:45]
	v_mfma_f32_16x16x32_bf16 v[42:45], v[186:189], v[226:229], v[42:45]
	v_mfma_f32_16x16x32_bf16 v[26:29], v[186:189], v[234:237], v[26:29]
	v_mfma_f32_16x16x32_bf16 v[26:29], v[190:193], v[238:241], v[26:29]
	v_mfma_f32_16x16x32_bf16 v[34:37], v[182:185], v[238:241], v[34:37]
	v_mfma_f32_16x16x32_bf16 v[34:37], v[178:181], v[234:237], v[34:37]
	v_mfma_f32_16x16x32_bf16 v[46:49], v[166:169], v[234:237], v[46:49]
	v_mfma_f32_16x16x32_bf16 v[46:49], v[174:177], v[238:241], v[46:49]
	v_mfma_f32_16x16x32_bf16 v[54:57], v[162:165], v[238:241], v[54:57]
	v_mfma_f32_16x16x32_bf16 v[54:57], v[158:161], v[234:237], v[54:57]
	v_mfma_f32_16x16x32_bf16 v[38:41], v[158:161], v[242:245], v[38:41]
	v_mfma_f32_16x16x32_bf16 v[38:41], v[162:165], v[246:249], v[38:41]
	v_mfma_f32_16x16x32_bf16 v[30:33], v[174:177], v[246:249], v[30:33]
	v_mfma_f32_16x16x32_bf16 v[30:33], v[166:169], v[242:245], v[30:33]
	v_mfma_f32_16x16x32_bf16 v[18:21], v[178:181], v[242:245], v[18:21]
	v_mfma_f32_16x16x32_bf16 v[18:21], v[182:185], v[246:249], v[18:21]
	v_mfma_f32_16x16x32_bf16 v[10:13], v[190:193], v[246:249], v[10:13]
	v_mfma_f32_16x16x32_bf16 v[10:13], v[186:189], v[242:245], v[10:13]
	v_mfma_f32_16x16x32_bf16 v[2:5], v[186:189], v[250:253], v[2:5]
	v_mfma_f32_16x16x32_bf16 v[2:5], v[190:193], v[142:145], v[2:5]
	v_mfma_f32_16x16x32_bf16 v[6:9], v[182:185], v[142:145], v[6:9]
	v_mfma_f32_16x16x32_bf16 v[6:9], v[178:181], v[250:253], v[6:9]
	v_mfma_f32_16x16x32_bf16 v[14:17], v[166:169], v[250:253], v[14:17]
	v_mfma_f32_16x16x32_bf16 v[14:17], v[174:177], v[142:145], v[14:17]
	v_mfma_f32_16x16x32_bf16 v[22:25], v[162:165], v[142:145], v[22:25]
	v_mfma_f32_16x16x32_bf16 v[22:25], v[158:161], v[250:253], v[22:25]
	s_setprio 0
	s_waitcnt vmcnt(0)
	s_barrier
	s_add_i32 s57, s57, 1
	s_cmp_lt_u32 s57, 44
	s_cbranch_scc1 .Lp9k_B_loop
